# GU / QKV-type output stores: scalar base (s[30:31]) + 32-bit lane offset instead of a 64-bit address VGPR pair
# speedup vs baseline: 1.0088x; 1.0088x over previous
; __device__ __forceinline__ unsigned cvt_pk_bf16(float lo, float hi) { unsigned r; asm volatile("v_cvt_pk_bf16_f32 %0, %1, %2" : "=v"(r) : "v"(lo), "v"(hi)); return r; }
; __device__ __forceinline__ float siluf_(float x) { return x * sigmoidf_(x); }
; #define PG8_STAGE(bufoff, gbase, voff) do { _Pragma("unroll") for (int _i = 0; _i < 2; ++_i) \
;         __builtin_amdgcn_global_load_lds((const unsigned*)((const char*)(gbase) + (voff)[_i]), (LAS unsigned*)(lds + (bufoff) + ldsw + _i * 8192), 16, 0, 0); } while (0)
; #define PG8_LDA(dst, b, h) do { _Pragma("unroll") for (int m = 0; m < 4; ++m) _Pragma("unroll") for (int k = 0; k < 2; ++k) dst[m][k] = *(const LAS bf16x8*)(lds + PG8_SA(b, h) + aoff + m * 2048 + k * 1024); } while (0)
; #define PG8_LDB(dst, b, h) do { _Pragma("unroll") for (int n = 0; n < 2; ++n) _Pragma("unroll") for (int k = 0; k < 2; ++k) dst[n][k] = *(const LAS bf16x8*)(lds + PG8_SB(b, h) + boff + n * 2048 + k * 1024); } while (0)
; #define PG8_BAR __builtin_amdgcn_s_barrier()
;     __device__ __forceinline__ void operator()(const f32x4 (&acc)[2][2][4][2], const Unit& u, int wr, int wc, int fr, int fq) const {
;         const int row0 = u.pm * BM + wr * 64 + fr, col0 = u.pn * HALF + wc * 32 + 8 * fq;
;         float rsv[2][4]; load_rstd(rsv, ssq, row0);
; #pragma unroll
;         for (int ai = 0; ai < 2; ++ai)
; #pragma unroll
;             for (int m = 0; m < 4; ++m) { const int row = row0 + ai * HALF + m * 16; bf16_t* rowp = O + (size_t)row * ldc + col0; const float rs = rsv[ai][m];
;                 f32x4 v0, v1;
; #pragma unroll
;                 for (int j = 0; j < 4; ++j) { v0[j] = siluf_(acc[ai][0][m][0][j] * rs) * (acc[ai][1][m][0][j] * rs); v1[j] = siluf_(acc[ai][0][m][1][j] * rs) * (acc[ai][1][m][1][j] * rs); }
;                 u32x4 w; w.x = cvt_pk_bf16(v0[0], v0[1]); w.y = cvt_pk_bf16(v0[2], v0[3]); w.z = cvt_pk_bf16(v1[0], v1[1]); w.w = cvt_pk_bf16(v1[2], v1[3]);
;                 *(u32x4*)rowp = w; }
; template <class Epi, bool ALIGN_EPI>
; __device__ __forceinline__ void gemm_phase(LAS unsigned char* lds, const Gemm g, const StaticOrder& S, const Epi& E, const int tid) {
;     ...
;             PG8_LDB(B0, 0, 0); PG8_LDB(B1, 0, 1); PG8_SCHED; PG8_LDA(At, 0, 0); PG8_STAGE(PG8_SA(1, 1), a1 + hA, voffA);
;             PG8_WAIT_V(8); PG8_WAIT_L(0); PG8_BAR; PG8_MMA(0, 0, At, B0); PG8_MMA(0, 1, At, B1); PG8_BAR; PG8_SCHED;
.Lgu_first_epi:
	s_add_i32 s11, s10, 2
	s_cmp_eq_u32 s58, s10
	v_lshl_add_u64 v[146:147], v[142:143], 0, s[92:93]
	s_cselect_b64 vcc, -1, 0
	v_add_u32_e32 v150, s33, v151
	s_add_i32 s10, 0, 0x14000
	v_cndmask_b32_e32 v167, v147, v139, vcc
	v_cndmask_b32_e32 v166, v146, v138, vcc
	ds_read_b128 v[146:149], v150
	ds_read_b128 v[154:157], v150 offset:1024
	ds_read_b128 v[158:161], v150 offset:2048
	ds_read_b128 v[162:165], v150 offset:3072
	v_add_u32_e32 v150, s10, v151
	ds_read_b128 v[176:179], v150
	ds_read_b128 v[180:183], v150 offset:1024
	ds_read_b128 v[184:187], v150 offset:2048
	ds_read_b128 v[188:191], v150 offset:3072
	v_cndmask_b32_e32 v221, v145, v141, vcc
	v_cndmask_b32_e32 v220, v144, v140, vcc
	v_lshl_add_u64 v[226:227], v[142:143], 0, v[134:135]
	s_add_i32 m0, s51, 0xc000
	ds_read_b128 v[192:195], v153
	ds_read_b128 v[196:199], v153 offset:1024
	ds_read_b128 v[200:203], v153 offset:2048
	ds_read_b128 v[204:207], v153 offset:3072
	ds_read_b128 v[208:211], v153 offset:4096
	ds_read_b128 v[212:215], v153 offset:5120
	ds_read_b128 v[216:219], v153 offset:6144
	ds_read_b128 v[240:243], v153 offset:7168
	global_load_lds_dwordx4 v[226:227], off
	v_lshl_add_u64 v[226:227], v[142:143], 0, v[136:137]
	s_add_i32 m0, s51, 0xe000
	s_nop 0
	global_load_lds_dwordx4 v[226:227], off
	s_waitcnt vmcnt(12)
	s_waitcnt lgkmcnt(0)
	s_barrier
	s_setprio 1
	s_waitcnt lgkmcnt(0)
	v_mfma_f32_16x16x32_bf16 v[120:123], v[146:149], v[192:195], 0
	s_lshl_b32 s98, s28, 5
	s_mov_b32 s99, 0
	s_mov_b32 s100, 0xbfb8aa3b
	s_mov_b32 s101, 0xbfb8aa3b
	v_mul_f32_e32 v56, v238, v56
	v_mul_f32_e32 v57, v238, v57
	v_mul_f32_e32 v58, v238, v58
	v_mul_f32_e32 v59, v238, v59
	v_mul_f32_e32 v60, v238, v60
	v_mul_f32_e32 v61, v238, v61
	v_mfma_f32_16x16x32_bf16 v[112:115], v[158:161], v[192:195], 0
	v_mul_f32_e32 v62, v238, v62
	v_mul_f32_e32 v63, v238, v63
	v_mul_f32_e32 v224, s100, v56
	v_mul_f32_e32 v225, s101, v57
	v_mul_f32_e32 v228, s100, v58
	v_mul_f32_e32 v229, s101, v59
	v_exp_f32_e32 v224, v224
	v_exp_f32_e32 v225, v225
	v_exp_f32_e32 v228, v228
	v_exp_f32_e32 v229, v229
	v_mfma_f32_16x16x32_bf16 v[104:107], v[146:149], v[200:203], 0
	v_add_f32_e32 v224, 1.0, v224
	v_add_f32_e32 v225, 1.0, v225
	v_add_f32_e32 v228, 1.0, v228
	v_add_f32_e32 v229, 1.0, v229
	v_rcp_f32_e32 v224, v224
	v_rcp_f32_e32 v225, v225
	v_rcp_f32_e32 v228, v228
	v_rcp_f32_e32 v229, v229
	v_nop
	v_mul_f32_e32 v56, v224, v56
	v_mfma_f32_16x16x32_bf16 v[96:99], v[158:161], v[200:203], 0
	v_mul_f32_e32 v57, v225, v57
	v_mul_f32_e32 v58, v228, v58
	v_mul_f32_e32 v59, v229, v59
	v_mul_f32_e32 v56, v60, v56
	v_mul_f32_e32 v57, v61, v57
	v_mul_f32_e32 v58, v62, v58
	v_mul_f32_e32 v59, v63, v59
	v_mul_f32_e32 v48, v238, v48
	v_mul_f32_e32 v49, v238, v49
	v_mul_f32_e32 v50, v238, v50
	v_mfma_f32_16x16x32_bf16 v[88:91], v[146:149], v[208:211], 0
	v_mul_f32_e32 v51, v238, v51
	v_mul_f32_e32 v52, v238, v52
	v_mul_f32_e32 v53, v238, v53
	v_mul_f32_e32 v54, v238, v54
	v_mul_f32_e32 v55, v238, v55
	v_mul_f32_e32 v224, s100, v48
	v_mul_f32_e32 v225, s101, v49
	v_mul_f32_e32 v228, s100, v50
	v_mul_f32_e32 v229, s101, v51
	v_exp_f32_e32 v224, v224
	v_mfma_f32_16x16x32_bf16 v[80:83], v[158:161], v[208:211], 0
	v_exp_f32_e32 v225, v225
	v_exp_f32_e32 v228, v228
	v_exp_f32_e32 v229, v229
	v_add_f32_e32 v224, 1.0, v224
	v_add_f32_e32 v225, 1.0, v225
	v_add_f32_e32 v228, 1.0, v228
	v_add_f32_e32 v229, 1.0, v229
	v_rcp_f32_e32 v224, v224
	v_rcp_f32_e32 v225, v225
	v_rcp_f32_e32 v228, v228
	v_mfma_f32_16x16x32_bf16 v[72:75], v[146:149], v[216:219], 0
	v_rcp_f32_e32 v229, v229
	v_nop
	v_mul_f32_e32 v48, v224, v48
	v_mul_f32_e32 v49, v225, v49
	v_mul_f32_e32 v50, v228, v50
	v_mul_f32_e32 v51, v229, v51
	v_mul_f32_e32 v48, v52, v48
	v_mul_f32_e32 v49, v53, v49
	v_mul_f32_e32 v50, v54, v50
	v_mul_f32_e32 v51, v55, v51
	v_mfma_f32_16x16x32_bf16 v[64:67], v[158:161], v[216:219], 0
	v_cvt_pk_bf16_f32 v56, v56, v57
	v_cvt_pk_bf16_f32 v57, v58, v59
	v_cvt_pk_bf16_f32 v58, v48, v49
	v_cvt_pk_bf16_f32 v59, v50, v51
	global_store_dwordx4 v232, v[56:59], s[30:31]
	v_add_u32_e32 v232, s98, v232
	v_mul_f32_e32 v40, v239, v40
	v_mul_f32_e32 v41, v239, v41
	v_mul_f32_e32 v42, v239, v42
	v_mul_f32_e32 v43, v239, v43
	v_mfma_f32_16x16x32_bf16 v[120:123], v[154:157], v[196:199], v[120:123]
	v_mul_f32_e32 v44, v239, v44
	v_mul_f32_e32 v45, v239, v45
	v_mul_f32_e32 v46, v239, v46
	v_mul_f32_e32 v47, v239, v47
	v_mul_f32_e32 v224, s100, v40
	v_mul_f32_e32 v225, s101, v41
	v_mul_f32_e32 v228, s100, v42
	v_mul_f32_e32 v229, s101, v43
	v_exp_f32_e32 v224, v224
	v_exp_f32_e32 v225, v225
	v_mfma_f32_16x16x32_bf16 v[112:115], v[162:165], v[196:199], v[112:115]
	v_exp_f32_e32 v228, v228
	v_exp_f32_e32 v229, v229
	v_add_f32_e32 v224, 1.0, v224
	v_add_f32_e32 v225, 1.0, v225
	v_add_f32_e32 v228, 1.0, v228
	v_add_f32_e32 v229, 1.0, v229
	v_rcp_f32_e32 v224, v224
	v_rcp_f32_e32 v225, v225
	v_rcp_f32_e32 v228, v228
	v_rcp_f32_e32 v229, v229
	v_mfma_f32_16x16x32_bf16 v[104:107], v[154:157], v[204:207], v[104:107]
	v_nop
	v_mul_f32_e32 v40, v224, v40
	v_mul_f32_e32 v41, v225, v41
	v_mul_f32_e32 v42, v228, v42
	v_mul_f32_e32 v43, v229, v43
	v_mul_f32_e32 v40, v44, v40
	v_mul_f32_e32 v41, v45, v41
	v_mul_f32_e32 v42, v46, v42
	v_mul_f32_e32 v43, v47, v43
	v_mul_f32_e32 v32, v239, v32
	v_mfma_f32_16x16x32_bf16 v[96:99], v[162:165], v[204:207], v[96:99]
	v_mul_f32_e32 v33, v239, v33
	v_mul_f32_e32 v34, v239, v34
	v_mul_f32_e32 v35, v239, v35
	v_mul_f32_e32 v36, v239, v36
	v_mul_f32_e32 v37, v239, v37
	v_mul_f32_e32 v38, v239, v38
	v_mul_f32_e32 v39, v239, v39
	v_mul_f32_e32 v224, s100, v32
	v_mul_f32_e32 v225, s101, v33
	v_mul_f32_e32 v228, s100, v34
; __device__ __forceinline__ unsigned cvt_pk_bf16(float lo, float hi) { unsigned r; asm volatile("v_cvt_pk_bf16_f32 %0, %1, %2" : "=v"(r) : "v"(lo), "v"(hi)); return r; }
; __device__ __forceinline__ float siluf_(float x) { return x * sigmoidf_(x); }
; #define PG8_MMA(ai, bj, At, Bt) do { __builtin_amdgcn_s_setprio(1); _Pragma("unroll") for (int k = 0; k < 2; ++k) _Pragma("unroll") for (int m = 0; m < 4; ++m) _Pragma("unroll") for (int n = 0; n < 2; ++n) \
;         acc[ai][bj][m][n] = __builtin_amdgcn_mfma_f32_16x16x32_bf16(Bt[n][k], At[m][k], acc[ai][bj][m][n], 0, 0, 0); __builtin_amdgcn_s_setprio(0); } while (0)
; #define PG8_WAIT_V(n) asm volatile("s_waitcnt vmcnt(" #n ")" ::: "memory")
; #define PG8_WAIT_L(n) asm volatile("s_waitcnt lgkmcnt(" #n ")" ::: "memory")
; #define PG8_BAR __builtin_amdgcn_s_barrier()
; #define PG8_SCHED __builtin_amdgcn_sched_barrier(0)
;     __device__ __forceinline__ void operator()(const f32x4 (&acc)[2][2][4][2], const Unit& u, int wr, int wc, int fr, int fq) const {
;         const int row0 = u.pm * BM + wr * 64 + fr, col0 = u.pn * HALF + wc * 32 + 8 * fq;
;         float rsv[2][4]; load_rstd(rsv, ssq, row0);
; #pragma unroll
;         for (int ai = 0; ai < 2; ++ai)
; #pragma unroll
;             for (int m = 0; m < 4; ++m) { const int row = row0 + ai * HALF + m * 16; bf16_t* rowp = O + (size_t)row * ldc + col0; const float rs = rsv[ai][m];
;                 f32x4 v0, v1;
; #pragma unroll
;                 for (int j = 0; j < 4; ++j) { v0[j] = siluf_(acc[ai][0][m][0][j] * rs) * (acc[ai][1][m][0][j] * rs); v1[j] = siluf_(acc[ai][0][m][1][j] * rs) * (acc[ai][1][m][1][j] * rs); }
;                 u32x4 w; w.x = cvt_pk_bf16(v0[0], v0[1]); w.y = cvt_pk_bf16(v0[2], v0[3]); w.z = cvt_pk_bf16(v1[0], v1[1]); w.w = cvt_pk_bf16(v1[2], v1[3]);
;                 *(u32x4*)rowp = w; }
; template <class Epi, bool ALIGN_EPI>
; __device__ __forceinline__ void gemm_phase(LAS unsigned char* lds, const Gemm g, const StaticOrder& S, const Epi& E, const int tid) {
;     ...
;             PG8_WAIT_V(8); PG8_WAIT_L(0); PG8_BAR; PG8_MMA(0, 0, At, B0); PG8_MMA(0, 1, At, B1); PG8_BAR; PG8_SCHED;
	v_mfma_f32_16x16x32_bf16 v[88:91], v[154:157], v[212:215], v[88:91]
	v_mul_f32_e32 v229, s101, v35
	v_exp_f32_e32 v224, v224
	v_exp_f32_e32 v225, v225
	v_exp_f32_e32 v228, v228
	v_exp_f32_e32 v229, v229
	v_add_f32_e32 v224, 1.0, v224
	v_add_f32_e32 v225, 1.0, v225
	v_add_f32_e32 v228, 1.0, v228
	v_add_f32_e32 v229, 1.0, v229
	v_rcp_f32_e32 v224, v224
	v_mfma_f32_16x16x32_bf16 v[80:83], v[162:165], v[212:215], v[80:83]
	v_rcp_f32_e32 v225, v225
	v_rcp_f32_e32 v228, v228
	v_rcp_f32_e32 v229, v229
	v_nop
	v_mul_f32_e32 v32, v224, v32
	v_mul_f32_e32 v33, v225, v33
	v_mul_f32_e32 v34, v228, v34
	v_mul_f32_e32 v35, v229, v35
	v_mul_f32_e32 v32, v36, v32
	v_mul_f32_e32 v33, v37, v33
	v_mfma_f32_16x16x32_bf16 v[72:75], v[154:157], v[240:243], v[72:75]
	v_mul_f32_e32 v34, v38, v34
	v_mul_f32_e32 v35, v39, v35
	v_cvt_pk_bf16_f32 v40, v40, v41
	v_cvt_pk_bf16_f32 v41, v42, v43
	v_cvt_pk_bf16_f32 v42, v32, v33
	v_cvt_pk_bf16_f32 v43, v34, v35
	global_store_dwordx4 v232, v[40:43], s[30:31]
	v_add_u32_e32 v232, s98, v232
	v_mul_f32_e32 v24, v230, v24
	v_mul_f32_e32 v25, v230, v25
	v_mfma_f32_16x16x32_bf16 v[64:67], v[162:165], v[240:243], v[64:67]
	v_mul_f32_e32 v26, v230, v26
	v_mul_f32_e32 v27, v230, v27
	v_mul_f32_e32 v28, v230, v28
	v_mul_f32_e32 v29, v230, v29
	v_mul_f32_e32 v30, v230, v30
	v_mul_f32_e32 v31, v230, v31
	v_mul_f32_e32 v224, s100, v24
	v_mul_f32_e32 v225, s101, v25
	v_mul_f32_e32 v228, s100, v26
	v_mul_f32_e32 v229, s101, v27
	s_setprio 0
	s_setprio 1
	v_mfma_f32_16x16x32_bf16 v[124:127], v[176:179], v[192:195], 0
	v_exp_f32_e32 v224, v224
	v_exp_f32_e32 v225, v225
	v_exp_f32_e32 v228, v228
	v_exp_f32_e32 v229, v229
	v_add_f32_e32 v224, 1.0, v224
	v_add_f32_e32 v225, 1.0, v225
	v_add_f32_e32 v228, 1.0, v228
	v_add_f32_e32 v229, 1.0, v229
	v_rcp_f32_e32 v224, v224
	v_rcp_f32_e32 v225, v225
	v_mfma_f32_16x16x32_bf16 v[116:119], v[184:187], v[192:195], 0
	v_rcp_f32_e32 v228, v228
	v_rcp_f32_e32 v229, v229
	v_nop
	v_mul_f32_e32 v24, v224, v24
	v_mul_f32_e32 v25, v225, v25
	v_mul_f32_e32 v26, v228, v26
	v_mul_f32_e32 v27, v229, v27
	v_mul_f32_e32 v24, v28, v24
	v_mul_f32_e32 v25, v29, v25
	v_mul_f32_e32 v26, v30, v26
	v_mfma_f32_16x16x32_bf16 v[108:111], v[176:179], v[200:203], 0
	v_mul_f32_e32 v27, v31, v27
	v_mul_f32_e32 v16, v230, v16
	v_mul_f32_e32 v17, v230, v17
	v_mul_f32_e32 v18, v230, v18
	v_mul_f32_e32 v19, v230, v19
	v_mul_f32_e32 v20, v230, v20
	v_mul_f32_e32 v21, v230, v21
	v_mul_f32_e32 v22, v230, v22
	v_mul_f32_e32 v23, v230, v23
	v_mul_f32_e32 v224, s100, v16
	v_mfma_f32_16x16x32_bf16 v[100:103], v[184:187], v[200:203], 0
	v_mul_f32_e32 v225, s101, v17
	v_mul_f32_e32 v228, s100, v18
	v_mul_f32_e32 v229, s101, v19
	v_exp_f32_e32 v224, v224
	v_exp_f32_e32 v225, v225
	v_exp_f32_e32 v228, v228
	v_exp_f32_e32 v229, v229
	v_add_f32_e32 v224, 1.0, v224
	v_add_f32_e32 v225, 1.0, v225
	v_add_f32_e32 v228, 1.0, v228
	v_mfma_f32_16x16x32_bf16 v[92:95], v[176:179], v[208:211], 0
	v_add_f32_e32 v229, 1.0, v229
	v_rcp_f32_e32 v224, v224
	v_rcp_f32_e32 v225, v225
	v_rcp_f32_e32 v228, v228
	v_rcp_f32_e32 v229, v229
	v_nop
	v_mul_f32_e32 v16, v224, v16
	v_mul_f32_e32 v17, v225, v17
	v_mul_f32_e32 v18, v228, v18
	v_mul_f32_e32 v19, v229, v19
	v_mfma_f32_16x16x32_bf16 v[84:87], v[184:187], v[208:211], 0
	v_mul_f32_e32 v16, v20, v16
	v_mul_f32_e32 v17, v21, v17
	v_mul_f32_e32 v18, v22, v18
	v_mul_f32_e32 v19, v23, v19
	v_cvt_pk_bf16_f32 v24, v24, v25
	v_cvt_pk_bf16_f32 v25, v26, v27
	v_cvt_pk_bf16_f32 v26, v16, v17
	v_cvt_pk_bf16_f32 v27, v18, v19
	global_store_dwordx4 v232, v[24:27], s[30:31]
	v_add_u32_e32 v232, s98, v232
	v_mfma_f32_16x16x32_bf16 v[76:79], v[176:179], v[216:219], 0
	v_mul_f32_e32 v8, v231, v8
	v_mul_f32_e32 v9, v231, v9
	v_mul_f32_e32 v10, v231, v10
	v_mul_f32_e32 v11, v231, v11
	v_mul_f32_e32 v12, v231, v12
	v_mul_f32_e32 v13, v231, v13
	v_mul_f32_e32 v14, v231, v14
	v_mul_f32_e32 v15, v231, v15
	v_mul_f32_e32 v224, s100, v8
	v_mul_f32_e32 v225, s101, v9
	v_mfma_f32_16x16x32_bf16 v[68:71], v[184:187], v[216:219], 0
	v_mul_f32_e32 v228, s100, v10
	v_mul_f32_e32 v229, s101, v11
	v_exp_f32_e32 v224, v224
	v_exp_f32_e32 v225, v225
	v_exp_f32_e32 v228, v228
	v_exp_f32_e32 v229, v229
	v_add_f32_e32 v224, 1.0, v224
	v_add_f32_e32 v225, 1.0, v225
	v_add_f32_e32 v228, 1.0, v228
	v_add_f32_e32 v229, 1.0, v229
	v_mfma_f32_16x16x32_bf16 v[124:127], v[180:183], v[196:199], v[124:127]
	v_rcp_f32_e32 v224, v224
	v_rcp_f32_e32 v225, v225
	v_rcp_f32_e32 v228, v228
	v_rcp_f32_e32 v229, v229
	v_nop
	v_mul_f32_e32 v8, v224, v8
	v_mul_f32_e32 v9, v225, v9
	v_mul_f32_e32 v10, v228, v10
	v_mul_f32_e32 v11, v229, v11
	v_mul_f32_e32 v8, v12, v8
	v_mfma_f32_16x16x32_bf16 v[116:119], v[188:191], v[196:199], v[116:119]
	v_mul_f32_e32 v9, v13, v9
	v_mul_f32_e32 v10, v14, v10
	v_mul_f32_e32 v11, v15, v11
	v_mul_f32_e32 v4, v231, v4
	v_mul_f32_e32 v5, v231, v5
	v_mul_f32_e32 v6, v231, v6
	v_mul_f32_e32 v7, v231, v7
	v_mul_f32_e32 v0, v231, v0
	v_mul_f32_e32 v1, v231, v1
	v_mul_f32_e32 v2, v231, v2
	v_mfma_f32_16x16x32_bf16 v[108:111], v[180:183], v[204:207], v[108:111]
	v_mul_f32_e32 v3, v231, v3
	v_mul_f32_e32 v224, s100, v4
	v_mul_f32_e32 v225, s101, v5
	v_mul_f32_e32 v228, s100, v6
	v_mul_f32_e32 v229, s101, v7
	v_exp_f32_e32 v224, v224
	v_exp_f32_e32 v225, v225
	v_exp_f32_e32 v228, v228
	v_exp_f32_e32 v229, v229
	v_add_f32_e32 v224, 1.0, v224
	v_mfma_f32_16x16x32_bf16 v[100:103], v[188:191], v[204:207], v[100:103]
	v_add_f32_e32 v225, 1.0, v225
	v_add_f32_e32 v228, 1.0, v228
	v_add_f32_e32 v229, 1.0, v229
	v_rcp_f32_e32 v224, v224
	v_rcp_f32_e32 v225, v225
	v_rcp_f32_e32 v228, v228
	v_rcp_f32_e32 v229, v229
	v_nop
	v_mul_f32_e32 v4, v224, v4
	v_mul_f32_e32 v5, v225, v5
	v_mfma_f32_16x16x32_bf16 v[92:95], v[180:183], v[212:215], v[92:95]
	v_mul_f32_e32 v6, v228, v6
	v_mul_f32_e32 v7, v229, v7
	v_mul_f32_e32 v4, v0, v4
	v_mul_f32_e32 v5, v1, v5
	v_mul_f32_e32 v6, v2, v6
	v_mul_f32_e32 v7, v3, v7
	v_cvt_pk_bf16_f32 v8, v8, v9
	v_cvt_pk_bf16_f32 v9, v10, v11
	v_cvt_pk_bf16_f32 v10, v4, v5
	v_cvt_pk_bf16_f32 v11, v6, v7
	v_mfma_f32_16x16x32_bf16 v[84:87], v[188:191], v[212:215], v[84:87]
	global_store_dwordx4 v232, v[8:11], s[30:31]
	v_mfma_f32_16x16x32_bf16 v[76:79], v[180:183], v[240:243], v[76:79]
	v_mfma_f32_16x16x32_bf16 v[68:71], v[188:191], v[240:243], v[68:71]
	s_setprio 0
	s_barrier
; #define PG8_STAGE(bufoff, gbase, voff) do { _Pragma("unroll") for (int _i = 0; _i < 2; ++_i) \
;         __builtin_amdgcn_global_load_lds((const unsigned*)((const char*)(gbase) + (voff)[_i]), (LAS unsigned*)(lds + (bufoff) + ldsw + _i * 8192), 16, 0, 0); } while (0)
; #define PG8_LDA(dst, b, h) do { _Pragma("unroll") for (int m = 0; m < 4; ++m) _Pragma("unroll") for (int k = 0; k < 2; ++k) dst[m][k] = *(const LAS bf16x8*)(lds + PG8_SA(b, h) + aoff + m * 2048 + k * 1024); } while (0)
; #define PG8_LDB(dst, b, h) do { _Pragma("unroll") for (int n = 0; n < 2; ++n) _Pragma("unroll") for (int k = 0; k < 2; ++k) dst[n][k] = *(const LAS bf16x8*)(lds + PG8_SB(b, h) + boff + n * 2048 + k * 1024); } while (0)
; #define PG8_MMA(ai, bj, At, Bt) do { __builtin_amdgcn_s_setprio(1); _Pragma("unroll") for (int k = 0; k < 2; ++k) _Pragma("unroll") for (int m = 0; m < 4; ++m) _Pragma("unroll") for (int n = 0; n < 2; ++n) \
;         acc[ai][bj][m][n] = __builtin_amdgcn_mfma_f32_16x16x32_bf16(Bt[n][k], At[m][k], acc[ai][bj][m][n], 0, 0, 0); __builtin_amdgcn_s_setprio(0); } while (0)
; #define PG8_WAIT_V(n) asm volatile("s_waitcnt vmcnt(" #n ")" ::: "memory")
; #define PG8_WAIT_L(n) asm volatile("s_waitcnt lgkmcnt(" #n ")" ::: "memory")
; #define PG8_BAR __builtin_amdgcn_s_barrier()
; #define PG8_SCHED __builtin_amdgcn_sched_barrier(0)
; template <class Epi, bool ALIGN_EPI>
; __device__ __forceinline__ void gemm_phase(LAS unsigned char* lds, const Gemm g, const StaticOrder& S, const Epi& E, const int tid) {
;     ...
;             PG8_LDA(At, 0, 1); PG8_STAGE(PG8_SB(0, 0), b2, voffB); PG8_STAGE(PG8_SB(0, 1), b2 + hB, voffB); PG8_STAGE(PG8_SA(0, 0), a2, voffA);
;             PG8_WAIT_V(8); PG8_WAIT_L(0); PG8_BAR; PG8_MMA(1, 0, At, B0); PG8_MMA(1, 1, At, B1); PG8_BAR; PG8_SCHED;
;             PG8_LDB(B0, 1, 0); PG8_LDB(B1, 1, 1); PG8_SCHED; PG8_LDA(At, 1, 0); PG8_STAGE(PG8_SA(0, 1), a2 + hA, voffA);
	s_add_i32 s65, s33, s45
	v_lshl_add_u64 v[226:227], v[220:221], 0, v[168:169]
	s_mov_b32 m0, s65
	ds_read_b128 v[192:195], v153 offset:16384
	ds_read_b128 v[196:199], v153 offset:17408
	ds_read_b128 v[200:203], v153 offset:18432
	ds_read_b128 v[204:207], v153 offset:19456
	ds_read_b128 v[208:211], v153 offset:20480
	ds_read_b128 v[212:215], v153 offset:21504
	ds_read_b128 v[216:219], v153 offset:22528
	ds_read_b128 v[240:243], v153 offset:23552
	global_load_lds_dwordx4 v[226:227], off
	v_lshl_add_u64 v[244:245], v[220:221], 0, v[128:129]
	s_add_i32 m0, s65, 0x2000
	v_lshl_add_u64 v[220:221], v[220:221], 0, s[12:13]
	s_add_i32 s10, s10, s45
	global_load_lds_dwordx4 v[244:245], off
	v_lshl_add_u64 v[246:247], v[220:221], 0, v[168:169]
	s_mov_b32 m0, s10
	v_lshl_add_u64 v[220:221], v[220:221], 0, v[128:129]
	global_load_lds_dwordx4 v[246:247], off
	s_add_i32 m0, s10, 0x2000
	v_lshl_add_u64 v[248:249], v[166:167], 0, v[132:133]
	global_load_lds_dwordx4 v[220:221], off
	s_mov_b32 m0, s51
	v_lshl_add_u64 v[250:251], v[166:167], 0, v[130:131]
	global_load_lds_dwordx4 v[248:249], off
	s_mov_b32 m0, s52
	s_nop 0
	global_load_lds_dwordx4 v[250:251], off
	s_waitcnt vmcnt(16)
	s_waitcnt lgkmcnt(0)
	s_barrier
	s_setprio 1
	s_waitcnt lgkmcnt(0)
	v_mfma_f32_16x16x32_bf16 v[56:59], v[146:149], v[192:195], 0
	v_mfma_f32_16x16x32_bf16 v[48:51], v[158:161], v[192:195], 0
	v_mfma_f32_16x16x32_bf16 v[40:43], v[146:149], v[200:203], 0
	v_mfma_f32_16x16x32_bf16 v[32:35], v[158:161], v[200:203], 0
	v_mfma_f32_16x16x32_bf16 v[24:27], v[146:149], v[208:211], 0
	v_mfma_f32_16x16x32_bf16 v[16:19], v[158:161], v[208:211], 0
	v_mfma_f32_16x16x32_bf16 v[8:11], v[146:149], v[216:219], 0
	v_mfma_f32_16x16x32_bf16 v[4:7], v[158:161], v[216:219], 0
	v_mfma_f32_16x16x32_bf16 v[56:59], v[154:157], v[196:199], v[56:59]
	v_mfma_f32_16x16x32_bf16 v[48:51], v[162:165], v[196:199], v[48:51]
	v_mfma_f32_16x16x32_bf16 v[40:43], v[154:157], v[204:207], v[40:43]
	v_mfma_f32_16x16x32_bf16 v[32:35], v[162:165], v[204:207], v[32:35]
	v_mfma_f32_16x16x32_bf16 v[24:27], v[154:157], v[212:215], v[24:27]
	v_mfma_f32_16x16x32_bf16 v[16:19], v[162:165], v[212:215], v[16:19]
	v_mfma_f32_16x16x32_bf16 v[8:11], v[154:157], v[240:243], v[8:11]
	v_mfma_f32_16x16x32_bf16 v[4:7], v[162:165], v[240:243], v[4:7]
	s_setprio 0
	s_setprio 1
	v_mfma_f32_16x16x32_bf16 v[60:63], v[176:179], v[192:195], 0
	v_mfma_f32_16x16x32_bf16 v[52:55], v[184:187], v[192:195], 0
	v_mfma_f32_16x16x32_bf16 v[44:47], v[176:179], v[200:203], 0
	v_mfma_f32_16x16x32_bf16 v[36:39], v[184:187], v[200:203], 0
	v_mfma_f32_16x16x32_bf16 v[28:31], v[176:179], v[208:211], 0
	v_mfma_f32_16x16x32_bf16 v[20:23], v[184:187], v[208:211], 0
	v_mfma_f32_16x16x32_bf16 v[12:15], v[176:179], v[216:219], 0
	v_mfma_f32_16x16x32_bf16 v[0:3], v[184:187], v[216:219], 0
	v_mfma_f32_16x16x32_bf16 v[60:63], v[180:183], v[196:199], v[60:63]
	v_mfma_f32_16x16x32_bf16 v[52:55], v[188:191], v[196:199], v[52:55]
	v_mfma_f32_16x16x32_bf16 v[44:47], v[180:183], v[204:207], v[44:47]
	v_mfma_f32_16x16x32_bf16 v[36:39], v[188:191], v[204:207], v[36:39]
	v_mfma_f32_16x16x32_bf16 v[28:31], v[180:183], v[212:215], v[28:31]
	v_mfma_f32_16x16x32_bf16 v[20:23], v[188:191], v[212:215], v[20:23]
	v_mfma_f32_16x16x32_bf16 v[12:15], v[180:183], v[240:243], v[12:15]
	v_mfma_f32_16x16x32_bf16 v[0:3], v[188:191], v[240:243], v[0:3]
	s_setprio 0
	s_barrier
	s_add_i32 s10, 0, 0x18000
	v_add_u32_e32 v150, s10, v151
	s_add_i32 s65, 0, 0x1c000
	ds_read_b128 v[146:149], v150
	ds_read_b128 v[154:157], v150 offset:1024
	ds_read_b128 v[158:161], v150 offset:2048
	ds_read_b128 v[162:165], v150 offset:3072
	v_add_u32_e32 v150, s65, v151
	ds_read_b128 v[176:179], v150
	ds_read_b128 v[180:183], v150 offset:1024
	ds_read_b128 v[184:187], v150 offset:2048
	ds_read_b128 v[188:191], v150 offset:3072
	v_lshl_add_u64 v[166:167], v[166:167], 0, s[94:95]
	s_mov_b32 m0, s53
	v_lshl_add_u64 v[252:253], v[166:167], 0, v[132:133]
	ds_read_b128 v[192:195], v153 offset:32768
	ds_read_b128 v[196:199], v153 offset:33792
	ds_read_b128 v[200:203], v153 offset:34816
	ds_read_b128 v[204:207], v153 offset:35840
	ds_read_b128 v[208:211], v153 offset:36864
	ds_read_b128 v[212:215], v153 offset:37888
	ds_read_b128 v[216:219], v153 offset:38912
	ds_read_b128 v[240:243], v153 offset:39936
	global_load_lds_dwordx4 v[252:253], off
	v_lshl_add_u64 v[166:167], v[166:167], 0, v[130:131]
	s_mov_b32 m0, s54
	s_nop 0
	global_load_lds_dwordx4 v[166:167], off
	s_waitcnt vmcnt(12)
	s_waitcnt lgkmcnt(0)
	s_barrier
; #define PG8_STAGE(bufoff, gbase, voff) do { _Pragma("unroll") for (int _i = 0; _i < 2; ++_i) \
;         __builtin_amdgcn_global_load_lds((const unsigned*)((const char*)(gbase) + (voff)[_i]), (LAS unsigned*)(lds + (bufoff) + ldsw + _i * 8192), 16, 0, 0); } while (0)
; #define PG8_LDA(dst, b, h) do { _Pragma("unroll") for (int m = 0; m < 4; ++m) _Pragma("unroll") for (int k = 0; k < 2; ++k) dst[m][k] = *(const LAS bf16x8*)(lds + PG8_SA(b, h) + aoff + m * 2048 + k * 1024); } while (0)
; #define PG8_LDB(dst, b, h) do { _Pragma("unroll") for (int n = 0; n < 2; ++n) _Pragma("unroll") for (int k = 0; k < 2; ++k) dst[n][k] = *(const LAS bf16x8*)(lds + PG8_SB(b, h) + boff + n * 2048 + k * 1024); } while (0)
; #define PG8_MMA(ai, bj, At, Bt) do { __builtin_amdgcn_s_setprio(1); _Pragma("unroll") for (int k = 0; k < 2; ++k) _Pragma("unroll") for (int m = 0; m < 4; ++m) _Pragma("unroll") for (int n = 0; n < 2; ++n) \
;         acc[ai][bj][m][n] = __builtin_amdgcn_mfma_f32_16x16x32_bf16(Bt[n][k], At[m][k], acc[ai][bj][m][n], 0, 0, 0); __builtin_amdgcn_s_setprio(0); } while (0)
; #define PG8_WAIT_V(n) asm volatile("s_waitcnt vmcnt(" #n ")" ::: "memory")
; #define PG8_WAIT_L(n) asm volatile("s_waitcnt lgkmcnt(" #n ")" ::: "memory")
; #define PG8_BAR __builtin_amdgcn_s_barrier()
; #define PG8_SCHED __builtin_amdgcn_sched_barrier(0)
; template <class Epi, bool ALIGN_EPI>
; __device__ __forceinline__ void gemm_phase(LAS unsigned char* lds, const Gemm g, const StaticOrder& S, const Epi& E, const int tid) {
;     ...
;             PG8_LDB(B0, 1, 0); PG8_LDB(B1, 1, 1); PG8_SCHED; PG8_LDA(At, 1, 0); PG8_STAGE(PG8_SA(0, 1), a2 + hA, voffA);
;             PG8_WAIT_V(8); PG8_WAIT_L(0); PG8_BAR; PG8_MMA(0, 0, At, B0); PG8_MMA(0, 1, At, B1); PG8_BAR; PG8_SCHED;
;             PG8_LDA(At, 1, 1); PG8_STAGE(PG8_SB(1, 0), b3, voffB); PG8_STAGE(PG8_SB(1, 1), b3 + hB, voffB); PG8_STAGE(PG8_SA(1, 0), a3, voffA);
;             PG8_WAIT_V(8); PG8_WAIT_L(0); PG8_BAR; PG8_MMA(1, 0, At, B0); PG8_MMA(1, 1, At, B1); PG8_BAR; PG8_SCHED;
	s_setprio 1
	s_waitcnt lgkmcnt(0)
	v_mfma_f32_16x16x32_bf16 v[120:123], v[146:149], v[192:195], v[120:123]
	v_mfma_f32_16x16x32_bf16 v[112:115], v[158:161], v[192:195], v[112:115]
	v_mfma_f32_16x16x32_bf16 v[104:107], v[146:149], v[200:203], v[104:107]
	v_mfma_f32_16x16x32_bf16 v[96:99], v[158:161], v[200:203], v[96:99]
	v_mfma_f32_16x16x32_bf16 v[88:91], v[146:149], v[208:211], v[88:91]
	v_mfma_f32_16x16x32_bf16 v[80:83], v[158:161], v[208:211], v[80:83]
	v_mfma_f32_16x16x32_bf16 v[72:75], v[146:149], v[216:219], v[72:75]
	v_mfma_f32_16x16x32_bf16 v[64:67], v[158:161], v[216:219], v[64:67]
	v_mfma_f32_16x16x32_bf16 v[120:123], v[154:157], v[196:199], v[120:123]
	v_mfma_f32_16x16x32_bf16 v[112:115], v[162:165], v[196:199], v[112:115]
	v_mfma_f32_16x16x32_bf16 v[104:107], v[154:157], v[204:207], v[104:107]
	v_mfma_f32_16x16x32_bf16 v[96:99], v[162:165], v[204:207], v[96:99]
	v_mfma_f32_16x16x32_bf16 v[88:91], v[154:157], v[212:215], v[88:91]
	v_mfma_f32_16x16x32_bf16 v[80:83], v[162:165], v[212:215], v[80:83]
	v_mfma_f32_16x16x32_bf16 v[72:75], v[154:157], v[240:243], v[72:75]
	v_mfma_f32_16x16x32_bf16 v[64:67], v[162:165], v[240:243], v[64:67]
	s_setprio 0
	s_setprio 1
	v_mfma_f32_16x16x32_bf16 v[124:127], v[176:179], v[192:195], v[124:127]
	v_mfma_f32_16x16x32_bf16 v[116:119], v[184:187], v[192:195], v[116:119]
	v_mfma_f32_16x16x32_bf16 v[108:111], v[176:179], v[200:203], v[108:111]
	v_mfma_f32_16x16x32_bf16 v[100:103], v[184:187], v[200:203], v[100:103]
	v_mfma_f32_16x16x32_bf16 v[92:95], v[176:179], v[208:211], v[92:95]
	v_mfma_f32_16x16x32_bf16 v[84:87], v[184:187], v[208:211], v[84:87]
	v_mfma_f32_16x16x32_bf16 v[76:79], v[176:179], v[216:219], v[76:79]
	v_mfma_f32_16x16x32_bf16 v[68:71], v[184:187], v[216:219], v[68:71]
	v_mfma_f32_16x16x32_bf16 v[124:127], v[180:183], v[196:199], v[124:127]
	v_mfma_f32_16x16x32_bf16 v[116:119], v[188:191], v[196:199], v[116:119]
	v_mfma_f32_16x16x32_bf16 v[108:111], v[180:183], v[204:207], v[108:111]
	v_mfma_f32_16x16x32_bf16 v[100:103], v[188:191], v[204:207], v[100:103]
	v_mfma_f32_16x16x32_bf16 v[92:95], v[180:183], v[212:215], v[92:95]
	v_mfma_f32_16x16x32_bf16 v[84:87], v[188:191], v[212:215], v[84:87]
	v_mfma_f32_16x16x32_bf16 v[76:79], v[180:183], v[240:243], v[76:79]
	v_mfma_f32_16x16x32_bf16 v[68:71], v[188:191], v[240:243], v[68:71]
	s_setprio 0
	s_barrier
	s_add_i32 s10, s10, s45
	v_lshl_add_u64 v[166:167], v[226:227], 0, s[92:93]
	s_mov_b32 m0, s10
	ds_read_b128 v[192:195], v153 offset:49152
	ds_read_b128 v[196:199], v153 offset:50176
	ds_read_b128 v[200:203], v153 offset:51200
	ds_read_b128 v[204:207], v153 offset:52224
	ds_read_b128 v[208:211], v153 offset:53248
	ds_read_b128 v[212:215], v153 offset:54272
	ds_read_b128 v[216:219], v153 offset:55296
	ds_read_b128 v[240:243], v153 offset:56320
	global_load_lds_dwordx4 v[166:167], off
	v_lshl_add_u64 v[166:167], v[244:245], 0, s[92:93]
	s_add_i32 m0, s10, 0x2000
	s_add_i32 s10, s65, s45
	global_load_lds_dwordx4 v[166:167], off
	v_lshl_add_u64 v[166:167], v[246:247], 0, s[92:93]
	s_mov_b32 m0, s10
	s_nop 0
	global_load_lds_dwordx4 v[166:167], off
	v_lshl_add_u64 v[166:167], v[220:221], 0, s[92:93]
	s_add_i32 m0, s10, 0x2000
	s_nop 0
	global_load_lds_dwordx4 v[166:167], off
	v_lshl_add_u64 v[166:167], v[248:249], 0, s[92:93]
	s_mov_b32 m0, s56
	s_nop 0
	global_load_lds_dwordx4 v[166:167], off
	v_lshl_add_u64 v[166:167], v[250:251], 0, s[92:93]
	s_mov_b32 m0, s57
	s_nop 0
	global_load_lds_dwordx4 v[166:167], off
	s_waitcnt vmcnt(8)
	s_waitcnt lgkmcnt(0)
	s_barrier
	s_setprio 1
	s_waitcnt lgkmcnt(0)
	v_mfma_f32_16x16x32_bf16 v[56:59], v[146:149], v[192:195], v[56:59]
	v_mfma_f32_16x16x32_bf16 v[48:51], v[158:161], v[192:195], v[48:51]
	v_mfma_f32_16x16x32_bf16 v[40:43], v[146:149], v[200:203], v[40:43]
	v_mfma_f32_16x16x32_bf16 v[32:35], v[158:161], v[200:203], v[32:35]
	v_mfma_f32_16x16x32_bf16 v[24:27], v[146:149], v[208:211], v[24:27]
	v_mfma_f32_16x16x32_bf16 v[16:19], v[158:161], v[208:211], v[16:19]
	v_mfma_f32_16x16x32_bf16 v[8:11], v[146:149], v[216:219], v[8:11]
	v_mfma_f32_16x16x32_bf16 v[4:7], v[158:161], v[216:219], v[4:7]
	v_mfma_f32_16x16x32_bf16 v[56:59], v[154:157], v[196:199], v[56:59]
	v_mfma_f32_16x16x32_bf16 v[48:51], v[162:165], v[196:199], v[48:51]
	v_mfma_f32_16x16x32_bf16 v[40:43], v[154:157], v[204:207], v[40:43]
	v_mfma_f32_16x16x32_bf16 v[32:35], v[162:165], v[204:207], v[32:35]
	v_mfma_f32_16x16x32_bf16 v[24:27], v[154:157], v[212:215], v[24:27]
	v_mfma_f32_16x16x32_bf16 v[16:19], v[162:165], v[212:215], v[16:19]
	v_mfma_f32_16x16x32_bf16 v[8:11], v[154:157], v[240:243], v[8:11]
	v_mfma_f32_16x16x32_bf16 v[4:7], v[162:165], v[240:243], v[4:7]
	s_setprio 0
	s_setprio 1
	v_mfma_f32_16x16x32_bf16 v[60:63], v[176:179], v[192:195], v[60:63]
	v_mfma_f32_16x16x32_bf16 v[52:55], v[184:187], v[192:195], v[52:55]
	v_mfma_f32_16x16x32_bf16 v[44:47], v[176:179], v[200:203], v[44:47]
	v_mfma_f32_16x16x32_bf16 v[36:39], v[184:187], v[200:203], v[36:39]
	v_mfma_f32_16x16x32_bf16 v[28:31], v[176:179], v[208:211], v[28:31]
	v_mfma_f32_16x16x32_bf16 v[20:23], v[184:187], v[208:211], v[20:23]
	v_mfma_f32_16x16x32_bf16 v[12:15], v[176:179], v[216:219], v[12:15]
	v_mfma_f32_16x16x32_bf16 v[0:3], v[184:187], v[216:219], v[0:3]
	v_mfma_f32_16x16x32_bf16 v[60:63], v[180:183], v[196:199], v[60:63]
	v_mfma_f32_16x16x32_bf16 v[52:55], v[188:191], v[196:199], v[52:55]
	v_mfma_f32_16x16x32_bf16 v[44:47], v[180:183], v[204:207], v[44:47]
	v_mfma_f32_16x16x32_bf16 v[36:39], v[188:191], v[204:207], v[36:39]
	v_mfma_f32_16x16x32_bf16 v[28:31], v[180:183], v[212:215], v[28:31]
	v_mfma_f32_16x16x32_bf16 v[20:23], v[188:191], v[212:215], v[20:23]
	v_mfma_f32_16x16x32_bf16 v[12:15], v[180:183], v[240:243], v[12:15]
	v_mfma_f32_16x16x32_bf16 v[0:3], v[188:191], v[240:243], v[0:3]
	s_setprio 0
	s_barrier
	v_lshl_add_u64 v[142:143], v[142:143], 0, s[80:81]
	v_lshl_add_u64 v[144:145], v[144:145], 0, s[80:81]
	s_mov_b32 s10, s11
	s_cmp_eq_u32 s10, s58
	s_cbranch_scc1 .Lgu_last
	s_branch .LBB0_308

; #define PG8_STAGE(bufoff, gbase, voff) do { _Pragma("unroll") for (int _i = 0; _i < 2; ++_i) \
;         __builtin_amdgcn_global_load_lds((const unsigned*)((const char*)(gbase) + (voff)[_i]), (LAS unsigned*)(lds + (bufoff) + ldsw + _i * 8192), 16, 0, 0); } while (0)
; #define PG8_LDA(dst, b, h) do { _Pragma("unroll") for (int m = 0; m < 4; ++m) _Pragma("unroll") for (int k = 0; k < 2; ++k) dst[m][k] = *(const LAS bf16x8*)(lds + PG8_SA(b, h) + aoff + m * 2048 + k * 1024); } while (0)
; #define PG8_LDB(dst, b, h) do { _Pragma("unroll") for (int n = 0; n < 2; ++n) _Pragma("unroll") for (int k = 0; k < 2; ++k) dst[n][k] = *(const LAS bf16x8*)(lds + PG8_SB(b, h) + boff + n * 2048 + k * 1024); } while (0)
; #define PG8_MMA(ai, bj, At, Bt) do { __builtin_amdgcn_s_setprio(1); _Pragma("unroll") for (int k = 0; k < 2; ++k) _Pragma("unroll") for (int m = 0; m < 4; ++m) _Pragma("unroll") for (int n = 0; n < 2; ++n) \
;         acc[ai][bj][m][n] = __builtin_amdgcn_mfma_f32_16x16x32_bf16(Bt[n][k], At[m][k], acc[ai][bj][m][n], 0, 0, 0); __builtin_amdgcn_s_setprio(0); } while (0)
; #define PG8_WAIT_V(n) asm volatile("s_waitcnt vmcnt(" #n ")" ::: "memory")
; template <class Epi, bool ALIGN_EPI>
; __device__ __forceinline__ void gemm_phase(LAS unsigned char* lds, const Gemm g, const StaticOrder& S, const Epi& E, const int tid) {
;     ...
;         const char* nA = has_next ? (const char*)g.A + (size_t)nxt.pm * tA + (size_t)nxt.pn * g.apn * 2 : cA; const char* nB = has_next ? (const char*)g.Bt + (size_t)nxt.pn * tB : cB;
;         for (int t = 0; t < nt; t += 2) {
;             const bool last = (t == nt - 2);
;             const char* a1 = cA + (size_t)(t + 1) * kstep;
;             const char* a2 = last ? nA : cA + (size_t)(t + 2) * kstep; const char* b2 = last ? nB : cB + (size_t)(t + 2) * kstep;
;             const char* a3 = a2 + kstep; const char* b3 = b2 + kstep;
;             PG8_LDB(B0, 0, 0); PG8_LDB(B1, 0, 1); PG8_SCHED; PG8_LDA(At, 0, 0); PG8_STAGE(PG8_SA(1, 1), a1 + hA, voffA);
;             PG8_WAIT_V(8); PG8_WAIT_L(0); PG8_BAR; PG8_MMA(0, 0, At, B0); PG8_MMA(0, 1, At, B1); PG8_BAR; PG8_SCHED;
;             PG8_LDA(At, 0, 1); PG8_STAGE(PG8_SB(0, 0), b2, voffB); PG8_STAGE(PG8_SB(0, 1), b2 + hB, voffB); PG8_STAGE(PG8_SA(0, 0), a2, voffA);
;             PG8_WAIT_V(8); PG8_WAIT_L(0); PG8_BAR; PG8_MMA(1, 0, At, B0); PG8_MMA(1, 1, At, B1); PG8_BAR; PG8_SCHED;
.Lgu_last:
	s_add_i32 s11, s10, 2
	s_cmp_eq_u32 s58, s10
	v_lshl_add_u64 v[146:147], v[142:143], 0, s[92:93]
	s_cselect_b64 vcc, -1, 0
	v_add_u32_e32 v150, s33, v151
	s_add_i32 s10, 0, 0x14000
	v_cndmask_b32_e32 v167, v147, v139, vcc
	v_cndmask_b32_e32 v166, v146, v138, vcc
	ds_read_b128 v[146:149], v150
	ds_read_b128 v[154:157], v150 offset:1024
	ds_read_b128 v[158:161], v150 offset:2048
	ds_read_b128 v[162:165], v150 offset:3072
	v_add_u32_e32 v150, s10, v151
	ds_read_b128 v[176:179], v150
	ds_read_b128 v[180:183], v150 offset:1024
	ds_read_b128 v[184:187], v150 offset:2048
	ds_read_b128 v[188:191], v150 offset:3072
	v_cndmask_b32_e32 v221, v145, v141, vcc
	v_cndmask_b32_e32 v220, v144, v140, vcc
	v_lshl_add_u64 v[226:227], v[142:143], 0, v[134:135]
	s_add_i32 m0, s51, 0xc000
	ds_read_b128 v[192:195], v153
	ds_read_b128 v[196:199], v153 offset:1024
	ds_read_b128 v[200:203], v153 offset:2048
	ds_read_b128 v[204:207], v153 offset:3072
	ds_read_b128 v[208:211], v153 offset:4096
	ds_read_b128 v[212:215], v153 offset:5120
	ds_read_b128 v[216:219], v153 offset:6144
	ds_read_b128 v[240:243], v153 offset:7168
	global_load_lds_dwordx4 v[226:227], off
	v_lshl_add_u64 v[226:227], v[142:143], 0, v[136:137]
	s_add_i32 m0, s51, 0xe000
	s_nop 0
	global_load_lds_dwordx4 v[226:227], off
	s_waitcnt vmcnt(8)
	s_waitcnt lgkmcnt(0)
	s_barrier
	s_setprio 1
	s_waitcnt lgkmcnt(0)
	v_mfma_f32_16x16x32_bf16 v[120:123], v[146:149], v[192:195], v[120:123]
	v_mfma_f32_16x16x32_bf16 v[112:115], v[158:161], v[192:195], v[112:115]
	v_mfma_f32_16x16x32_bf16 v[104:107], v[146:149], v[200:203], v[104:107]
	v_mfma_f32_16x16x32_bf16 v[96:99], v[158:161], v[200:203], v[96:99]
	v_mfma_f32_16x16x32_bf16 v[88:91], v[146:149], v[208:211], v[88:91]
	v_mfma_f32_16x16x32_bf16 v[80:83], v[158:161], v[208:211], v[80:83]
	v_mfma_f32_16x16x32_bf16 v[72:75], v[146:149], v[216:219], v[72:75]
	v_mfma_f32_16x16x32_bf16 v[64:67], v[158:161], v[216:219], v[64:67]
	v_mfma_f32_16x16x32_bf16 v[120:123], v[154:157], v[196:199], v[120:123]
	v_mfma_f32_16x16x32_bf16 v[112:115], v[162:165], v[196:199], v[112:115]
	v_mfma_f32_16x16x32_bf16 v[104:107], v[154:157], v[204:207], v[104:107]
	v_mfma_f32_16x16x32_bf16 v[96:99], v[162:165], v[204:207], v[96:99]
	v_mfma_f32_16x16x32_bf16 v[88:91], v[154:157], v[212:215], v[88:91]
	v_mfma_f32_16x16x32_bf16 v[80:83], v[162:165], v[212:215], v[80:83]
	v_mfma_f32_16x16x32_bf16 v[72:75], v[154:157], v[240:243], v[72:75]
	v_mfma_f32_16x16x32_bf16 v[64:67], v[162:165], v[240:243], v[64:67]
	s_setprio 0
	s_setprio 1
	v_mfma_f32_16x16x32_bf16 v[124:127], v[176:179], v[192:195], v[124:127]
	v_mfma_f32_16x16x32_bf16 v[116:119], v[184:187], v[192:195], v[116:119]
	v_mfma_f32_16x16x32_bf16 v[108:111], v[176:179], v[200:203], v[108:111]
	v_mfma_f32_16x16x32_bf16 v[100:103], v[184:187], v[200:203], v[100:103]
	v_mfma_f32_16x16x32_bf16 v[92:95], v[176:179], v[208:211], v[92:95]
	v_mfma_f32_16x16x32_bf16 v[84:87], v[184:187], v[208:211], v[84:87]
	v_mfma_f32_16x16x32_bf16 v[76:79], v[176:179], v[216:219], v[76:79]
	v_mfma_f32_16x16x32_bf16 v[68:71], v[184:187], v[216:219], v[68:71]
	v_mfma_f32_16x16x32_bf16 v[124:127], v[180:183], v[196:199], v[124:127]
	v_mfma_f32_16x16x32_bf16 v[116:119], v[188:191], v[196:199], v[116:119]
	v_mfma_f32_16x16x32_bf16 v[108:111], v[180:183], v[204:207], v[108:111]
	v_mfma_f32_16x16x32_bf16 v[100:103], v[188:191], v[204:207], v[100:103]
	v_mfma_f32_16x16x32_bf16 v[92:95], v[180:183], v[212:215], v[92:95]
	v_mfma_f32_16x16x32_bf16 v[84:87], v[188:191], v[212:215], v[84:87]
	v_mfma_f32_16x16x32_bf16 v[76:79], v[180:183], v[240:243], v[76:79]
	v_mfma_f32_16x16x32_bf16 v[68:71], v[188:191], v[240:243], v[68:71]
	s_setprio 0
	s_barrier
	s_add_i32 s65, s33, s45
	v_lshl_add_u64 v[226:227], v[220:221], 0, v[168:169]
	s_mov_b32 m0, s65
	ds_read_b128 v[192:195], v153 offset:16384
	ds_read_b128 v[196:199], v153 offset:17408
	ds_read_b128 v[200:203], v153 offset:18432
	ds_read_b128 v[204:207], v153 offset:19456
	ds_read_b128 v[208:211], v153 offset:20480
	ds_read_b128 v[212:215], v153 offset:21504
	ds_read_b128 v[216:219], v153 offset:22528
	ds_read_b128 v[240:243], v153 offset:23552
	global_load_lds_dwordx4 v[226:227], off
	v_lshl_add_u64 v[244:245], v[220:221], 0, v[128:129]
	s_add_i32 m0, s65, 0x2000
	v_lshl_add_u64 v[220:221], v[220:221], 0, s[12:13]
	s_add_i32 s10, s10, s45
	global_load_lds_dwordx4 v[244:245], off
	v_lshl_add_u64 v[246:247], v[220:221], 0, v[168:169]
	s_mov_b32 m0, s10
	v_lshl_add_u64 v[220:221], v[220:221], 0, v[128:129]
	global_load_lds_dwordx4 v[246:247], off
	s_add_i32 m0, s10, 0x2000
	v_lshl_add_u64 v[248:249], v[166:167], 0, v[132:133]
	global_load_lds_dwordx4 v[220:221], off
	s_mov_b32 m0, s51
	v_lshl_add_u64 v[250:251], v[166:167], 0, v[130:131]
	global_load_lds_dwordx4 v[248:249], off
	s_mov_b32 m0, s52
	s_nop 0
	global_load_lds_dwordx4 v[250:251], off
	s_waitcnt vmcnt(8)
	s_waitcnt lgkmcnt(0)
	s_barrier
; #define PG8_STAGE(bufoff, gbase, voff) do { _Pragma("unroll") for (int _i = 0; _i < 2; ++_i) \
;         __builtin_amdgcn_global_load_lds((const unsigned*)((const char*)(gbase) + (voff)[_i]), (LAS unsigned*)(lds + (bufoff) + ldsw + _i * 8192), 16, 0, 0); } while (0)
; #define PG8_LDA(dst, b, h) do { _Pragma("unroll") for (int m = 0; m < 4; ++m) _Pragma("unroll") for (int k = 0; k < 2; ++k) dst[m][k] = *(const LAS bf16x8*)(lds + PG8_SA(b, h) + aoff + m * 2048 + k * 1024); } while (0)
; #define PG8_LDB(dst, b, h) do { _Pragma("unroll") for (int n = 0; n < 2; ++n) _Pragma("unroll") for (int k = 0; k < 2; ++k) dst[n][k] = *(const LAS bf16x8*)(lds + PG8_SB(b, h) + boff + n * 2048 + k * 1024); } while (0)
; #define PG8_MMA(ai, bj, At, Bt) do { __builtin_amdgcn_s_setprio(1); _Pragma("unroll") for (int k = 0; k < 2; ++k) _Pragma("unroll") for (int m = 0; m < 4; ++m) _Pragma("unroll") for (int n = 0; n < 2; ++n) \
;         acc[ai][bj][m][n] = __builtin_amdgcn_mfma_f32_16x16x32_bf16(Bt[n][k], At[m][k], acc[ai][bj][m][n], 0, 0, 0); __builtin_amdgcn_s_setprio(0); } while (0)
; #define PG8_WAIT_V(n) asm volatile("s_waitcnt vmcnt(" #n ")" ::: "memory")
; #define PG8_WAIT_L(n) asm volatile("s_waitcnt lgkmcnt(" #n ")" ::: "memory")
; #define PG8_BAR __builtin_amdgcn_s_barrier()
; #define PG8_SCHED __builtin_amdgcn_sched_barrier(0)
; template <class Epi, bool ALIGN_EPI>
; __device__ __forceinline__ void gemm_phase(LAS unsigned char* lds, const Gemm g, const StaticOrder& S, const Epi& E, const int tid) {
;     ...
;             PG8_LDA(At, 0, 1); PG8_STAGE(PG8_SB(0, 0), b2, voffB); PG8_STAGE(PG8_SB(0, 1), b2 + hB, voffB); PG8_STAGE(PG8_SA(0, 0), a2, voffA);
;             PG8_WAIT_V(8); PG8_WAIT_L(0); PG8_BAR; PG8_MMA(1, 0, At, B0); PG8_MMA(1, 1, At, B1); PG8_BAR; PG8_SCHED;
;             PG8_LDB(B0, 1, 0); PG8_LDB(B1, 1, 1); PG8_SCHED; PG8_LDA(At, 1, 0); PG8_STAGE(PG8_SA(0, 1), a2 + hA, voffA);
;             PG8_WAIT_V(8); PG8_WAIT_L(0); PG8_BAR; PG8_MMA(0, 0, At, B0); PG8_MMA(0, 1, At, B1); PG8_BAR; PG8_SCHED;
;             PG8_LDA(At, 1, 1); PG8_STAGE(PG8_SB(1, 0), b3, voffB); PG8_STAGE(PG8_SB(1, 1), b3 + hB, voffB); PG8_STAGE(PG8_SA(1, 0), a3, voffA);
;             PG8_WAIT_V(8); PG8_WAIT_L(0); PG8_BAR; PG8_MMA(1, 0, At, B0); PG8_MMA(1, 1, At, B1); PG8_BAR; PG8_SCHED;
	s_setprio 1
	s_waitcnt lgkmcnt(0)
	v_mfma_f32_16x16x32_bf16 v[56:59], v[146:149], v[192:195], v[56:59]
	v_mfma_f32_16x16x32_bf16 v[48:51], v[158:161], v[192:195], v[48:51]
	v_mfma_f32_16x16x32_bf16 v[40:43], v[146:149], v[200:203], v[40:43]
	v_mfma_f32_16x16x32_bf16 v[32:35], v[158:161], v[200:203], v[32:35]
	v_mfma_f32_16x16x32_bf16 v[24:27], v[146:149], v[208:211], v[24:27]
	v_mfma_f32_16x16x32_bf16 v[16:19], v[158:161], v[208:211], v[16:19]
	v_mfma_f32_16x16x32_bf16 v[8:11], v[146:149], v[216:219], v[8:11]
	v_mfma_f32_16x16x32_bf16 v[4:7], v[158:161], v[216:219], v[4:7]
	v_mfma_f32_16x16x32_bf16 v[56:59], v[154:157], v[196:199], v[56:59]
	v_mfma_f32_16x16x32_bf16 v[48:51], v[162:165], v[196:199], v[48:51]
	v_mfma_f32_16x16x32_bf16 v[40:43], v[154:157], v[204:207], v[40:43]
	v_mfma_f32_16x16x32_bf16 v[32:35], v[162:165], v[204:207], v[32:35]
	v_mfma_f32_16x16x32_bf16 v[24:27], v[154:157], v[212:215], v[24:27]
	v_mfma_f32_16x16x32_bf16 v[16:19], v[162:165], v[212:215], v[16:19]
	v_mfma_f32_16x16x32_bf16 v[8:11], v[154:157], v[240:243], v[8:11]
	v_mfma_f32_16x16x32_bf16 v[4:7], v[162:165], v[240:243], v[4:7]
	s_setprio 0
	s_setprio 1
	v_mfma_f32_16x16x32_bf16 v[60:63], v[176:179], v[192:195], v[60:63]
	v_mfma_f32_16x16x32_bf16 v[52:55], v[184:187], v[192:195], v[52:55]
	v_mfma_f32_16x16x32_bf16 v[44:47], v[176:179], v[200:203], v[44:47]
	v_mfma_f32_16x16x32_bf16 v[36:39], v[184:187], v[200:203], v[36:39]
	v_mfma_f32_16x16x32_bf16 v[28:31], v[176:179], v[208:211], v[28:31]
	v_mfma_f32_16x16x32_bf16 v[20:23], v[184:187], v[208:211], v[20:23]
	v_mfma_f32_16x16x32_bf16 v[12:15], v[176:179], v[216:219], v[12:15]
	v_mfma_f32_16x16x32_bf16 v[0:3], v[184:187], v[216:219], v[0:3]
	v_mfma_f32_16x16x32_bf16 v[60:63], v[180:183], v[196:199], v[60:63]
	v_mfma_f32_16x16x32_bf16 v[52:55], v[188:191], v[196:199], v[52:55]
	v_mfma_f32_16x16x32_bf16 v[44:47], v[180:183], v[204:207], v[44:47]
	v_mfma_f32_16x16x32_bf16 v[36:39], v[188:191], v[204:207], v[36:39]
	v_mfma_f32_16x16x32_bf16 v[28:31], v[180:183], v[212:215], v[28:31]
	v_mfma_f32_16x16x32_bf16 v[20:23], v[188:191], v[212:215], v[20:23]
	v_mfma_f32_16x16x32_bf16 v[12:15], v[180:183], v[240:243], v[12:15]
	v_mfma_f32_16x16x32_bf16 v[0:3], v[188:191], v[240:243], v[0:3]
	s_setprio 0
	s_barrier
	s_add_i32 s10, 0, 0x18000
	v_add_u32_e32 v150, s10, v151
	s_add_i32 s65, 0, 0x1c000
	ds_read_b128 v[146:149], v150
	ds_read_b128 v[154:157], v150 offset:1024
	ds_read_b128 v[158:161], v150 offset:2048
	ds_read_b128 v[162:165], v150 offset:3072
	v_add_u32_e32 v150, s65, v151
	ds_read_b128 v[176:179], v150
	ds_read_b128 v[180:183], v150 offset:1024
	ds_read_b128 v[184:187], v150 offset:2048
	ds_read_b128 v[188:191], v150 offset:3072
	v_lshl_add_u64 v[166:167], v[166:167], 0, s[94:95]
	s_mov_b32 m0, s53
	v_lshl_add_u64 v[252:253], v[166:167], 0, v[132:133]
	ds_read_b128 v[192:195], v153 offset:32768
	ds_read_b128 v[196:199], v153 offset:33792
	ds_read_b128 v[200:203], v153 offset:34816
	ds_read_b128 v[204:207], v153 offset:35840
	ds_read_b128 v[208:211], v153 offset:36864
	ds_read_b128 v[212:215], v153 offset:37888
	ds_read_b128 v[216:219], v153 offset:38912
	ds_read_b128 v[240:243], v153 offset:39936
	global_load_lds_dwordx4 v[252:253], off
	v_lshl_add_u64 v[166:167], v[166:167], 0, v[130:131]
	s_mov_b32 m0, s54
	s_nop 0
	global_load_lds_dwordx4 v[166:167], off
	s_waitcnt vmcnt(8)
	s_waitcnt lgkmcnt(0)
	s_barrier
	s_setprio 1
	s_waitcnt lgkmcnt(0)
	v_mfma_f32_16x16x32_bf16 v[120:123], v[146:149], v[192:195], v[120:123]
	v_mfma_f32_16x16x32_bf16 v[112:115], v[158:161], v[192:195], v[112:115]
	v_mfma_f32_16x16x32_bf16 v[104:107], v[146:149], v[200:203], v[104:107]
	v_mfma_f32_16x16x32_bf16 v[96:99], v[158:161], v[200:203], v[96:99]
	v_mfma_f32_16x16x32_bf16 v[88:91], v[146:149], v[208:211], v[88:91]
	v_mfma_f32_16x16x32_bf16 v[80:83], v[158:161], v[208:211], v[80:83]
	v_mfma_f32_16x16x32_bf16 v[72:75], v[146:149], v[216:219], v[72:75]
	v_mfma_f32_16x16x32_bf16 v[64:67], v[158:161], v[216:219], v[64:67]
	v_mfma_f32_16x16x32_bf16 v[120:123], v[154:157], v[196:199], v[120:123]
	v_mfma_f32_16x16x32_bf16 v[112:115], v[162:165], v[196:199], v[112:115]
	v_mfma_f32_16x16x32_bf16 v[104:107], v[154:157], v[204:207], v[104:107]
	v_mfma_f32_16x16x32_bf16 v[96:99], v[162:165], v[204:207], v[96:99]
	v_mfma_f32_16x16x32_bf16 v[88:91], v[154:157], v[212:215], v[88:91]
	v_mfma_f32_16x16x32_bf16 v[80:83], v[162:165], v[212:215], v[80:83]
	v_mfma_f32_16x16x32_bf16 v[72:75], v[154:157], v[240:243], v[72:75]
	v_mfma_f32_16x16x32_bf16 v[64:67], v[162:165], v[240:243], v[64:67]
	s_setprio 0
	s_setprio 1
	v_mfma_f32_16x16x32_bf16 v[124:127], v[176:179], v[192:195], v[124:127]
	v_mfma_f32_16x16x32_bf16 v[116:119], v[184:187], v[192:195], v[116:119]
	v_mfma_f32_16x16x32_bf16 v[108:111], v[176:179], v[200:203], v[108:111]
	v_mfma_f32_16x16x32_bf16 v[100:103], v[184:187], v[200:203], v[100:103]
	v_mfma_f32_16x16x32_bf16 v[92:95], v[176:179], v[208:211], v[92:95]
	v_mfma_f32_16x16x32_bf16 v[84:87], v[184:187], v[208:211], v[84:87]
	v_mfma_f32_16x16x32_bf16 v[76:79], v[176:179], v[216:219], v[76:79]
	v_mfma_f32_16x16x32_bf16 v[68:71], v[184:187], v[216:219], v[68:71]
	v_mfma_f32_16x16x32_bf16 v[124:127], v[180:183], v[196:199], v[124:127]
	v_mfma_f32_16x16x32_bf16 v[116:119], v[188:191], v[196:199], v[116:119]
	v_mfma_f32_16x16x32_bf16 v[108:111], v[180:183], v[204:207], v[108:111]
	v_mfma_f32_16x16x32_bf16 v[100:103], v[188:191], v[204:207], v[100:103]
	v_mfma_f32_16x16x32_bf16 v[92:95], v[180:183], v[212:215], v[92:95]
	v_mfma_f32_16x16x32_bf16 v[84:87], v[188:191], v[212:215], v[84:87]
	v_mfma_f32_16x16x32_bf16 v[76:79], v[180:183], v[240:243], v[76:79]
	v_mfma_f32_16x16x32_bf16 v[68:71], v[188:191], v[240:243], v[68:71]
	s_setprio 0
	s_barrier
; __device__ __forceinline__ unsigned cvt_pk_bf16(float lo, float hi) { unsigned r; asm volatile("v_cvt_pk_bf16_f32 %0, %1, %2" : "=v"(r) : "v"(lo), "v"(hi)); return r; }
; __device__ __forceinline__ float siluf_(float x) { return x * sigmoidf_(x); }
; #define PG8_STAGE(bufoff, gbase, voff) do { _Pragma("unroll") for (int _i = 0; _i < 2; ++_i) \
;         __builtin_amdgcn_global_load_lds((const unsigned*)((const char*)(gbase) + (voff)[_i]), (LAS unsigned*)(lds + (bufoff) + ldsw + _i * 8192), 16, 0, 0); } while (0)
; #define PG8_LDA(dst, b, h) do { _Pragma("unroll") for (int m = 0; m < 4; ++m) _Pragma("unroll") for (int k = 0; k < 2; ++k) dst[m][k] = *(const LAS bf16x8*)(lds + PG8_SA(b, h) + aoff + m * 2048 + k * 1024); } while (0)
; #define PG8_WAIT_V(n) asm volatile("s_waitcnt vmcnt(" #n ")" ::: "memory")
; #define PG8_BAR __builtin_amdgcn_s_barrier()
;     __device__ __forceinline__ void operator()(const f32x4 (&acc)[2][2][4][2], const Unit& u, int wr, int wc, int fr, int fq) const {
;         const int row0 = u.pm * BM + wr * 64 + fr, col0 = u.pn * HALF + wc * 32 + 8 * fq;
;         float rsv[2][4]; load_rstd(rsv, ssq, row0);
; #pragma unroll
;         for (int ai = 0; ai < 2; ++ai)
; #pragma unroll
;             for (int m = 0; m < 4; ++m) { const int row = row0 + ai * HALF + m * 16; bf16_t* rowp = O + (size_t)row * ldc + col0; const float rs = rsv[ai][m];
;                 f32x4 v0, v1;
; #pragma unroll
;                 for (int j = 0; j < 4; ++j) { v0[j] = siluf_(acc[ai][0][m][0][j] * rs) * (acc[ai][1][m][0][j] * rs); v1[j] = siluf_(acc[ai][0][m][1][j] * rs) * (acc[ai][1][m][1][j] * rs); }
;                 u32x4 w; w.x = cvt_pk_bf16(v0[0], v0[1]); w.y = cvt_pk_bf16(v0[2], v0[3]); w.z = cvt_pk_bf16(v1[0], v1[1]); w.w = cvt_pk_bf16(v1[2], v1[3]);
;                 *(u32x4*)rowp = w; }
; template <class Epi, bool ALIGN_EPI>
; __device__ __forceinline__ void gemm_phase(LAS unsigned char* lds, const Gemm g, const StaticOrder& S, const Epi& E, const int tid) {
;     ...
;             PG8_WAIT_V(8); PG8_WAIT_L(0); PG8_BAR; PG8_MMA(0, 0, At, B0); PG8_MMA(0, 1, At, B1); PG8_BAR; PG8_SCHED;
;             PG8_LDA(At, 1, 1); PG8_STAGE(PG8_SB(1, 0), b3, voffB); PG8_STAGE(PG8_SB(1, 1), b3 + hB, voffB); PG8_STAGE(PG8_SA(1, 0), a3, voffA);
;             PG8_WAIT_V(8); PG8_WAIT_L(0); PG8_BAR; PG8_MMA(1, 0, At, B0); PG8_MMA(1, 1, At, B1); PG8_BAR; PG8_SCHED;
	s_add_i32 s10, s10, s45
	v_lshl_add_u64 v[166:167], v[226:227], 0, s[92:93]
	s_mov_b32 m0, s10
	ds_read_b128 v[192:195], v153 offset:49152
	ds_read_b128 v[196:199], v153 offset:50176
	ds_read_b128 v[200:203], v153 offset:51200
	ds_read_b128 v[204:207], v153 offset:52224
	ds_read_b128 v[208:211], v153 offset:53248
	ds_read_b128 v[212:215], v153 offset:54272
	ds_read_b128 v[216:219], v153 offset:55296
	ds_read_b128 v[240:243], v153 offset:56320
	global_load_lds_dwordx4 v[166:167], off
	v_lshl_add_u64 v[166:167], v[244:245], 0, s[92:93]
	s_add_i32 m0, s10, 0x2000
	s_add_i32 s10, s65, s45
	global_load_lds_dwordx4 v[166:167], off
	v_lshl_add_u64 v[166:167], v[246:247], 0, s[92:93]
	s_mov_b32 m0, s10
	s_nop 0
	global_load_lds_dwordx4 v[166:167], off
	v_lshl_add_u64 v[166:167], v[220:221], 0, s[92:93]
	s_add_i32 m0, s10, 0x2000
	s_nop 0
	global_load_lds_dwordx4 v[166:167], off
	v_lshl_add_u64 v[166:167], v[248:249], 0, s[92:93]
	s_mov_b32 m0, s56
	s_nop 0
	global_load_lds_dwordx4 v[166:167], off
	v_lshl_add_u64 v[166:167], v[250:251], 0, s[92:93]
	s_mov_b32 m0, s57
	s_nop 0
	global_load_lds_dwordx4 v[166:167], off
	s_waitcnt vmcnt(8)
	s_waitcnt lgkmcnt(0)
	s_barrier
	s_setprio 1
	s_waitcnt lgkmcnt(0)
	v_mfma_f32_16x16x32_bf16 v[56:59], v[146:149], v[192:195], v[56:59]
	v_lshrrev_b32_e32 v171, 8, v170
	v_and_b32_e32 v234, 15, v170
	v_lshl_add_u32 v171, v171, 6, v234
	s_lshl_b32 s98, s64, 8
	v_add_u32_e32 v171, s98, v171
	v_mul_lo_u32 v171, v171, s28
	v_bfe_u32 v234, v170, 6, 2
	v_bfe_u32 v224, v170, 4, 2
	v_lshlrev_b32_e32 v234, 5, v234
	v_lshl_or_b32 v234, v224, 3, v234
	v_mfma_f32_16x16x32_bf16 v[48:51], v[158:161], v[192:195], v[48:51]
	s_lshl_b32 s98, s63, 7
	v_add_u32_e32 v234, s98, v234
	v_add_lshl_u32 v232, v171, v234, 1
	s_lshl_b32 s98, s28, 5
	s_mov_b32 s99, 0
	s_mov_b32 s100, 0xbfb8aa3b
	s_mov_b32 s101, 0xbfb8aa3b
	v_mul_f32_e32 v120, v172, v120
	v_mul_f32_e32 v121, v172, v121
	v_mul_f32_e32 v122, v172, v122
	v_mfma_f32_16x16x32_bf16 v[40:43], v[146:149], v[200:203], v[40:43]
	v_mul_f32_e32 v123, v172, v123
	v_mul_f32_e32 v124, v172, v124
	v_mul_f32_e32 v125, v172, v125
	v_mul_f32_e32 v126, v172, v126
	v_mul_f32_e32 v127, v172, v127
	v_mul_f32_e32 v224, s100, v120
	v_mul_f32_e32 v225, s101, v121
	v_mul_f32_e32 v228, s100, v122
	v_mul_f32_e32 v229, s101, v123
	v_exp_f32_e32 v224, v224
	v_mfma_f32_16x16x32_bf16 v[32:35], v[158:161], v[200:203], v[32:35]
	v_exp_f32_e32 v225, v225
	v_exp_f32_e32 v228, v228
	v_exp_f32_e32 v229, v229
	v_add_f32_e32 v224, 1.0, v224
	v_add_f32_e32 v225, 1.0, v225
	v_add_f32_e32 v228, 1.0, v228
	v_add_f32_e32 v229, 1.0, v229
	v_rcp_f32_e32 v224, v224
	v_rcp_f32_e32 v225, v225
	v_rcp_f32_e32 v228, v228
	v_mfma_f32_16x16x32_bf16 v[24:27], v[146:149], v[208:211], v[24:27]
	v_rcp_f32_e32 v229, v229
	v_nop
	v_mul_f32_e32 v120, v224, v120
	v_mul_f32_e32 v121, v225, v121
	v_mul_f32_e32 v122, v228, v122
	v_mul_f32_e32 v123, v229, v123
	v_mul_f32_e32 v120, v124, v120
	v_mul_f32_e32 v121, v125, v121
	v_mul_f32_e32 v122, v126, v122
	v_mul_f32_e32 v123, v127, v123
	v_mfma_f32_16x16x32_bf16 v[16:19], v[158:161], v[208:211], v[16:19]
	v_mul_f32_e32 v112, v172, v112
	v_mul_f32_e32 v113, v172, v113
	v_mul_f32_e32 v114, v172, v114
	v_mul_f32_e32 v115, v172, v115
	v_mul_f32_e32 v116, v172, v116
	v_mul_f32_e32 v117, v172, v117
	v_mul_f32_e32 v118, v172, v118
	v_mul_f32_e32 v119, v172, v119
	v_mul_f32_e32 v224, s100, v112
	v_mul_f32_e32 v225, s101, v113
	v_mfma_f32_16x16x32_bf16 v[8:11], v[146:149], v[216:219], v[8:11]
	v_mul_f32_e32 v228, s100, v114
	v_mul_f32_e32 v229, s101, v115
	v_exp_f32_e32 v224, v224
	v_exp_f32_e32 v225, v225
	v_exp_f32_e32 v228, v228
	v_exp_f32_e32 v229, v229
	v_add_f32_e32 v224, 1.0, v224
	v_add_f32_e32 v225, 1.0, v225
	v_add_f32_e32 v228, 1.0, v228
	v_add_f32_e32 v229, 1.0, v229
	v_mfma_f32_16x16x32_bf16 v[4:7], v[158:161], v[216:219], v[4:7]
	v_rcp_f32_e32 v224, v224
	v_rcp_f32_e32 v225, v225
	v_rcp_f32_e32 v228, v228
	v_rcp_f32_e32 v229, v229
	v_nop
	v_mul_f32_e32 v112, v224, v112
	v_mul_f32_e32 v113, v225, v113
	v_mul_f32_e32 v114, v228, v114
	v_mul_f32_e32 v115, v229, v115
	v_mul_f32_e32 v112, v116, v112
	v_mfma_f32_16x16x32_bf16 v[56:59], v[154:157], v[196:199], v[56:59]
	v_mul_f32_e32 v113, v117, v113
	v_mul_f32_e32 v114, v118, v114
	v_mul_f32_e32 v115, v119, v115
	v_cvt_pk_bf16_f32 v120, v120, v121
	v_cvt_pk_bf16_f32 v121, v122, v123
	v_cvt_pk_bf16_f32 v122, v112, v113
	v_cvt_pk_bf16_f32 v123, v114, v115
	global_store_dwordx4 v232, v[120:123], s[30:31]
	v_add_u32_e32 v232, s98, v232
	v_mul_f32_e32 v104, v173, v104
	v_mfma_f32_16x16x32_bf16 v[48:51], v[162:165], v[196:199], v[48:51]
	v_mul_f32_e32 v105, v173, v105
	v_mul_f32_e32 v106, v173, v106
	v_mul_f32_e32 v107, v173, v107
	v_mul_f32_e32 v108, v173, v108
	v_mul_f32_e32 v109, v173, v109
	v_mul_f32_e32 v110, v173, v110
	v_mul_f32_e32 v111, v173, v111
	v_mul_f32_e32 v224, s100, v104
	v_mul_f32_e32 v225, s101, v105
	v_mul_f32_e32 v228, s100, v106
	v_mfma_f32_16x16x32_bf16 v[40:43], v[154:157], v[204:207], v[40:43]
	v_mul_f32_e32 v229, s101, v107
	v_exp_f32_e32 v224, v224
	v_exp_f32_e32 v225, v225
	v_exp_f32_e32 v228, v228
	v_exp_f32_e32 v229, v229
	v_add_f32_e32 v224, 1.0, v224
	v_add_f32_e32 v225, 1.0, v225
	v_add_f32_e32 v228, 1.0, v228
	v_add_f32_e32 v229, 1.0, v229
	v_rcp_f32_e32 v224, v224
	v_mfma_f32_16x16x32_bf16 v[32:35], v[162:165], v[204:207], v[32:35]
	v_rcp_f32_e32 v225, v225
	v_rcp_f32_e32 v228, v228
	v_rcp_f32_e32 v229, v229
	v_nop
	v_mul_f32_e32 v104, v224, v104
	v_mul_f32_e32 v105, v225, v105
	v_mul_f32_e32 v106, v228, v106
	v_mul_f32_e32 v107, v229, v107
	v_mul_f32_e32 v104, v108, v104
	v_mul_f32_e32 v105, v109, v105
; __device__ __forceinline__ unsigned cvt_pk_bf16(float lo, float hi) { unsigned r; asm volatile("v_cvt_pk_bf16_f32 %0, %1, %2" : "=v"(r) : "v"(lo), "v"(hi)); return r; }
; __device__ __forceinline__ float siluf_(float x) { return x * sigmoidf_(x); }
; #define PG8_STAGE(bufoff, gbase, voff) do { _Pragma("unroll") for (int _i = 0; _i < 2; ++_i) \
;         __builtin_amdgcn_global_load_lds((const unsigned*)((const char*)(gbase) + (voff)[_i]), (LAS unsigned*)(lds + (bufoff) + ldsw + _i * 8192), 16, 0, 0); } while (0)
; #define PG8_LDA(dst, b, h) do { _Pragma("unroll") for (int m = 0; m < 4; ++m) _Pragma("unroll") for (int k = 0; k < 2; ++k) dst[m][k] = *(const LAS bf16x8*)(lds + PG8_SA(b, h) + aoff + m * 2048 + k * 1024); } while (0)
; #define PG8_WAIT_V(n) asm volatile("s_waitcnt vmcnt(" #n ")" ::: "memory")
; #define PG8_BAR __builtin_amdgcn_s_barrier()
;     __device__ __forceinline__ void operator()(const f32x4 (&acc)[2][2][4][2], const Unit& u, int wr, int wc, int fr, int fq) const {
;         const int row0 = u.pm * BM + wr * 64 + fr, col0 = u.pn * HALF + wc * 32 + 8 * fq;
;         float rsv[2][4]; load_rstd(rsv, ssq, row0);
; #pragma unroll
;         for (int ai = 0; ai < 2; ++ai)
; #pragma unroll
;             for (int m = 0; m < 4; ++m) { const int row = row0 + ai * HALF + m * 16; bf16_t* rowp = O + (size_t)row * ldc + col0; const float rs = rsv[ai][m];
;                 f32x4 v0, v1;
; #pragma unroll
;                 for (int j = 0; j < 4; ++j) { v0[j] = siluf_(acc[ai][0][m][0][j] * rs) * (acc[ai][1][m][0][j] * rs); v1[j] = siluf_(acc[ai][0][m][1][j] * rs) * (acc[ai][1][m][1][j] * rs); }
;                 u32x4 w; w.x = cvt_pk_bf16(v0[0], v0[1]); w.y = cvt_pk_bf16(v0[2], v0[3]); w.z = cvt_pk_bf16(v1[0], v1[1]); w.w = cvt_pk_bf16(v1[2], v1[3]);
;                 *(u32x4*)rowp = w; }
; template <class Epi, bool ALIGN_EPI>
; __device__ __forceinline__ void gemm_phase(LAS unsigned char* lds, const Gemm g, const StaticOrder& S, const Epi& E, const int tid) {
;     ...
;             PG8_WAIT_V(8); PG8_WAIT_L(0); PG8_BAR; PG8_MMA(0, 0, At, B0); PG8_MMA(0, 1, At, B1); PG8_BAR; PG8_SCHED;
;             PG8_LDA(At, 1, 1); PG8_STAGE(PG8_SB(1, 0), b3, voffB); PG8_STAGE(PG8_SB(1, 1), b3 + hB, voffB); PG8_STAGE(PG8_SA(1, 0), a3, voffA);
;             PG8_WAIT_V(8); PG8_WAIT_L(0); PG8_BAR; PG8_MMA(1, 0, At, B0); PG8_MMA(1, 1, At, B1); PG8_BAR; PG8_SCHED;
	v_mfma_f32_16x16x32_bf16 v[24:27], v[154:157], v[212:215], v[24:27]
	v_mul_f32_e32 v106, v110, v106
	v_mul_f32_e32 v107, v111, v107
	v_mul_f32_e32 v96, v173, v96
	v_mul_f32_e32 v97, v173, v97
	v_mul_f32_e32 v98, v173, v98
	v_mul_f32_e32 v99, v173, v99
	v_mul_f32_e32 v100, v173, v100
	v_mul_f32_e32 v101, v173, v101
	v_mul_f32_e32 v102, v173, v102
	v_mul_f32_e32 v103, v173, v103
	v_mfma_f32_16x16x32_bf16 v[16:19], v[162:165], v[212:215], v[16:19]
	v_mul_f32_e32 v224, s100, v96
	v_mul_f32_e32 v225, s101, v97
	v_mul_f32_e32 v228, s100, v98
	v_mul_f32_e32 v229, s101, v99
	v_exp_f32_e32 v224, v224
	v_exp_f32_e32 v225, v225
	v_exp_f32_e32 v228, v228
	v_exp_f32_e32 v229, v229
	v_add_f32_e32 v224, 1.0, v224
	v_add_f32_e32 v225, 1.0, v225
	v_mfma_f32_16x16x32_bf16 v[8:11], v[154:157], v[240:243], v[8:11]
	v_add_f32_e32 v228, 1.0, v228
	v_add_f32_e32 v229, 1.0, v229
	v_rcp_f32_e32 v224, v224
	v_rcp_f32_e32 v225, v225
	v_rcp_f32_e32 v228, v228
	v_rcp_f32_e32 v229, v229
	v_nop
	v_mul_f32_e32 v96, v224, v96
	v_mul_f32_e32 v97, v225, v97
	v_mul_f32_e32 v98, v228, v98
	v_mfma_f32_16x16x32_bf16 v[4:7], v[162:165], v[240:243], v[4:7]
	v_mul_f32_e32 v99, v229, v99
	v_mul_f32_e32 v96, v100, v96
	v_mul_f32_e32 v97, v101, v97
	v_mul_f32_e32 v98, v102, v98
	v_mul_f32_e32 v99, v103, v99
	v_cvt_pk_bf16_f32 v104, v104, v105
	v_cvt_pk_bf16_f32 v105, v106, v107
	v_cvt_pk_bf16_f32 v106, v96, v97
	v_cvt_pk_bf16_f32 v107, v98, v99
	global_store_dwordx4 v232, v[104:107], s[30:31]
	s_setprio 0
	s_setprio 1
	v_mfma_f32_16x16x32_bf16 v[60:63], v[176:179], v[192:195], v[60:63]
	v_add_u32_e32 v232, s98, v232
	v_mul_f32_e32 v88, v236, v88
	v_mul_f32_e32 v89, v236, v89
	v_mul_f32_e32 v90, v236, v90
	v_mul_f32_e32 v91, v236, v91
	v_mul_f32_e32 v92, v236, v92
	v_mul_f32_e32 v93, v236, v93
	v_mul_f32_e32 v94, v236, v94
	v_mul_f32_e32 v95, v236, v95
	v_mul_f32_e32 v224, s100, v88
	v_mfma_f32_16x16x32_bf16 v[52:55], v[184:187], v[192:195], v[52:55]
	v_mul_f32_e32 v225, s101, v89
	v_mul_f32_e32 v228, s100, v90
	v_mul_f32_e32 v229, s101, v91
	v_exp_f32_e32 v224, v224
	v_exp_f32_e32 v225, v225
	v_exp_f32_e32 v228, v228
	v_exp_f32_e32 v229, v229
	v_add_f32_e32 v224, 1.0, v224
	v_add_f32_e32 v225, 1.0, v225
	v_add_f32_e32 v228, 1.0, v228
	v_mfma_f32_16x16x32_bf16 v[44:47], v[176:179], v[200:203], v[44:47]
	v_add_f32_e32 v229, 1.0, v229
	v_rcp_f32_e32 v224, v224
	v_rcp_f32_e32 v225, v225
	v_rcp_f32_e32 v228, v228
	v_rcp_f32_e32 v229, v229
	v_nop
	v_mul_f32_e32 v88, v224, v88
	v_mul_f32_e32 v89, v225, v89
	v_mul_f32_e32 v90, v228, v90
	v_mul_f32_e32 v91, v229, v91
	v_mfma_f32_16x16x32_bf16 v[36:39], v[184:187], v[200:203], v[36:39]
	v_mul_f32_e32 v88, v92, v88
	v_mul_f32_e32 v89, v93, v89
	v_mul_f32_e32 v90, v94, v90
	v_mul_f32_e32 v91, v95, v91
	v_mul_f32_e32 v80, v236, v80
	v_mul_f32_e32 v81, v236, v81
	v_mul_f32_e32 v82, v236, v82
	v_mul_f32_e32 v83, v236, v83
	v_mul_f32_e32 v84, v236, v84
	v_mul_f32_e32 v85, v236, v85
	v_mfma_f32_16x16x32_bf16 v[28:31], v[176:179], v[208:211], v[28:31]
	v_mul_f32_e32 v86, v236, v86
	v_mul_f32_e32 v87, v236, v87
	v_mul_f32_e32 v224, s100, v80
	v_mul_f32_e32 v225, s101, v81
	v_mul_f32_e32 v228, s100, v82
	v_mul_f32_e32 v229, s101, v83
	v_exp_f32_e32 v224, v224
	v_exp_f32_e32 v225, v225
	v_exp_f32_e32 v228, v228
	v_exp_f32_e32 v229, v229
	v_mfma_f32_16x16x32_bf16 v[20:23], v[184:187], v[208:211], v[20:23]
	v_add_f32_e32 v224, 1.0, v224
	v_add_f32_e32 v225, 1.0, v225
	v_add_f32_e32 v228, 1.0, v228
	v_add_f32_e32 v229, 1.0, v229
	v_rcp_f32_e32 v224, v224
	v_rcp_f32_e32 v225, v225
	v_rcp_f32_e32 v228, v228
	v_rcp_f32_e32 v229, v229
	v_nop
	v_mul_f32_e32 v80, v224, v80
	v_mfma_f32_16x16x32_bf16 v[12:15], v[176:179], v[216:219], v[12:15]
	v_mul_f32_e32 v81, v225, v81
	v_mul_f32_e32 v82, v228, v82
	v_mul_f32_e32 v83, v229, v83
	v_mul_f32_e32 v80, v84, v80
	v_mul_f32_e32 v81, v85, v81
	v_mul_f32_e32 v82, v86, v82
	v_mul_f32_e32 v83, v87, v83
	v_cvt_pk_bf16_f32 v88, v88, v89
	v_cvt_pk_bf16_f32 v89, v90, v91
	v_cvt_pk_bf16_f32 v90, v80, v81
	v_mfma_f32_16x16x32_bf16 v[0:3], v[184:187], v[216:219], v[0:3]
	v_cvt_pk_bf16_f32 v91, v82, v83
	global_store_dwordx4 v232, v[88:91], s[30:31]
	v_add_u32_e32 v232, s98, v232
	v_mul_f32_e32 v72, v237, v72
	v_mul_f32_e32 v73, v237, v73
	v_mul_f32_e32 v74, v237, v74
	v_mul_f32_e32 v75, v237, v75
	v_mul_f32_e32 v76, v237, v76
	v_mul_f32_e32 v77, v237, v77
	v_mul_f32_e32 v78, v237, v78
	v_mfma_f32_16x16x32_bf16 v[60:63], v[180:183], v[196:199], v[60:63]
	v_mul_f32_e32 v79, v237, v79
	v_mul_f32_e32 v224, s100, v72
	v_mul_f32_e32 v225, s101, v73
	v_mul_f32_e32 v228, s100, v74
	v_mul_f32_e32 v229, s101, v75
	v_exp_f32_e32 v224, v224
	v_exp_f32_e32 v225, v225
	v_exp_f32_e32 v228, v228
	v_exp_f32_e32 v229, v229
	v_add_f32_e32 v224, 1.0, v224
	v_mfma_f32_16x16x32_bf16 v[52:55], v[188:191], v[196:199], v[52:55]
	v_add_f32_e32 v225, 1.0, v225
	v_add_f32_e32 v228, 1.0, v228
	v_add_f32_e32 v229, 1.0, v229
	v_rcp_f32_e32 v224, v224
	v_rcp_f32_e32 v225, v225
	v_rcp_f32_e32 v228, v228
	v_rcp_f32_e32 v229, v229
	v_nop
	v_mul_f32_e32 v72, v224, v72
	v_mul_f32_e32 v73, v225, v73
	v_mfma_f32_16x16x32_bf16 v[44:47], v[180:183], v[204:207], v[44:47]
	v_mul_f32_e32 v74, v228, v74
	v_mul_f32_e32 v75, v229, v75
	v_mul_f32_e32 v72, v76, v72
	v_mul_f32_e32 v73, v77, v73
	v_mul_f32_e32 v74, v78, v74
	v_mul_f32_e32 v75, v79, v75
	v_mul_f32_e32 v64, v237, v64
	v_mul_f32_e32 v65, v237, v65
	v_mul_f32_e32 v66, v237, v66
	v_mul_f32_e32 v67, v237, v67
	v_mfma_f32_16x16x32_bf16 v[36:39], v[188:191], v[204:207], v[36:39]
	v_mul_f32_e32 v68, v237, v68
	v_mul_f32_e32 v69, v237, v69
	v_mul_f32_e32 v70, v237, v70
	v_mul_f32_e32 v71, v237, v71
	v_mul_f32_e32 v224, s100, v64
	v_mul_f32_e32 v225, s101, v65
	v_mul_f32_e32 v228, s100, v66
	v_mul_f32_e32 v229, s101, v67
	v_exp_f32_e32 v224, v224
	v_exp_f32_e32 v225, v225
	v_mfma_f32_16x16x32_bf16 v[28:31], v[180:183], v[212:215], v[28:31]
	v_exp_f32_e32 v228, v228
	v_exp_f32_e32 v229, v229
	v_add_f32_e32 v224, 1.0, v224
	v_add_f32_e32 v225, 1.0, v225
	v_add_f32_e32 v228, 1.0, v228
	v_add_f32_e32 v229, 1.0, v229
	v_rcp_f32_e32 v224, v224
	v_rcp_f32_e32 v225, v225
	v_rcp_f32_e32 v228, v228
	v_rcp_f32_e32 v229, v229
	v_mfma_f32_16x16x32_bf16 v[20:23], v[188:191], v[212:215], v[20:23]
	v_nop
	v_mul_f32_e32 v64, v224, v64
	v_mul_f32_e32 v65, v225, v65
	v_mul_f32_e32 v66, v228, v66
	v_mul_f32_e32 v67, v229, v67
	v_mul_f32_e32 v64, v68, v64
	v_mul_f32_e32 v65, v69, v65
	v_mul_f32_e32 v66, v70, v66
	v_mul_f32_e32 v67, v71, v67
	v_cvt_pk_bf16_f32 v72, v72, v73
	v_mfma_f32_16x16x32_bf16 v[12:15], v[180:183], v[240:243], v[12:15]
	v_cvt_pk_bf16_f32 v73, v74, v75
	v_cvt_pk_bf16_f32 v74, v64, v65
	v_cvt_pk_bf16_f32 v75, v66, v67
	global_store_dwordx4 v232, v[72:75], s[30:31]
	v_add_u32_e32 v232, s98, v232
	v_add_u32_e32 v232, s98, v232
	v_add_u32_e32 v232, s98, v232
	v_add_u32_e32 v232, s98, v232
	v_add_u32_e32 v232, s98, v232
	v_mfma_f32_16x16x32_bf16 v[0:3], v[188:191], v[240:243], v[0:3]
	s_setprio 0
	s_barrier
; #define PG8_BAR __builtin_amdgcn_s_barrier()
; template <class Epi, bool ALIGN_EPI>
; __device__ __forceinline__ void gemm_phase(LAS unsigned char* lds, const Gemm g, const StaticOrder& S, const Epi& E, const int tid) {
;     ...
;         if (!has_next) break;
; #pragma unroll
;         for (int a = 0; a < 2; ++a)
; #pragma unroll
;             for (int b = 0; b < 2; ++b)
; #pragma unroll
;                 for (int m = 0; m < 4; ++m)
; #pragma unroll
;                     for (int n = 0; n < 2; ++n) acc[a][b][m][n] = (f32x4){0.f, 0.f, 0.f, 0.f};
;         cur = nxt; cA = nA; cB = nB; ++ui;
;         if constexpr (ALIGN_EPI) { if (wr == 1) PG8_BAR; }
	v_lshl_add_u64 v[142:143], v[142:143], 0, s[80:81]
	v_lshl_add_u64 v[144:145], v[144:145], 0, s[80:81]
	s_and_b64 vcc, exec, s[8:9]
	s_cbranch_vccnz .Lgu_notdefer
	s_cmp_lg_u32 s62, s64
	s_cbranch_scc1 .Lgu_notdefer
	s_mov_b32 s101, 1
	s_mov_b32 s63, s61
	s_mov_b32 s64, s62
	v_mov_b64_e32 v[144:145], v[140:141]
	v_mov_b64_e32 v[142:143], v[138:139]
	s_branch .LBB0_300

; __device__ __forceinline__ unsigned cvt_pk_bf16(float lo, float hi) { unsigned r; asm volatile("v_cvt_pk_bf16_f32 %0, %1, %2" : "=v"(r) : "v"(lo), "v"(hi)); return r; }
; __device__ __forceinline__ float siluf_(float x) { return x * sigmoidf_(x); }
;     __device__ __forceinline__ void operator()(const f32x4 (&acc)[2][2][4][2], const Unit& u, int wr, int wc, int fr, int fq) const {
;         const int row0 = u.pm * BM + wr * 64 + fr, col0 = u.pn * HALF + wc * 32 + 8 * fq;
;         float rsv[2][4]; load_rstd(rsv, ssq, row0);
; #pragma unroll
;         for (int ai = 0; ai < 2; ++ai)
; #pragma unroll
;             for (int m = 0; m < 4; ++m) { const int row = row0 + ai * HALF + m * 16; bf16_t* rowp = O + (size_t)row * ldc + col0; const float rs = rsv[ai][m];
;                 f32x4 v0, v1;
; #pragma unroll
;                 for (int j = 0; j < 4; ++j) { v0[j] = siluf_(acc[ai][0][m][0][j] * rs) * (acc[ai][1][m][0][j] * rs); v1[j] = siluf_(acc[ai][0][m][1][j] * rs) * (acc[ai][1][m][1][j] * rs); }
;                 u32x4 w; w.x = cvt_pk_bf16(v0[0], v0[1]); w.y = cvt_pk_bf16(v0[2], v0[3]); w.z = cvt_pk_bf16(v1[0], v1[1]); w.w = cvt_pk_bf16(v1[2], v1[3]);
;                 *(u32x4*)rowp = w; }
.Lgu_nopf:
	s_lshl_b32 s98, s28, 5
	s_mov_b32 s99, 0
	s_mov_b32 s100, 0xbfb8aa3b
	s_mov_b32 s101, 0xbfb8aa3b
	v_pk_mul_f32 v[56:57], v[56:57], v[238:239] op_sel_hi:[1,0]
	v_pk_mul_f32 v[58:59], v[58:59], v[238:239] op_sel_hi:[1,0]
	v_pk_mul_f32 v[60:61], v[60:61], v[238:239] op_sel_hi:[1,0]
	v_pk_mul_f32 v[62:63], v[62:63], v[238:239] op_sel_hi:[1,0]
	v_pk_mul_f32 v[224:225], v[56:57], s[100:101]
	v_pk_mul_f32 v[228:229], v[58:59], s[100:101]
	v_exp_f32_e32 v224, v224
	v_exp_f32_e32 v225, v225
	v_exp_f32_e32 v228, v228
	v_exp_f32_e32 v229, v229
	v_add_f32_e32 v224, 1.0, v224
	v_add_f32_e32 v225, 1.0, v225
	v_add_f32_e32 v228, 1.0, v228
	v_add_f32_e32 v229, 1.0, v229
	v_rcp_f32_e32 v224, v224
	v_rcp_f32_e32 v225, v225
	v_rcp_f32_e32 v228, v228
	v_rcp_f32_e32 v229, v229
	v_nop
	v_pk_mul_f32 v[56:57], v[56:57], v[224:225]
	v_pk_mul_f32 v[58:59], v[58:59], v[228:229]
	v_pk_mul_f32 v[56:57], v[56:57], v[60:61]
	v_pk_mul_f32 v[58:59], v[58:59], v[62:63]
	v_pk_mul_f32 v[48:49], v[48:49], v[238:239] op_sel_hi:[1,0]
	v_pk_mul_f32 v[50:51], v[50:51], v[238:239] op_sel_hi:[1,0]
	v_pk_mul_f32 v[52:53], v[52:53], v[238:239] op_sel_hi:[1,0]
	v_pk_mul_f32 v[54:55], v[54:55], v[238:239] op_sel_hi:[1,0]
	v_pk_mul_f32 v[224:225], v[48:49], s[100:101]
	v_pk_mul_f32 v[228:229], v[50:51], s[100:101]
	v_exp_f32_e32 v224, v224
	v_exp_f32_e32 v225, v225
	v_exp_f32_e32 v228, v228
	v_exp_f32_e32 v229, v229
	v_add_f32_e32 v224, 1.0, v224
	v_add_f32_e32 v225, 1.0, v225
	v_add_f32_e32 v228, 1.0, v228
	v_add_f32_e32 v229, 1.0, v229
	v_rcp_f32_e32 v224, v224
	v_rcp_f32_e32 v225, v225
	v_rcp_f32_e32 v228, v228
	v_rcp_f32_e32 v229, v229
	v_nop
	v_pk_mul_f32 v[48:49], v[48:49], v[224:225]
	v_pk_mul_f32 v[50:51], v[50:51], v[228:229]
	v_pk_mul_f32 v[48:49], v[48:49], v[52:53]
	v_pk_mul_f32 v[50:51], v[50:51], v[54:55]
	v_cvt_pk_bf16_f32 v56, v56, v57
	v_cvt_pk_bf16_f32 v57, v58, v59
	v_cvt_pk_bf16_f32 v58, v48, v49
	v_cvt_pk_bf16_f32 v59, v50, v51
	global_store_dwordx4 v232, v[56:59], s[30:31]
	v_add_u32_e32 v232, s98, v232
	v_pk_mul_f32 v[40:41], v[40:41], v[238:239] op_sel:[0,1]
	v_pk_mul_f32 v[42:43], v[42:43], v[238:239] op_sel:[0,1]
	v_pk_mul_f32 v[44:45], v[44:45], v[238:239] op_sel:[0,1]
	v_pk_mul_f32 v[46:47], v[46:47], v[238:239] op_sel:[0,1]
	v_pk_mul_f32 v[224:225], v[40:41], s[100:101]
	v_pk_mul_f32 v[228:229], v[42:43], s[100:101]
	v_exp_f32_e32 v224, v224
	v_exp_f32_e32 v225, v225
	v_exp_f32_e32 v228, v228
	v_exp_f32_e32 v229, v229
	v_add_f32_e32 v224, 1.0, v224
	v_add_f32_e32 v225, 1.0, v225
	v_add_f32_e32 v228, 1.0, v228
	v_add_f32_e32 v229, 1.0, v229
	v_rcp_f32_e32 v224, v224
	v_rcp_f32_e32 v225, v225
	v_rcp_f32_e32 v228, v228
	v_rcp_f32_e32 v229, v229
	v_nop
	v_pk_mul_f32 v[40:41], v[40:41], v[224:225]
	v_pk_mul_f32 v[42:43], v[42:43], v[228:229]
	v_pk_mul_f32 v[40:41], v[40:41], v[44:45]
	v_pk_mul_f32 v[42:43], v[42:43], v[46:47]
	v_pk_mul_f32 v[32:33], v[32:33], v[238:239] op_sel:[0,1]
	v_pk_mul_f32 v[34:35], v[34:35], v[238:239] op_sel:[0,1]
	v_pk_mul_f32 v[36:37], v[36:37], v[238:239] op_sel:[0,1]
	v_pk_mul_f32 v[38:39], v[38:39], v[238:239] op_sel:[0,1]
	v_pk_mul_f32 v[224:225], v[32:33], s[100:101]
	v_pk_mul_f32 v[228:229], v[34:35], s[100:101]
	v_exp_f32_e32 v224, v224
	v_exp_f32_e32 v225, v225
	v_exp_f32_e32 v228, v228
	v_exp_f32_e32 v229, v229
	v_add_f32_e32 v224, 1.0, v224
	v_add_f32_e32 v225, 1.0, v225
	v_add_f32_e32 v228, 1.0, v228
	v_add_f32_e32 v229, 1.0, v229
	v_rcp_f32_e32 v224, v224
	v_rcp_f32_e32 v225, v225
	v_rcp_f32_e32 v228, v228
	v_rcp_f32_e32 v229, v229
	v_nop
	v_pk_mul_f32 v[32:33], v[32:33], v[224:225]
	v_pk_mul_f32 v[34:35], v[34:35], v[228:229]
	v_pk_mul_f32 v[32:33], v[32:33], v[36:37]
	v_pk_mul_f32 v[34:35], v[34:35], v[38:39]
	v_cvt_pk_bf16_f32 v40, v40, v41
	v_cvt_pk_bf16_f32 v41, v42, v43
	v_cvt_pk_bf16_f32 v42, v32, v33
	v_cvt_pk_bf16_f32 v43, v34, v35
	global_store_dwordx4 v232, v[40:43], s[30:31]
	v_add_u32_e32 v232, s98, v232
; __device__ __forceinline__ unsigned cvt_pk_bf16(float lo, float hi) { unsigned r; asm volatile("v_cvt_pk_bf16_f32 %0, %1, %2" : "=v"(r) : "v"(lo), "v"(hi)); return r; }
; __device__ __forceinline__ float siluf_(float x) { return x * sigmoidf_(x); }
; #define PG8_BAR __builtin_amdgcn_s_barrier()
;     __device__ __forceinline__ void operator()(const f32x4 (&acc)[2][2][4][2], const Unit& u, int wr, int wc, int fr, int fq) const {
;         const int row0 = u.pm * BM + wr * 64 + fr, col0 = u.pn * HALF + wc * 32 + 8 * fq;
;         float rsv[2][4]; load_rstd(rsv, ssq, row0);
; #pragma unroll
;         for (int ai = 0; ai < 2; ++ai)
; #pragma unroll
;             for (int m = 0; m < 4; ++m) { const int row = row0 + ai * HALF + m * 16; bf16_t* rowp = O + (size_t)row * ldc + col0; const float rs = rsv[ai][m];
;                 f32x4 v0, v1;
; #pragma unroll
;                 for (int j = 0; j < 4; ++j) { v0[j] = siluf_(acc[ai][0][m][0][j] * rs) * (acc[ai][1][m][0][j] * rs); v1[j] = siluf_(acc[ai][0][m][1][j] * rs) * (acc[ai][1][m][1][j] * rs); }
;                 u32x4 w; w.x = cvt_pk_bf16(v0[0], v0[1]); w.y = cvt_pk_bf16(v0[2], v0[3]); w.z = cvt_pk_bf16(v1[0], v1[1]); w.w = cvt_pk_bf16(v1[2], v1[3]);
;                 *(u32x4*)rowp = w; }
; template <class Epi, bool ALIGN_EPI>
; __device__ __forceinline__ void gemm_phase(LAS unsigned char* lds, const Gemm g, const StaticOrder& S, const Epi& E, const int tid) {
;     ...
;         if constexpr (ALIGN_EPI) { if (wr == 1) PG8_BAR; }
	v_pk_mul_f32 v[24:25], v[24:25], v[230:231] op_sel_hi:[1,0]
	v_pk_mul_f32 v[26:27], v[26:27], v[230:231] op_sel_hi:[1,0]
	v_pk_mul_f32 v[28:29], v[28:29], v[230:231] op_sel_hi:[1,0]
	v_pk_mul_f32 v[30:31], v[30:31], v[230:231] op_sel_hi:[1,0]
	v_pk_mul_f32 v[224:225], v[24:25], s[100:101]
	v_pk_mul_f32 v[228:229], v[26:27], s[100:101]
	v_exp_f32_e32 v224, v224
	v_exp_f32_e32 v225, v225
	v_exp_f32_e32 v228, v228
	v_exp_f32_e32 v229, v229
	v_add_f32_e32 v224, 1.0, v224
	v_add_f32_e32 v225, 1.0, v225
	v_add_f32_e32 v228, 1.0, v228
	v_add_f32_e32 v229, 1.0, v229
	v_rcp_f32_e32 v224, v224
	v_rcp_f32_e32 v225, v225
	v_rcp_f32_e32 v228, v228
	v_rcp_f32_e32 v229, v229
	v_nop
	v_pk_mul_f32 v[24:25], v[24:25], v[224:225]
	v_pk_mul_f32 v[26:27], v[26:27], v[228:229]
	v_pk_mul_f32 v[24:25], v[24:25], v[28:29]
	v_pk_mul_f32 v[26:27], v[26:27], v[30:31]
	v_pk_mul_f32 v[16:17], v[16:17], v[230:231] op_sel_hi:[1,0]
	v_pk_mul_f32 v[18:19], v[18:19], v[230:231] op_sel_hi:[1,0]
	v_pk_mul_f32 v[20:21], v[20:21], v[230:231] op_sel_hi:[1,0]
	v_pk_mul_f32 v[22:23], v[22:23], v[230:231] op_sel_hi:[1,0]
	v_pk_mul_f32 v[224:225], v[16:17], s[100:101]
	v_pk_mul_f32 v[228:229], v[18:19], s[100:101]
	v_exp_f32_e32 v224, v224
	v_exp_f32_e32 v225, v225
	v_exp_f32_e32 v228, v228
	v_exp_f32_e32 v229, v229
	v_add_f32_e32 v224, 1.0, v224
	v_add_f32_e32 v225, 1.0, v225
	v_add_f32_e32 v228, 1.0, v228
	v_add_f32_e32 v229, 1.0, v229
	v_rcp_f32_e32 v224, v224
	v_rcp_f32_e32 v225, v225
	v_rcp_f32_e32 v228, v228
	v_rcp_f32_e32 v229, v229
	v_nop
	v_pk_mul_f32 v[16:17], v[16:17], v[224:225]
	v_pk_mul_f32 v[18:19], v[18:19], v[228:229]
	v_pk_mul_f32 v[16:17], v[16:17], v[20:21]
	v_pk_mul_f32 v[18:19], v[18:19], v[22:23]
	v_cvt_pk_bf16_f32 v24, v24, v25
	v_cvt_pk_bf16_f32 v25, v26, v27
	v_cvt_pk_bf16_f32 v26, v16, v17
	v_cvt_pk_bf16_f32 v27, v18, v19
	global_store_dwordx4 v232, v[24:27], s[30:31]
	v_add_u32_e32 v232, s98, v232
	v_pk_mul_f32 v[8:9], v[8:9], v[230:231] op_sel:[0,1]
	v_pk_mul_f32 v[10:11], v[10:11], v[230:231] op_sel:[0,1]
	v_pk_mul_f32 v[12:13], v[12:13], v[230:231] op_sel:[0,1]
	v_pk_mul_f32 v[14:15], v[14:15], v[230:231] op_sel:[0,1]
	v_pk_mul_f32 v[224:225], v[8:9], s[100:101]
	v_pk_mul_f32 v[228:229], v[10:11], s[100:101]
	v_exp_f32_e32 v224, v224
	v_exp_f32_e32 v225, v225
	v_exp_f32_e32 v228, v228
	v_exp_f32_e32 v229, v229
	v_add_f32_e32 v224, 1.0, v224
	v_add_f32_e32 v225, 1.0, v225
	v_add_f32_e32 v228, 1.0, v228
	v_add_f32_e32 v229, 1.0, v229
	v_rcp_f32_e32 v224, v224
	v_rcp_f32_e32 v225, v225
	v_rcp_f32_e32 v228, v228
	v_rcp_f32_e32 v229, v229
	v_nop
	v_pk_mul_f32 v[8:9], v[8:9], v[224:225]
	v_pk_mul_f32 v[10:11], v[10:11], v[228:229]
	v_pk_mul_f32 v[8:9], v[8:9], v[12:13]
	v_pk_mul_f32 v[10:11], v[10:11], v[14:15]
	v_pk_mul_f32 v[4:5], v[4:5], v[230:231] op_sel:[0,1]
	v_pk_mul_f32 v[6:7], v[6:7], v[230:231] op_sel:[0,1]
	v_pk_mul_f32 v[0:1], v[0:1], v[230:231] op_sel:[0,1]
	v_pk_mul_f32 v[2:3], v[2:3], v[230:231] op_sel:[0,1]
	v_pk_mul_f32 v[224:225], v[4:5], s[100:101]
	v_pk_mul_f32 v[228:229], v[6:7], s[100:101]
	v_exp_f32_e32 v224, v224
	v_exp_f32_e32 v225, v225
	v_exp_f32_e32 v228, v228
	v_exp_f32_e32 v229, v229
	v_add_f32_e32 v224, 1.0, v224
	v_add_f32_e32 v225, 1.0, v225
	v_add_f32_e32 v228, 1.0, v228
	v_add_f32_e32 v229, 1.0, v229
	v_rcp_f32_e32 v224, v224
	v_rcp_f32_e32 v225, v225
	v_rcp_f32_e32 v228, v228
	v_rcp_f32_e32 v229, v229
	v_nop
	v_pk_mul_f32 v[4:5], v[4:5], v[224:225]
	v_pk_mul_f32 v[6:7], v[6:7], v[228:229]
	v_pk_mul_f32 v[4:5], v[4:5], v[0:1]
	v_pk_mul_f32 v[6:7], v[6:7], v[2:3]
	v_cvt_pk_bf16_f32 v8, v8, v9
	v_cvt_pk_bf16_f32 v9, v10, v11
	v_cvt_pk_bf16_f32 v10, v4, v5
	v_cvt_pk_bf16_f32 v11, v6, v7
	global_store_dwordx4 v232, v[8:11], s[30:31]
	s_mov_b32 s101, 0
	s_mov_b64 s[10:11], -1
	s_and_b64 vcc, exec, s[8:9]
	s_cbranch_vccnz .LBB0_299
	s_andn2_b64 vcc, exec, s[40:41]
	s_cbranch_vccnz .LBB0_298
	s_barrier
	s_branch .LBB0_298

; __device__ __forceinline__ unsigned cvt_pk_bf16(float lo, float hi) { unsigned r; asm volatile("v_cvt_pk_bf16_f32 %0, %1, %2" : "=v"(r) : "v"(lo), "v"(hi)); return r; }
; __device__ __forceinline__ float gelu_tanh(float x) { const float u = 0.7978845608028654f * (x + 0.044715f * x * x * x); return x * fast_rcp(1.0f + fast_exp2(-2.0f * LOG2E * u)); }
; #define PG8_STAGE(bufoff, gbase, voff) do { _Pragma("unroll") for (int _i = 0; _i < 2; ++_i) \
;         __builtin_amdgcn_global_load_lds((const unsigned*)((const char*)(gbase) + (voff)[_i]), (LAS unsigned*)(lds + (bufoff) + ldsw + _i * 8192), 16, 0, 0); } while (0)
; #define PG8_BAR __builtin_amdgcn_s_barrier()
;     __device__ __forceinline__ void operator()(const f32x4 (&acc)[2][2][4][2], const Unit& u, int wr, int wc, int fr, int fq) const {
;         const int row0 = u.pm * BM + wr * 64 + fr, col0 = u.pn * BM + wc * 32 + 8 * fq;
;         float rsv[2][4]; load_rstd(rsv, ssq, row0);
; #pragma unroll
;         for (int ai = 0; ai < 2; ++ai)
; #pragma unroll
;             for (int m = 0; m < 4; ++m) { const int row = row0 + ai * HALF + m * 16; bf16_t* rowp = O + (size_t)row * ldc + col0; const float rs = rsv[ai][m];
; #pragma unroll
;                 for (int bj = 0; bj < 2; ++bj) { f32x4 v0 = acc[ai][bj][m][0] * rs, v1 = acc[ai][bj][m][1] * rs;
;                     if (ACT == 1) {
; #pragma unroll
;                         for (int j = 0; j < 4; ++j) { v0[j] = gelu_tanh(v0[j]); v1[j] = gelu_tanh(v1[j]); } }
;                     u32x4 w; w.x = cvt_pk_bf16(v0[0], v0[1]); w.y = cvt_pk_bf16(v0[2], v0[3]); w.z = cvt_pk_bf16(v1[0], v1[1]); w.w = cvt_pk_bf16(v1[2], v1[3]);
;                     *(u32x4*)(rowp + bj * HALF) = w; } }
; template <class Epi, bool ALIGN_EPI>
; __device__ __forceinline__ void gemm_phase(LAS unsigned char* lds, const Gemm g, const StaticOrder& S, const Epi& E, const int tid) {
;     ...
;             PG8_LDB(B0, 0, 0); PG8_LDB(B1, 0, 1); PG8_SCHED; PG8_LDA(At, 0, 0); PG8_STAGE(PG8_SA(1, 1), a1 + hA, voffA);
;             PG8_WAIT_V(8); PG8_WAIT_L(0); PG8_BAR; PG8_MMA(0, 0, At, B0); PG8_MMA(0, 1, At, B1); PG8_BAR; PG8_SCHED;
;             PG8_LDA(At, 0, 1); PG8_STAGE(PG8_SB(0, 0), b2, voffB); PG8_STAGE(PG8_SB(0, 1), b2 + hB, voffB); PG8_STAGE(PG8_SA(0, 0), a2, voffA);
;             PG8_WAIT_V(8); PG8_WAIT_L(0); PG8_BAR; PG8_MMA(1, 0, At, B0); PG8_MMA(1, 1, At, B1); PG8_BAR; PG8_SCHED;
.Lq5_first_epi:
	s_add_i32 s11, s10, 2
	s_cmp_eq_u32 s55, s10
	s_cselect_b64 vcc, -1, 0
	v_add_u32_e32 v148, s33, v149
	s_add_i32 s10, 0, 0x14000
	ds_read_b128 v[152:155], v148
	ds_read_b128 v[156:159], v148 offset:1024
	ds_read_b128 v[160:163], v148 offset:2048
	ds_read_b128 v[164:167], v148 offset:3072
	v_add_u32_e32 v148, s10, v149
	ds_read_b128 v[176:179], v148
	ds_read_b128 v[180:183], v148 offset:1024
	ds_read_b128 v[184:187], v148 offset:2048
	ds_read_b128 v[188:191], v148 offset:3072
	v_lshl_add_u64 v[146:147], v[142:143], 0, s[92:93]
	v_cndmask_b32_e32 v147, v147, v139, vcc
	v_cndmask_b32_e32 v146, v146, v138, vcc
	v_cndmask_b32_e32 v221, v145, v141, vcc
	v_cndmask_b32_e32 v220, v144, v140, vcc
	v_lshl_add_u64 v[244:245], v[142:143], 0, v[134:135]
	s_add_i32 m0, s25, 0xc000
	ds_read_b128 v[192:195], v151
	ds_read_b128 v[196:199], v151 offset:1024
	ds_read_b128 v[200:203], v151 offset:2048
	ds_read_b128 v[204:207], v151 offset:3072
	ds_read_b128 v[208:211], v151 offset:4096
	ds_read_b128 v[212:215], v151 offset:5120
	ds_read_b128 v[216:219], v151 offset:6144
	ds_read_b128 v[240:243], v151 offset:7168
	global_load_lds_dwordx4 v[244:245], off
	v_lshl_add_u64 v[244:245], v[142:143], 0, v[136:137]
	s_add_i32 m0, s25, 0xe000
	s_nop 0
	global_load_lds_dwordx4 v[244:245], off
	s_waitcnt vmcnt(16)
	s_waitcnt lgkmcnt(0)
	s_barrier
	s_setprio 1
	s_waitcnt lgkmcnt(0)
	v_mfma_f32_16x16x32_bf16 v[124:127], v[152:155], v[192:195], 0
	s_lshl_b32 s98, s28, 5
	s_mov_b32 s99, 0
	v_mul_f32_e32 v60, v238, v60
	v_mul_f32_e32 v61, v238, v61
	v_mfma_f32_16x16x32_bf16 v[120:123], v[160:163], v[192:195], 0
	v_mul_f32_e32 v62, v238, v62
	v_mul_f32_e32 v63, v238, v63
	v_mul_f32_e32 v56, v238, v56
	v_mul_f32_e32 v57, v238, v57
	v_mfma_f32_16x16x32_bf16 v[108:111], v[152:155], v[200:203], 0
	v_mul_f32_e32 v58, v238, v58
	v_mul_f32_e32 v59, v238, v59
	v_cvt_pk_bf16_f32 v60, v60, v61
	v_cvt_pk_bf16_f32 v61, v62, v63
	v_mfma_f32_16x16x32_bf16 v[104:107], v[160:163], v[200:203], 0
	v_cvt_pk_bf16_f32 v62, v56, v57
	v_cvt_pk_bf16_f32 v63, v58, v59
	global_store_dwordx4 v232, v[60:63], s[30:31]
	v_mul_f32_e32 v52, v238, v52
	v_mfma_f32_16x16x32_bf16 v[92:95], v[152:155], v[208:211], 0
	v_mul_f32_e32 v53, v238, v53
	v_mul_f32_e32 v54, v238, v54
	v_mul_f32_e32 v55, v238, v55
	v_mul_f32_e32 v48, v238, v48
	v_mfma_f32_16x16x32_bf16 v[88:91], v[160:163], v[208:211], 0
	v_mul_f32_e32 v49, v238, v49
	v_mul_f32_e32 v50, v238, v50
	v_mul_f32_e32 v51, v238, v51
	v_cvt_pk_bf16_f32 v52, v52, v53
	v_mfma_f32_16x16x32_bf16 v[76:79], v[152:155], v[216:219], 0
	v_cvt_pk_bf16_f32 v53, v54, v55
	v_cvt_pk_bf16_f32 v54, v48, v49
	v_cvt_pk_bf16_f32 v55, v50, v51
	global_store_dwordx4 v232, v[52:55], s[30:31] offset:256
	v_mfma_f32_16x16x32_bf16 v[72:75], v[160:163], v[216:219], 0
	v_add_u32_e32 v232, s98, v232
	v_mul_f32_e32 v44, v239, v44
	v_mul_f32_e32 v45, v239, v45
	v_mul_f32_e32 v46, v239, v46
	v_mfma_f32_16x16x32_bf16 v[124:127], v[156:159], v[196:199], v[124:127]
	v_mul_f32_e32 v47, v239, v47
	v_mul_f32_e32 v40, v239, v40
	v_mul_f32_e32 v41, v239, v41
	v_mul_f32_e32 v42, v239, v42
	v_mfma_f32_16x16x32_bf16 v[120:123], v[164:167], v[196:199], v[120:123]
	v_mul_f32_e32 v43, v239, v43
	v_cvt_pk_bf16_f32 v44, v44, v45
	v_cvt_pk_bf16_f32 v45, v46, v47
	v_cvt_pk_bf16_f32 v46, v40, v41
	v_mfma_f32_16x16x32_bf16 v[108:111], v[156:159], v[204:207], v[108:111]
	v_cvt_pk_bf16_f32 v47, v42, v43
	global_store_dwordx4 v232, v[44:47], s[30:31]
	v_mul_f32_e32 v36, v239, v36
	v_mul_f32_e32 v37, v239, v37
	v_mfma_f32_16x16x32_bf16 v[104:107], v[164:167], v[204:207], v[104:107]
	v_mul_f32_e32 v38, v239, v38
	v_mul_f32_e32 v39, v239, v39
	v_mul_f32_e32 v32, v239, v32
	v_mul_f32_e32 v33, v239, v33
	v_mfma_f32_16x16x32_bf16 v[92:95], v[156:159], v[212:215], v[92:95]
	v_mul_f32_e32 v34, v239, v34
	v_mul_f32_e32 v35, v239, v35
	v_cvt_pk_bf16_f32 v36, v36, v37
	v_cvt_pk_bf16_f32 v37, v38, v39
	v_mfma_f32_16x16x32_bf16 v[88:91], v[164:167], v[212:215], v[88:91]
	v_cvt_pk_bf16_f32 v38, v32, v33
	v_cvt_pk_bf16_f32 v39, v34, v35
	global_store_dwordx4 v232, v[36:39], s[30:31] offset:256
	v_add_u32_e32 v232, s98, v232
	v_mfma_f32_16x16x32_bf16 v[76:79], v[156:159], v[240:243], v[76:79]
	v_mul_f32_e32 v28, v230, v28
	v_mul_f32_e32 v29, v230, v29
	v_mul_f32_e32 v30, v230, v30
	v_mul_f32_e32 v31, v230, v31
	v_mfma_f32_16x16x32_bf16 v[72:75], v[164:167], v[240:243], v[72:75]
	v_mul_f32_e32 v24, v230, v24
	v_mul_f32_e32 v25, v230, v25
	v_mul_f32_e32 v26, v230, v26
	v_mul_f32_e32 v27, v230, v27
	s_setprio 0
	s_setprio 1
	v_mfma_f32_16x16x32_bf16 v[116:119], v[176:179], v[192:195], 0
	v_cvt_pk_bf16_f32 v28, v28, v29
	v_cvt_pk_bf16_f32 v29, v30, v31
	v_cvt_pk_bf16_f32 v30, v24, v25
	v_cvt_pk_bf16_f32 v31, v26, v27
	v_mfma_f32_16x16x32_bf16 v[112:115], v[184:187], v[192:195], 0
	global_store_dwordx4 v232, v[28:31], s[30:31]
	v_mul_f32_e32 v20, v230, v20
	v_mul_f32_e32 v21, v230, v21
	v_mul_f32_e32 v22, v230, v22
	v_mfma_f32_16x16x32_bf16 v[100:103], v[176:179], v[200:203], 0
	v_mul_f32_e32 v23, v230, v23
	v_mul_f32_e32 v16, v230, v16
	v_mul_f32_e32 v17, v230, v17
	v_mul_f32_e32 v18, v230, v18
	v_mfma_f32_16x16x32_bf16 v[96:99], v[184:187], v[200:203], 0
	v_mul_f32_e32 v19, v230, v19
	v_cvt_pk_bf16_f32 v20, v20, v21
	v_cvt_pk_bf16_f32 v21, v22, v23
	v_cvt_pk_bf16_f32 v22, v16, v17
	v_mfma_f32_16x16x32_bf16 v[84:87], v[176:179], v[208:211], 0
	v_cvt_pk_bf16_f32 v23, v18, v19
	global_store_dwordx4 v232, v[20:23], s[30:31] offset:256
	v_add_u32_e32 v232, s98, v232
	v_mul_f32_e32 v12, v231, v12
	v_mfma_f32_16x16x32_bf16 v[80:83], v[184:187], v[208:211], 0
	v_mul_f32_e32 v13, v231, v13
	v_mul_f32_e32 v14, v231, v14
; __device__ __forceinline__ unsigned cvt_pk_bf16(float lo, float hi) { unsigned r; asm volatile("v_cvt_pk_bf16_f32 %0, %1, %2" : "=v"(r) : "v"(lo), "v"(hi)); return r; }
; __device__ __forceinline__ float gelu_tanh(float x) { const float u = 0.7978845608028654f * (x + 0.044715f * x * x * x); return x * fast_rcp(1.0f + fast_exp2(-2.0f * LOG2E * u)); }
; #define PG8_STAGE(bufoff, gbase, voff) do { _Pragma("unroll") for (int _i = 0; _i < 2; ++_i) \
;         __builtin_amdgcn_global_load_lds((const unsigned*)((const char*)(gbase) + (voff)[_i]), (LAS unsigned*)(lds + (bufoff) + ldsw + _i * 8192), 16, 0, 0); } while (0)
; #define PG8_LDA(dst, b, h) do { _Pragma("unroll") for (int m = 0; m < 4; ++m) _Pragma("unroll") for (int k = 0; k < 2; ++k) dst[m][k] = *(const LAS bf16x8*)(lds + PG8_SA(b, h) + aoff + m * 2048 + k * 1024); } while (0)
; #define PG8_BAR __builtin_amdgcn_s_barrier()
;     __device__ __forceinline__ void operator()(const f32x4 (&acc)[2][2][4][2], const Unit& u, int wr, int wc, int fr, int fq) const {
;     ...
;             for (int m = 0; m < 4; ++m) { const int row = row0 + ai * HALF + m * 16; bf16_t* rowp = O + (size_t)row * ldc + col0; const float rs = rsv[ai][m];
; #pragma unroll
;                 for (int bj = 0; bj < 2; ++bj) { f32x4 v0 = acc[ai][bj][m][0] * rs, v1 = acc[ai][bj][m][1] * rs;
;                     if (ACT == 1) {
; #pragma unroll
;                         for (int j = 0; j < 4; ++j) { v0[j] = gelu_tanh(v0[j]); v1[j] = gelu_tanh(v1[j]); } }
;                     u32x4 w; w.x = cvt_pk_bf16(v0[0], v0[1]); w.y = cvt_pk_bf16(v0[2], v0[3]); w.z = cvt_pk_bf16(v1[0], v1[1]); w.w = cvt_pk_bf16(v1[2], v1[3]);
;                     *(u32x4*)(rowp + bj * HALF) = w; } }
; template <class Epi, bool ALIGN_EPI>
; __device__ __forceinline__ void gemm_phase(LAS unsigned char* lds, const Gemm g, const StaticOrder& S, const Epi& E, const int tid) {
;     ...
;             PG8_LDA(At, 0, 1); PG8_STAGE(PG8_SB(0, 0), b2, voffB); PG8_STAGE(PG8_SB(0, 1), b2 + hB, voffB); PG8_STAGE(PG8_SA(0, 0), a2, voffA);
;             PG8_WAIT_V(8); PG8_WAIT_L(0); PG8_BAR; PG8_MMA(1, 0, At, B0); PG8_MMA(1, 1, At, B1); PG8_BAR; PG8_SCHED;
;             PG8_LDB(B0, 1, 0); PG8_LDB(B1, 1, 1); PG8_SCHED; PG8_LDA(At, 1, 0); PG8_STAGE(PG8_SA(0, 1), a2 + hA, voffA);
;             PG8_WAIT_V(8); PG8_WAIT_L(0); PG8_BAR; PG8_MMA(0, 0, At, B0); PG8_MMA(0, 1, At, B1); PG8_BAR; PG8_SCHED;
	v_mul_f32_e32 v15, v231, v15
	v_mul_f32_e32 v8, v231, v8
	v_mfma_f32_16x16x32_bf16 v[68:71], v[176:179], v[216:219], 0
	v_mul_f32_e32 v9, v231, v9
	v_mul_f32_e32 v10, v231, v10
	v_mul_f32_e32 v11, v231, v11
	v_cvt_pk_bf16_f32 v12, v12, v13
	v_mfma_f32_16x16x32_bf16 v[64:67], v[184:187], v[216:219], 0
	v_cvt_pk_bf16_f32 v13, v14, v15
	v_cvt_pk_bf16_f32 v14, v8, v9
	v_cvt_pk_bf16_f32 v15, v10, v11
	global_store_dwordx4 v232, v[12:15], s[30:31]
	v_mfma_f32_16x16x32_bf16 v[116:119], v[180:183], v[196:199], v[116:119]
	v_mul_f32_e32 v4, v231, v4
	v_mul_f32_e32 v5, v231, v5
	v_mul_f32_e32 v6, v231, v6
	v_mul_f32_e32 v7, v231, v7
	v_mfma_f32_16x16x32_bf16 v[112:115], v[188:191], v[196:199], v[112:115]
	v_mul_f32_e32 v0, v231, v0
	v_mul_f32_e32 v1, v231, v1
	v_mul_f32_e32 v2, v231, v2
	v_mul_f32_e32 v3, v231, v3
	v_mfma_f32_16x16x32_bf16 v[100:103], v[180:183], v[204:207], v[100:103]
	v_cvt_pk_bf16_f32 v4, v4, v5
	v_cvt_pk_bf16_f32 v5, v6, v7
	v_cvt_pk_bf16_f32 v6, v0, v1
	v_cvt_pk_bf16_f32 v7, v2, v3
	v_mfma_f32_16x16x32_bf16 v[96:99], v[188:191], v[204:207], v[96:99]
	global_store_dwordx4 v232, v[4:7], s[30:31] offset:256
	v_mfma_f32_16x16x32_bf16 v[84:87], v[180:183], v[212:215], v[84:87]
	v_mfma_f32_16x16x32_bf16 v[80:83], v[188:191], v[212:215], v[80:83]
	v_mfma_f32_16x16x32_bf16 v[68:71], v[180:183], v[240:243], v[68:71]
	v_mfma_f32_16x16x32_bf16 v[64:67], v[188:191], v[240:243], v[64:67]
	s_setprio 0
	s_barrier
	s_add_i32 s62, s33, s45
	v_lshl_add_u64 v[244:245], v[220:221], 0, v[168:169]
	s_mov_b32 m0, s62
	ds_read_b128 v[192:195], v151 offset:16384
	ds_read_b128 v[196:199], v151 offset:17408
	ds_read_b128 v[200:203], v151 offset:18432
	ds_read_b128 v[204:207], v151 offset:19456
	ds_read_b128 v[208:211], v151 offset:20480
	ds_read_b128 v[212:215], v151 offset:21504
	ds_read_b128 v[216:219], v151 offset:22528
	ds_read_b128 v[240:243], v151 offset:23552
	global_load_lds_dwordx4 v[244:245], off
	v_lshl_add_u64 v[246:247], v[220:221], 0, v[128:129]
	s_add_i32 m0, s62, 0x2000
	v_lshl_add_u64 v[220:221], v[220:221], 0, s[12:13]
	s_add_i32 s10, s10, s45
	global_load_lds_dwordx4 v[246:247], off
	v_lshl_add_u64 v[248:249], v[220:221], 0, v[168:169]
	s_mov_b32 m0, s10
	v_lshl_add_u64 v[220:221], v[220:221], 0, v[128:129]
	global_load_lds_dwordx4 v[248:249], off
	s_add_i32 m0, s10, 0x2000
	v_lshl_add_u64 v[250:251], v[146:147], 0, v[132:133]
	global_load_lds_dwordx4 v[220:221], off
	s_mov_b32 m0, s25
	v_lshl_add_u64 v[252:253], v[146:147], 0, v[130:131]
	global_load_lds_dwordx4 v[250:251], off
	s_mov_b32 m0, s50
	s_nop 0
	global_load_lds_dwordx4 v[252:253], off
	s_waitcnt vmcnt(24)
	s_waitcnt lgkmcnt(0)
	s_barrier
	s_setprio 1
	s_waitcnt lgkmcnt(0)
	v_mfma_f32_16x16x32_bf16 v[60:63], v[152:155], v[192:195], 0
	v_mfma_f32_16x16x32_bf16 v[56:59], v[160:163], v[192:195], 0
	v_mfma_f32_16x16x32_bf16 v[44:47], v[152:155], v[200:203], 0
	v_mfma_f32_16x16x32_bf16 v[40:43], v[160:163], v[200:203], 0
	v_mfma_f32_16x16x32_bf16 v[28:31], v[152:155], v[208:211], 0
	v_mfma_f32_16x16x32_bf16 v[24:27], v[160:163], v[208:211], 0
	v_mfma_f32_16x16x32_bf16 v[12:15], v[152:155], v[216:219], 0
	v_mfma_f32_16x16x32_bf16 v[8:11], v[160:163], v[216:219], 0
	v_mfma_f32_16x16x32_bf16 v[60:63], v[156:159], v[196:199], v[60:63]
	v_mfma_f32_16x16x32_bf16 v[56:59], v[164:167], v[196:199], v[56:59]
	v_mfma_f32_16x16x32_bf16 v[44:47], v[156:159], v[204:207], v[44:47]
	v_mfma_f32_16x16x32_bf16 v[40:43], v[164:167], v[204:207], v[40:43]
	v_mfma_f32_16x16x32_bf16 v[28:31], v[156:159], v[212:215], v[28:31]
	v_mfma_f32_16x16x32_bf16 v[24:27], v[164:167], v[212:215], v[24:27]
	v_mfma_f32_16x16x32_bf16 v[12:15], v[156:159], v[240:243], v[12:15]
	v_mfma_f32_16x16x32_bf16 v[8:11], v[164:167], v[240:243], v[8:11]
	s_setprio 0
	s_setprio 1
	v_mfma_f32_16x16x32_bf16 v[52:55], v[176:179], v[192:195], 0
	v_mfma_f32_16x16x32_bf16 v[48:51], v[184:187], v[192:195], 0
	v_mfma_f32_16x16x32_bf16 v[36:39], v[176:179], v[200:203], 0
	v_mfma_f32_16x16x32_bf16 v[32:35], v[184:187], v[200:203], 0
	v_mfma_f32_16x16x32_bf16 v[20:23], v[176:179], v[208:211], 0
	v_mfma_f32_16x16x32_bf16 v[16:19], v[184:187], v[208:211], 0
	v_mfma_f32_16x16x32_bf16 v[4:7], v[176:179], v[216:219], 0
	v_mfma_f32_16x16x32_bf16 v[0:3], v[184:187], v[216:219], 0
	v_mfma_f32_16x16x32_bf16 v[52:55], v[180:183], v[196:199], v[52:55]
	v_mfma_f32_16x16x32_bf16 v[48:51], v[188:191], v[196:199], v[48:51]
	v_mfma_f32_16x16x32_bf16 v[36:39], v[180:183], v[204:207], v[36:39]
	v_mfma_f32_16x16x32_bf16 v[32:35], v[188:191], v[204:207], v[32:35]
	v_mfma_f32_16x16x32_bf16 v[20:23], v[180:183], v[212:215], v[20:23]
	v_mfma_f32_16x16x32_bf16 v[16:19], v[188:191], v[212:215], v[16:19]
	v_mfma_f32_16x16x32_bf16 v[4:7], v[180:183], v[240:243], v[4:7]
	v_mfma_f32_16x16x32_bf16 v[0:3], v[188:191], v[240:243], v[0:3]
	s_setprio 0
	s_barrier
	s_add_i32 s10, 0, 0x18000
	v_add_u32_e32 v148, s10, v149
	s_add_i32 s62, 0, 0x1c000
	ds_read_b128 v[152:155], v148
	ds_read_b128 v[156:159], v148 offset:1024
	ds_read_b128 v[160:163], v148 offset:2048
	ds_read_b128 v[164:167], v148 offset:3072
	v_add_u32_e32 v148, s62, v149
	ds_read_b128 v[176:179], v148
	ds_read_b128 v[180:183], v148 offset:1024
	ds_read_b128 v[184:187], v148 offset:2048
	ds_read_b128 v[188:191], v148 offset:3072
	v_lshl_add_u64 v[146:147], v[146:147], 0, s[94:95]
	s_mov_b32 m0, s51
	v_lshl_add_u64 v[226:227], v[146:147], 0, v[132:133]
	ds_read_b128 v[192:195], v151 offset:32768
	ds_read_b128 v[196:199], v151 offset:33792
	ds_read_b128 v[200:203], v151 offset:34816
	ds_read_b128 v[204:207], v151 offset:35840
	ds_read_b128 v[208:211], v151 offset:36864
	ds_read_b128 v[212:215], v151 offset:37888
	ds_read_b128 v[216:219], v151 offset:38912
	ds_read_b128 v[240:243], v151 offset:39936
	global_load_lds_dwordx4 v[226:227], off
	v_lshl_add_u64 v[146:147], v[146:147], 0, v[130:131]
	s_mov_b32 m0, s52
	s_nop 0
	global_load_lds_dwordx4 v[146:147], off
	s_waitcnt vmcnt(16)
	s_waitcnt lgkmcnt(0)
	s_barrier
; #define PG8_STAGE(bufoff, gbase, voff) do { _Pragma("unroll") for (int _i = 0; _i < 2; ++_i) \
;         __builtin_amdgcn_global_load_lds((const unsigned*)((const char*)(gbase) + (voff)[_i]), (LAS unsigned*)(lds + (bufoff) + ldsw + _i * 8192), 16, 0, 0); } while (0)
; #define PG8_LDA(dst, b, h) do { _Pragma("unroll") for (int m = 0; m < 4; ++m) _Pragma("unroll") for (int k = 0; k < 2; ++k) dst[m][k] = *(const LAS bf16x8*)(lds + PG8_SA(b, h) + aoff + m * 2048 + k * 1024); } while (0)
; #define PG8_LDB(dst, b, h) do { _Pragma("unroll") for (int n = 0; n < 2; ++n) _Pragma("unroll") for (int k = 0; k < 2; ++k) dst[n][k] = *(const LAS bf16x8*)(lds + PG8_SB(b, h) + boff + n * 2048 + k * 1024); } while (0)
; #define PG8_MMA(ai, bj, At, Bt) do { __builtin_amdgcn_s_setprio(1); _Pragma("unroll") for (int k = 0; k < 2; ++k) _Pragma("unroll") for (int m = 0; m < 4; ++m) _Pragma("unroll") for (int n = 0; n < 2; ++n) \
;         acc[ai][bj][m][n] = __builtin_amdgcn_mfma_f32_16x16x32_bf16(Bt[n][k], At[m][k], acc[ai][bj][m][n], 0, 0, 0); __builtin_amdgcn_s_setprio(0); } while (0)
; #define PG8_WAIT_V(n) asm volatile("s_waitcnt vmcnt(" #n ")" ::: "memory")
; #define PG8_WAIT_L(n) asm volatile("s_waitcnt lgkmcnt(" #n ")" ::: "memory")
; #define PG8_BAR __builtin_amdgcn_s_barrier()
; #define PG8_SCHED __builtin_amdgcn_sched_barrier(0)
; template <class Epi, bool ALIGN_EPI>
; __device__ __forceinline__ void gemm_phase(LAS unsigned char* lds, const Gemm g, const StaticOrder& S, const Epi& E, const int tid) {
;     ...
;             PG8_LDB(B0, 1, 0); PG8_LDB(B1, 1, 1); PG8_SCHED; PG8_LDA(At, 1, 0); PG8_STAGE(PG8_SA(0, 1), a2 + hA, voffA);
;             PG8_WAIT_V(8); PG8_WAIT_L(0); PG8_BAR; PG8_MMA(0, 0, At, B0); PG8_MMA(0, 1, At, B1); PG8_BAR; PG8_SCHED;
;             PG8_LDA(At, 1, 1); PG8_STAGE(PG8_SB(1, 0), b3, voffB); PG8_STAGE(PG8_SB(1, 1), b3 + hB, voffB); PG8_STAGE(PG8_SA(1, 0), a3, voffA);
;             PG8_WAIT_V(8); PG8_WAIT_L(0); PG8_BAR; PG8_MMA(1, 0, At, B0); PG8_MMA(1, 1, At, B1); PG8_BAR; PG8_SCHED;
	s_setprio 1
	s_waitcnt lgkmcnt(0)
	v_mfma_f32_16x16x32_bf16 v[124:127], v[152:155], v[192:195], v[124:127]
	v_mfma_f32_16x16x32_bf16 v[120:123], v[160:163], v[192:195], v[120:123]
	v_mfma_f32_16x16x32_bf16 v[108:111], v[152:155], v[200:203], v[108:111]
	v_mfma_f32_16x16x32_bf16 v[104:107], v[160:163], v[200:203], v[104:107]
	v_mfma_f32_16x16x32_bf16 v[92:95], v[152:155], v[208:211], v[92:95]
	v_mfma_f32_16x16x32_bf16 v[88:91], v[160:163], v[208:211], v[88:91]
	v_mfma_f32_16x16x32_bf16 v[76:79], v[152:155], v[216:219], v[76:79]
	v_mfma_f32_16x16x32_bf16 v[72:75], v[160:163], v[216:219], v[72:75]
	v_mfma_f32_16x16x32_bf16 v[124:127], v[156:159], v[196:199], v[124:127]
	v_mfma_f32_16x16x32_bf16 v[120:123], v[164:167], v[196:199], v[120:123]
	v_mfma_f32_16x16x32_bf16 v[108:111], v[156:159], v[204:207], v[108:111]
	v_mfma_f32_16x16x32_bf16 v[104:107], v[164:167], v[204:207], v[104:107]
	v_mfma_f32_16x16x32_bf16 v[92:95], v[156:159], v[212:215], v[92:95]
	v_mfma_f32_16x16x32_bf16 v[88:91], v[164:167], v[212:215], v[88:91]
	v_mfma_f32_16x16x32_bf16 v[76:79], v[156:159], v[240:243], v[76:79]
	v_mfma_f32_16x16x32_bf16 v[72:75], v[164:167], v[240:243], v[72:75]
	s_setprio 0
	s_setprio 1
	v_mfma_f32_16x16x32_bf16 v[116:119], v[176:179], v[192:195], v[116:119]
	v_mfma_f32_16x16x32_bf16 v[112:115], v[184:187], v[192:195], v[112:115]
	v_mfma_f32_16x16x32_bf16 v[100:103], v[176:179], v[200:203], v[100:103]
	v_mfma_f32_16x16x32_bf16 v[96:99], v[184:187], v[200:203], v[96:99]
	v_mfma_f32_16x16x32_bf16 v[84:87], v[176:179], v[208:211], v[84:87]
	v_mfma_f32_16x16x32_bf16 v[80:83], v[184:187], v[208:211], v[80:83]
	v_mfma_f32_16x16x32_bf16 v[68:71], v[176:179], v[216:219], v[68:71]
	v_mfma_f32_16x16x32_bf16 v[64:67], v[184:187], v[216:219], v[64:67]
	v_mfma_f32_16x16x32_bf16 v[116:119], v[180:183], v[196:199], v[116:119]
	v_mfma_f32_16x16x32_bf16 v[112:115], v[188:191], v[196:199], v[112:115]
	v_mfma_f32_16x16x32_bf16 v[100:103], v[180:183], v[204:207], v[100:103]
	v_mfma_f32_16x16x32_bf16 v[96:99], v[188:191], v[204:207], v[96:99]
	v_mfma_f32_16x16x32_bf16 v[84:87], v[180:183], v[212:215], v[84:87]
	v_mfma_f32_16x16x32_bf16 v[80:83], v[188:191], v[212:215], v[80:83]
	v_mfma_f32_16x16x32_bf16 v[68:71], v[180:183], v[240:243], v[68:71]
	v_mfma_f32_16x16x32_bf16 v[64:67], v[188:191], v[240:243], v[64:67]
	s_setprio 0
	s_barrier
	s_add_i32 s10, s10, s45
	v_lshl_add_u64 v[146:147], v[244:245], 0, s[92:93]
	s_mov_b32 m0, s10
	ds_read_b128 v[192:195], v151 offset:49152
	ds_read_b128 v[196:199], v151 offset:50176
	ds_read_b128 v[200:203], v151 offset:51200
	ds_read_b128 v[204:207], v151 offset:52224
	ds_read_b128 v[208:211], v151 offset:53248
	ds_read_b128 v[212:215], v151 offset:54272
	ds_read_b128 v[216:219], v151 offset:55296
	ds_read_b128 v[240:243], v151 offset:56320
	global_load_lds_dwordx4 v[146:147], off
	v_lshl_add_u64 v[146:147], v[246:247], 0, s[92:93]
	s_add_i32 m0, s10, 0x2000
	s_add_i32 s10, s62, s45
	global_load_lds_dwordx4 v[146:147], off
	v_lshl_add_u64 v[146:147], v[248:249], 0, s[92:93]
	s_mov_b32 m0, s10
	s_nop 0
	global_load_lds_dwordx4 v[146:147], off
	v_lshl_add_u64 v[146:147], v[220:221], 0, s[92:93]
	s_add_i32 m0, s10, 0x2000
	s_nop 0
	global_load_lds_dwordx4 v[146:147], off
	v_lshl_add_u64 v[146:147], v[250:251], 0, s[92:93]
	s_mov_b32 m0, s53
	s_nop 0
	global_load_lds_dwordx4 v[146:147], off
	v_lshl_add_u64 v[146:147], v[252:253], 0, s[92:93]
	s_mov_b32 m0, s54
	s_nop 0
	global_load_lds_dwordx4 v[146:147], off
	s_waitcnt vmcnt(8)
	s_waitcnt lgkmcnt(0)
	s_barrier
	s_setprio 1
	s_waitcnt lgkmcnt(0)
	v_mfma_f32_16x16x32_bf16 v[60:63], v[152:155], v[192:195], v[60:63]
	v_mfma_f32_16x16x32_bf16 v[56:59], v[160:163], v[192:195], v[56:59]
	v_mfma_f32_16x16x32_bf16 v[44:47], v[152:155], v[200:203], v[44:47]
	v_mfma_f32_16x16x32_bf16 v[40:43], v[160:163], v[200:203], v[40:43]
	v_mfma_f32_16x16x32_bf16 v[28:31], v[152:155], v[208:211], v[28:31]
	v_mfma_f32_16x16x32_bf16 v[24:27], v[160:163], v[208:211], v[24:27]
	v_mfma_f32_16x16x32_bf16 v[12:15], v[152:155], v[216:219], v[12:15]
	v_mfma_f32_16x16x32_bf16 v[8:11], v[160:163], v[216:219], v[8:11]
	v_mfma_f32_16x16x32_bf16 v[60:63], v[156:159], v[196:199], v[60:63]
	v_mfma_f32_16x16x32_bf16 v[56:59], v[164:167], v[196:199], v[56:59]
	v_mfma_f32_16x16x32_bf16 v[44:47], v[156:159], v[204:207], v[44:47]
	v_mfma_f32_16x16x32_bf16 v[40:43], v[164:167], v[204:207], v[40:43]
	v_mfma_f32_16x16x32_bf16 v[28:31], v[156:159], v[212:215], v[28:31]
	v_mfma_f32_16x16x32_bf16 v[24:27], v[164:167], v[212:215], v[24:27]
	v_mfma_f32_16x16x32_bf16 v[12:15], v[156:159], v[240:243], v[12:15]
	v_mfma_f32_16x16x32_bf16 v[8:11], v[164:167], v[240:243], v[8:11]
	s_setprio 0
	s_setprio 1
	v_mfma_f32_16x16x32_bf16 v[52:55], v[176:179], v[192:195], v[52:55]
	v_mfma_f32_16x16x32_bf16 v[48:51], v[184:187], v[192:195], v[48:51]
	v_mfma_f32_16x16x32_bf16 v[36:39], v[176:179], v[200:203], v[36:39]
	v_mfma_f32_16x16x32_bf16 v[32:35], v[184:187], v[200:203], v[32:35]
	v_mfma_f32_16x16x32_bf16 v[20:23], v[176:179], v[208:211], v[20:23]
	v_mfma_f32_16x16x32_bf16 v[16:19], v[184:187], v[208:211], v[16:19]
	v_mfma_f32_16x16x32_bf16 v[4:7], v[176:179], v[216:219], v[4:7]
	v_mfma_f32_16x16x32_bf16 v[0:3], v[184:187], v[216:219], v[0:3]
	v_mfma_f32_16x16x32_bf16 v[52:55], v[180:183], v[196:199], v[52:55]
	v_mfma_f32_16x16x32_bf16 v[48:51], v[188:191], v[196:199], v[48:51]
	v_mfma_f32_16x16x32_bf16 v[36:39], v[180:183], v[204:207], v[36:39]
	v_mfma_f32_16x16x32_bf16 v[32:35], v[188:191], v[204:207], v[32:35]
	v_mfma_f32_16x16x32_bf16 v[20:23], v[180:183], v[212:215], v[20:23]
	v_mfma_f32_16x16x32_bf16 v[16:19], v[188:191], v[212:215], v[16:19]
	v_mfma_f32_16x16x32_bf16 v[4:7], v[180:183], v[240:243], v[4:7]
	v_mfma_f32_16x16x32_bf16 v[0:3], v[188:191], v[240:243], v[0:3]
	s_setprio 0
	s_barrier
	v_lshl_add_u64 v[142:143], v[142:143], 0, s[80:81]
	v_lshl_add_u64 v[144:145], v[144:145], 0, s[80:81]
	s_mov_b32 s10, s11
	s_cmp_eq_u32 s10, s55
	s_cbranch_scc1 .Lq5_last
	s_branch .LBB0_354

; #define PG8_STAGE(bufoff, gbase, voff) do { _Pragma("unroll") for (int _i = 0; _i < 2; ++_i) \
;         __builtin_amdgcn_global_load_lds((const unsigned*)((const char*)(gbase) + (voff)[_i]), (LAS unsigned*)(lds + (bufoff) + ldsw + _i * 8192), 16, 0, 0); } while (0)
; #define PG8_LDA(dst, b, h) do { _Pragma("unroll") for (int m = 0; m < 4; ++m) _Pragma("unroll") for (int k = 0; k < 2; ++k) dst[m][k] = *(const LAS bf16x8*)(lds + PG8_SA(b, h) + aoff + m * 2048 + k * 1024); } while (0)
; #define PG8_LDB(dst, b, h) do { _Pragma("unroll") for (int n = 0; n < 2; ++n) _Pragma("unroll") for (int k = 0; k < 2; ++k) dst[n][k] = *(const LAS bf16x8*)(lds + PG8_SB(b, h) + boff + n * 2048 + k * 1024); } while (0)
; #define PG8_MMA(ai, bj, At, Bt) do { __builtin_amdgcn_s_setprio(1); _Pragma("unroll") for (int k = 0; k < 2; ++k) _Pragma("unroll") for (int m = 0; m < 4; ++m) _Pragma("unroll") for (int n = 0; n < 2; ++n) \
;         acc[ai][bj][m][n] = __builtin_amdgcn_mfma_f32_16x16x32_bf16(Bt[n][k], At[m][k], acc[ai][bj][m][n], 0, 0, 0); __builtin_amdgcn_s_setprio(0); } while (0)
; #define PG8_WAIT_V(n) asm volatile("s_waitcnt vmcnt(" #n ")" ::: "memory")
; template <class Epi, bool ALIGN_EPI>
; __device__ __forceinline__ void gemm_phase(LAS unsigned char* lds, const Gemm g, const StaticOrder& S, const Epi& E, const int tid) {
;     ...
;         const char* nA = has_next ? (const char*)g.A + (size_t)nxt.pm * tA + (size_t)nxt.pn * g.apn * 2 : cA; const char* nB = has_next ? (const char*)g.Bt + (size_t)nxt.pn * tB : cB;
;         for (int t = 0; t < nt; t += 2) {
;             const bool last = (t == nt - 2);
;             const char* a1 = cA + (size_t)(t + 1) * kstep;
;             const char* a2 = last ? nA : cA + (size_t)(t + 2) * kstep; const char* b2 = last ? nB : cB + (size_t)(t + 2) * kstep;
;             const char* a3 = a2 + kstep; const char* b3 = b2 + kstep;
;             PG8_LDB(B0, 0, 0); PG8_LDB(B1, 0, 1); PG8_SCHED; PG8_LDA(At, 0, 0); PG8_STAGE(PG8_SA(1, 1), a1 + hA, voffA);
;             PG8_WAIT_V(8); PG8_WAIT_L(0); PG8_BAR; PG8_MMA(0, 0, At, B0); PG8_MMA(0, 1, At, B1); PG8_BAR; PG8_SCHED;
;             PG8_LDA(At, 0, 1); PG8_STAGE(PG8_SB(0, 0), b2, voffB); PG8_STAGE(PG8_SB(0, 1), b2 + hB, voffB); PG8_STAGE(PG8_SA(0, 0), a2, voffA);
;             PG8_WAIT_V(8); PG8_WAIT_L(0); PG8_BAR; PG8_MMA(1, 0, At, B0); PG8_MMA(1, 1, At, B1); PG8_BAR; PG8_SCHED;
.Lq5_last:
	s_add_i32 s11, s10, 2
	s_cmp_eq_u32 s55, s10
	s_cselect_b64 vcc, -1, 0
	v_add_u32_e32 v148, s33, v149
	s_add_i32 s10, 0, 0x14000
	ds_read_b128 v[152:155], v148
	ds_read_b128 v[156:159], v148 offset:1024
	ds_read_b128 v[160:163], v148 offset:2048
	ds_read_b128 v[164:167], v148 offset:3072
	v_add_u32_e32 v148, s10, v149
	ds_read_b128 v[176:179], v148
	ds_read_b128 v[180:183], v148 offset:1024
	ds_read_b128 v[184:187], v148 offset:2048
	ds_read_b128 v[188:191], v148 offset:3072
	v_lshl_add_u64 v[146:147], v[142:143], 0, s[92:93]
	v_cndmask_b32_e32 v147, v147, v139, vcc
	v_cndmask_b32_e32 v146, v146, v138, vcc
	v_cndmask_b32_e32 v221, v145, v141, vcc
	v_cndmask_b32_e32 v220, v144, v140, vcc
	v_lshl_add_u64 v[244:245], v[142:143], 0, v[134:135]
	s_add_i32 m0, s25, 0xc000
	ds_read_b128 v[192:195], v151
	ds_read_b128 v[196:199], v151 offset:1024
	ds_read_b128 v[200:203], v151 offset:2048
	ds_read_b128 v[204:207], v151 offset:3072
	ds_read_b128 v[208:211], v151 offset:4096
	ds_read_b128 v[212:215], v151 offset:5120
	ds_read_b128 v[216:219], v151 offset:6144
	ds_read_b128 v[240:243], v151 offset:7168
	global_load_lds_dwordx4 v[244:245], off
	v_lshl_add_u64 v[244:245], v[142:143], 0, v[136:137]
	s_add_i32 m0, s25, 0xe000
	s_nop 0
	global_load_lds_dwordx4 v[244:245], off
	s_waitcnt vmcnt(8)
	s_waitcnt lgkmcnt(0)
	s_barrier
	s_setprio 1
	s_waitcnt lgkmcnt(0)
	v_mfma_f32_16x16x32_bf16 v[124:127], v[152:155], v[192:195], v[124:127]
	v_mfma_f32_16x16x32_bf16 v[120:123], v[160:163], v[192:195], v[120:123]
	v_mfma_f32_16x16x32_bf16 v[108:111], v[152:155], v[200:203], v[108:111]
	v_mfma_f32_16x16x32_bf16 v[104:107], v[160:163], v[200:203], v[104:107]
	v_mfma_f32_16x16x32_bf16 v[92:95], v[152:155], v[208:211], v[92:95]
	v_mfma_f32_16x16x32_bf16 v[88:91], v[160:163], v[208:211], v[88:91]
	v_mfma_f32_16x16x32_bf16 v[76:79], v[152:155], v[216:219], v[76:79]
	v_mfma_f32_16x16x32_bf16 v[72:75], v[160:163], v[216:219], v[72:75]
	v_mfma_f32_16x16x32_bf16 v[124:127], v[156:159], v[196:199], v[124:127]
	v_mfma_f32_16x16x32_bf16 v[120:123], v[164:167], v[196:199], v[120:123]
	v_mfma_f32_16x16x32_bf16 v[108:111], v[156:159], v[204:207], v[108:111]
	v_mfma_f32_16x16x32_bf16 v[104:107], v[164:167], v[204:207], v[104:107]
	v_mfma_f32_16x16x32_bf16 v[92:95], v[156:159], v[212:215], v[92:95]
	v_mfma_f32_16x16x32_bf16 v[88:91], v[164:167], v[212:215], v[88:91]
	v_mfma_f32_16x16x32_bf16 v[76:79], v[156:159], v[240:243], v[76:79]
	v_mfma_f32_16x16x32_bf16 v[72:75], v[164:167], v[240:243], v[72:75]
	s_setprio 0
	s_setprio 1
	v_mfma_f32_16x16x32_bf16 v[116:119], v[176:179], v[192:195], v[116:119]
	v_mfma_f32_16x16x32_bf16 v[112:115], v[184:187], v[192:195], v[112:115]
	v_mfma_f32_16x16x32_bf16 v[100:103], v[176:179], v[200:203], v[100:103]
	v_mfma_f32_16x16x32_bf16 v[96:99], v[184:187], v[200:203], v[96:99]
	v_mfma_f32_16x16x32_bf16 v[84:87], v[176:179], v[208:211], v[84:87]
	v_mfma_f32_16x16x32_bf16 v[80:83], v[184:187], v[208:211], v[80:83]
	v_mfma_f32_16x16x32_bf16 v[68:71], v[176:179], v[216:219], v[68:71]
	v_mfma_f32_16x16x32_bf16 v[64:67], v[184:187], v[216:219], v[64:67]
	v_mfma_f32_16x16x32_bf16 v[116:119], v[180:183], v[196:199], v[116:119]
	v_mfma_f32_16x16x32_bf16 v[112:115], v[188:191], v[196:199], v[112:115]
	v_mfma_f32_16x16x32_bf16 v[100:103], v[180:183], v[204:207], v[100:103]
	v_mfma_f32_16x16x32_bf16 v[96:99], v[188:191], v[204:207], v[96:99]
	v_mfma_f32_16x16x32_bf16 v[84:87], v[180:183], v[212:215], v[84:87]
	v_mfma_f32_16x16x32_bf16 v[80:83], v[188:191], v[212:215], v[80:83]
	v_mfma_f32_16x16x32_bf16 v[68:71], v[180:183], v[240:243], v[68:71]
	v_mfma_f32_16x16x32_bf16 v[64:67], v[188:191], v[240:243], v[64:67]
	s_setprio 0
	s_barrier
	s_add_i32 s62, s33, s45
	v_lshl_add_u64 v[244:245], v[220:221], 0, v[168:169]
	s_mov_b32 m0, s62
	ds_read_b128 v[192:195], v151 offset:16384
	ds_read_b128 v[196:199], v151 offset:17408
	ds_read_b128 v[200:203], v151 offset:18432
	ds_read_b128 v[204:207], v151 offset:19456
	ds_read_b128 v[208:211], v151 offset:20480
	ds_read_b128 v[212:215], v151 offset:21504
	ds_read_b128 v[216:219], v151 offset:22528
	ds_read_b128 v[240:243], v151 offset:23552
	global_load_lds_dwordx4 v[244:245], off
	v_lshl_add_u64 v[246:247], v[220:221], 0, v[128:129]
	s_add_i32 m0, s62, 0x2000
	v_lshl_add_u64 v[220:221], v[220:221], 0, s[12:13]
	s_add_i32 s10, s10, s45
	global_load_lds_dwordx4 v[246:247], off
	v_lshl_add_u64 v[248:249], v[220:221], 0, v[168:169]
	s_mov_b32 m0, s10
	v_lshl_add_u64 v[220:221], v[220:221], 0, v[128:129]
	global_load_lds_dwordx4 v[248:249], off
	s_add_i32 m0, s10, 0x2000
	v_lshl_add_u64 v[250:251], v[146:147], 0, v[132:133]
	global_load_lds_dwordx4 v[220:221], off
	s_mov_b32 m0, s25
	v_lshl_add_u64 v[252:253], v[146:147], 0, v[130:131]
	global_load_lds_dwordx4 v[250:251], off
	s_mov_b32 m0, s50
	s_nop 0
	global_load_lds_dwordx4 v[252:253], off
	s_waitcnt vmcnt(8)
	s_waitcnt lgkmcnt(0)
	s_barrier
; #define PG8_STAGE(bufoff, gbase, voff) do { _Pragma("unroll") for (int _i = 0; _i < 2; ++_i) \
;         __builtin_amdgcn_global_load_lds((const unsigned*)((const char*)(gbase) + (voff)[_i]), (LAS unsigned*)(lds + (bufoff) + ldsw + _i * 8192), 16, 0, 0); } while (0)
; #define PG8_LDA(dst, b, h) do { _Pragma("unroll") for (int m = 0; m < 4; ++m) _Pragma("unroll") for (int k = 0; k < 2; ++k) dst[m][k] = *(const LAS bf16x8*)(lds + PG8_SA(b, h) + aoff + m * 2048 + k * 1024); } while (0)
; #define PG8_LDB(dst, b, h) do { _Pragma("unroll") for (int n = 0; n < 2; ++n) _Pragma("unroll") for (int k = 0; k < 2; ++k) dst[n][k] = *(const LAS bf16x8*)(lds + PG8_SB(b, h) + boff + n * 2048 + k * 1024); } while (0)
; #define PG8_MMA(ai, bj, At, Bt) do { __builtin_amdgcn_s_setprio(1); _Pragma("unroll") for (int k = 0; k < 2; ++k) _Pragma("unroll") for (int m = 0; m < 4; ++m) _Pragma("unroll") for (int n = 0; n < 2; ++n) \
;         acc[ai][bj][m][n] = __builtin_amdgcn_mfma_f32_16x16x32_bf16(Bt[n][k], At[m][k], acc[ai][bj][m][n], 0, 0, 0); __builtin_amdgcn_s_setprio(0); } while (0)
; #define PG8_WAIT_V(n) asm volatile("s_waitcnt vmcnt(" #n ")" ::: "memory")
; #define PG8_WAIT_L(n) asm volatile("s_waitcnt lgkmcnt(" #n ")" ::: "memory")
; #define PG8_BAR __builtin_amdgcn_s_barrier()
; #define PG8_SCHED __builtin_amdgcn_sched_barrier(0)
; template <class Epi, bool ALIGN_EPI>
; __device__ __forceinline__ void gemm_phase(LAS unsigned char* lds, const Gemm g, const StaticOrder& S, const Epi& E, const int tid) {
;     ...
;             PG8_LDA(At, 0, 1); PG8_STAGE(PG8_SB(0, 0), b2, voffB); PG8_STAGE(PG8_SB(0, 1), b2 + hB, voffB); PG8_STAGE(PG8_SA(0, 0), a2, voffA);
;             PG8_WAIT_V(8); PG8_WAIT_L(0); PG8_BAR; PG8_MMA(1, 0, At, B0); PG8_MMA(1, 1, At, B1); PG8_BAR; PG8_SCHED;
;             PG8_LDB(B0, 1, 0); PG8_LDB(B1, 1, 1); PG8_SCHED; PG8_LDA(At, 1, 0); PG8_STAGE(PG8_SA(0, 1), a2 + hA, voffA);
;             PG8_WAIT_V(8); PG8_WAIT_L(0); PG8_BAR; PG8_MMA(0, 0, At, B0); PG8_MMA(0, 1, At, B1); PG8_BAR; PG8_SCHED;
;             PG8_LDA(At, 1, 1); PG8_STAGE(PG8_SB(1, 0), b3, voffB); PG8_STAGE(PG8_SB(1, 1), b3 + hB, voffB); PG8_STAGE(PG8_SA(1, 0), a3, voffA);
;             PG8_WAIT_V(8); PG8_WAIT_L(0); PG8_BAR; PG8_MMA(1, 0, At, B0); PG8_MMA(1, 1, At, B1); PG8_BAR; PG8_SCHED;
	s_setprio 1
	s_waitcnt lgkmcnt(0)
	v_mfma_f32_16x16x32_bf16 v[60:63], v[152:155], v[192:195], v[60:63]
	v_mfma_f32_16x16x32_bf16 v[56:59], v[160:163], v[192:195], v[56:59]
	v_mfma_f32_16x16x32_bf16 v[44:47], v[152:155], v[200:203], v[44:47]
	v_mfma_f32_16x16x32_bf16 v[40:43], v[160:163], v[200:203], v[40:43]
	v_mfma_f32_16x16x32_bf16 v[28:31], v[152:155], v[208:211], v[28:31]
	v_mfma_f32_16x16x32_bf16 v[24:27], v[160:163], v[208:211], v[24:27]
	v_mfma_f32_16x16x32_bf16 v[12:15], v[152:155], v[216:219], v[12:15]
	v_mfma_f32_16x16x32_bf16 v[8:11], v[160:163], v[216:219], v[8:11]
	v_mfma_f32_16x16x32_bf16 v[60:63], v[156:159], v[196:199], v[60:63]
	v_mfma_f32_16x16x32_bf16 v[56:59], v[164:167], v[196:199], v[56:59]
	v_mfma_f32_16x16x32_bf16 v[44:47], v[156:159], v[204:207], v[44:47]
	v_mfma_f32_16x16x32_bf16 v[40:43], v[164:167], v[204:207], v[40:43]
	v_mfma_f32_16x16x32_bf16 v[28:31], v[156:159], v[212:215], v[28:31]
	v_mfma_f32_16x16x32_bf16 v[24:27], v[164:167], v[212:215], v[24:27]
	v_mfma_f32_16x16x32_bf16 v[12:15], v[156:159], v[240:243], v[12:15]
	v_mfma_f32_16x16x32_bf16 v[8:11], v[164:167], v[240:243], v[8:11]
	s_setprio 0
	s_setprio 1
	v_mfma_f32_16x16x32_bf16 v[52:55], v[176:179], v[192:195], v[52:55]
	v_mfma_f32_16x16x32_bf16 v[48:51], v[184:187], v[192:195], v[48:51]
	v_mfma_f32_16x16x32_bf16 v[36:39], v[176:179], v[200:203], v[36:39]
	v_mfma_f32_16x16x32_bf16 v[32:35], v[184:187], v[200:203], v[32:35]
	v_mfma_f32_16x16x32_bf16 v[20:23], v[176:179], v[208:211], v[20:23]
	v_mfma_f32_16x16x32_bf16 v[16:19], v[184:187], v[208:211], v[16:19]
	v_mfma_f32_16x16x32_bf16 v[4:7], v[176:179], v[216:219], v[4:7]
	v_mfma_f32_16x16x32_bf16 v[0:3], v[184:187], v[216:219], v[0:3]
	v_mfma_f32_16x16x32_bf16 v[52:55], v[180:183], v[196:199], v[52:55]
	v_mfma_f32_16x16x32_bf16 v[48:51], v[188:191], v[196:199], v[48:51]
	v_mfma_f32_16x16x32_bf16 v[36:39], v[180:183], v[204:207], v[36:39]
	v_mfma_f32_16x16x32_bf16 v[32:35], v[188:191], v[204:207], v[32:35]
	v_mfma_f32_16x16x32_bf16 v[20:23], v[180:183], v[212:215], v[20:23]
	v_mfma_f32_16x16x32_bf16 v[16:19], v[188:191], v[212:215], v[16:19]
	v_mfma_f32_16x16x32_bf16 v[4:7], v[180:183], v[240:243], v[4:7]
	v_mfma_f32_16x16x32_bf16 v[0:3], v[188:191], v[240:243], v[0:3]
	s_setprio 0
	s_barrier
	s_add_i32 s10, 0, 0x18000
	v_add_u32_e32 v148, s10, v149
	s_add_i32 s62, 0, 0x1c000
	ds_read_b128 v[152:155], v148
	ds_read_b128 v[156:159], v148 offset:1024
	ds_read_b128 v[160:163], v148 offset:2048
	ds_read_b128 v[164:167], v148 offset:3072
	v_add_u32_e32 v148, s62, v149
	ds_read_b128 v[176:179], v148
	ds_read_b128 v[180:183], v148 offset:1024
	ds_read_b128 v[184:187], v148 offset:2048
	ds_read_b128 v[188:191], v148 offset:3072
	v_lshl_add_u64 v[146:147], v[146:147], 0, s[94:95]
	s_mov_b32 m0, s51
	v_lshl_add_u64 v[226:227], v[146:147], 0, v[132:133]
	ds_read_b128 v[192:195], v151 offset:32768
	ds_read_b128 v[196:199], v151 offset:33792
	ds_read_b128 v[200:203], v151 offset:34816
	ds_read_b128 v[204:207], v151 offset:35840
	ds_read_b128 v[208:211], v151 offset:36864
	ds_read_b128 v[212:215], v151 offset:37888
	ds_read_b128 v[216:219], v151 offset:38912
	ds_read_b128 v[240:243], v151 offset:39936
	global_load_lds_dwordx4 v[226:227], off
	v_lshl_add_u64 v[146:147], v[146:147], 0, v[130:131]
	s_mov_b32 m0, s52
	s_nop 0
	global_load_lds_dwordx4 v[146:147], off
	s_waitcnt vmcnt(8)
	s_waitcnt lgkmcnt(0)
	s_barrier
	s_setprio 1
	s_waitcnt lgkmcnt(0)
	v_mfma_f32_16x16x32_bf16 v[124:127], v[152:155], v[192:195], v[124:127]
	v_mfma_f32_16x16x32_bf16 v[120:123], v[160:163], v[192:195], v[120:123]
	v_mfma_f32_16x16x32_bf16 v[108:111], v[152:155], v[200:203], v[108:111]
	v_mfma_f32_16x16x32_bf16 v[104:107], v[160:163], v[200:203], v[104:107]
	v_mfma_f32_16x16x32_bf16 v[92:95], v[152:155], v[208:211], v[92:95]
	v_mfma_f32_16x16x32_bf16 v[88:91], v[160:163], v[208:211], v[88:91]
	v_mfma_f32_16x16x32_bf16 v[76:79], v[152:155], v[216:219], v[76:79]
	v_mfma_f32_16x16x32_bf16 v[72:75], v[160:163], v[216:219], v[72:75]
	v_mfma_f32_16x16x32_bf16 v[124:127], v[156:159], v[196:199], v[124:127]
	v_mfma_f32_16x16x32_bf16 v[120:123], v[164:167], v[196:199], v[120:123]
	v_mfma_f32_16x16x32_bf16 v[108:111], v[156:159], v[204:207], v[108:111]
	v_mfma_f32_16x16x32_bf16 v[104:107], v[164:167], v[204:207], v[104:107]
	v_mfma_f32_16x16x32_bf16 v[92:95], v[156:159], v[212:215], v[92:95]
	v_mfma_f32_16x16x32_bf16 v[88:91], v[164:167], v[212:215], v[88:91]
	v_mfma_f32_16x16x32_bf16 v[76:79], v[156:159], v[240:243], v[76:79]
	v_mfma_f32_16x16x32_bf16 v[72:75], v[164:167], v[240:243], v[72:75]
	s_setprio 0
	s_setprio 1
	v_mfma_f32_16x16x32_bf16 v[116:119], v[176:179], v[192:195], v[116:119]
	v_mfma_f32_16x16x32_bf16 v[112:115], v[184:187], v[192:195], v[112:115]
	v_mfma_f32_16x16x32_bf16 v[100:103], v[176:179], v[200:203], v[100:103]
	v_mfma_f32_16x16x32_bf16 v[96:99], v[184:187], v[200:203], v[96:99]
	v_mfma_f32_16x16x32_bf16 v[84:87], v[176:179], v[208:211], v[84:87]
	v_mfma_f32_16x16x32_bf16 v[80:83], v[184:187], v[208:211], v[80:83]
	v_mfma_f32_16x16x32_bf16 v[68:71], v[176:179], v[216:219], v[68:71]
	v_mfma_f32_16x16x32_bf16 v[64:67], v[184:187], v[216:219], v[64:67]
	v_mfma_f32_16x16x32_bf16 v[116:119], v[180:183], v[196:199], v[116:119]
	v_mfma_f32_16x16x32_bf16 v[112:115], v[188:191], v[196:199], v[112:115]
	v_mfma_f32_16x16x32_bf16 v[100:103], v[180:183], v[204:207], v[100:103]
	v_mfma_f32_16x16x32_bf16 v[96:99], v[188:191], v[204:207], v[96:99]
	v_mfma_f32_16x16x32_bf16 v[84:87], v[180:183], v[212:215], v[84:87]
	v_mfma_f32_16x16x32_bf16 v[80:83], v[188:191], v[212:215], v[80:83]
	v_mfma_f32_16x16x32_bf16 v[68:71], v[180:183], v[240:243], v[68:71]
	v_mfma_f32_16x16x32_bf16 v[64:67], v[188:191], v[240:243], v[64:67]
	s_setprio 0
	s_barrier
; #define PG8_STAGE(bufoff, gbase, voff) do { _Pragma("unroll") for (int _i = 0; _i < 2; ++_i) \
;         __builtin_amdgcn_global_load_lds((const unsigned*)((const char*)(gbase) + (voff)[_i]), (LAS unsigned*)(lds + (bufoff) + ldsw + _i * 8192), 16, 0, 0); } while (0)
; #define PG8_LDA(dst, b, h) do { _Pragma("unroll") for (int m = 0; m < 4; ++m) _Pragma("unroll") for (int k = 0; k < 2; ++k) dst[m][k] = *(const LAS bf16x8*)(lds + PG8_SA(b, h) + aoff + m * 2048 + k * 1024); } while (0)
; #define PG8_MMA(ai, bj, At, Bt) do { __builtin_amdgcn_s_setprio(1); _Pragma("unroll") for (int k = 0; k < 2; ++k) _Pragma("unroll") for (int m = 0; m < 4; ++m) _Pragma("unroll") for (int n = 0; n < 2; ++n) \
;         acc[ai][bj][m][n] = __builtin_amdgcn_mfma_f32_16x16x32_bf16(Bt[n][k], At[m][k], acc[ai][bj][m][n], 0, 0, 0); __builtin_amdgcn_s_setprio(0); } while (0)
; #define PG8_WAIT_V(n) asm volatile("s_waitcnt vmcnt(" #n ")" ::: "memory")
; #define PG8_WAIT_L(n) asm volatile("s_waitcnt lgkmcnt(" #n ")" ::: "memory")
; #define PG8_BAR __builtin_amdgcn_s_barrier()
; #define PG8_SCHED __builtin_amdgcn_sched_barrier(0)
; template <class Epi, bool ALIGN_EPI>
; __device__ __forceinline__ void gemm_phase(LAS unsigned char* lds, const Gemm g, const StaticOrder& S, const Epi& E, const int tid) {
;     ...
;             PG8_LDA(At, 1, 1); PG8_STAGE(PG8_SB(1, 0), b3, voffB); PG8_STAGE(PG8_SB(1, 1), b3 + hB, voffB); PG8_STAGE(PG8_SA(1, 0), a3, voffA);
;             PG8_WAIT_V(8); PG8_WAIT_L(0); PG8_BAR; PG8_MMA(1, 0, At, B0); PG8_MMA(1, 1, At, B1); PG8_BAR; PG8_SCHED;
	s_add_i32 s10, s10, s45
	v_lshl_add_u64 v[146:147], v[244:245], 0, s[92:93]
	s_mov_b32 m0, s10
	ds_read_b128 v[192:195], v151 offset:49152
	ds_read_b128 v[196:199], v151 offset:50176
	ds_read_b128 v[200:203], v151 offset:51200
	ds_read_b128 v[204:207], v151 offset:52224
	ds_read_b128 v[208:211], v151 offset:53248
	ds_read_b128 v[212:215], v151 offset:54272
	ds_read_b128 v[216:219], v151 offset:55296
	ds_read_b128 v[240:243], v151 offset:56320
	global_load_lds_dwordx4 v[146:147], off
	v_lshl_add_u64 v[146:147], v[246:247], 0, s[92:93]
	s_add_i32 m0, s10, 0x2000
	s_add_i32 s10, s62, s45
	global_load_lds_dwordx4 v[146:147], off
	v_lshl_add_u64 v[146:147], v[248:249], 0, s[92:93]
	s_mov_b32 m0, s10
	s_nop 0
	global_load_lds_dwordx4 v[146:147], off
	v_lshl_add_u64 v[146:147], v[220:221], 0, s[92:93]
	s_add_i32 m0, s10, 0x2000
	s_nop 0
	global_load_lds_dwordx4 v[146:147], off
	v_lshl_add_u64 v[146:147], v[250:251], 0, s[92:93]
	s_mov_b32 m0, s53
	s_nop 0
	global_load_lds_dwordx4 v[146:147], off
	v_lshl_add_u64 v[146:147], v[252:253], 0, s[92:93]
	s_mov_b32 m0, s54
	s_nop 0
	global_load_lds_dwordx4 v[146:147], off
	s_waitcnt vmcnt(8)
	s_waitcnt lgkmcnt(0)
	s_barrier
; __device__ __forceinline__ unsigned cvt_pk_bf16(float lo, float hi) { unsigned r; asm volatile("v_cvt_pk_bf16_f32 %0, %1, %2" : "=v"(r) : "v"(lo), "v"(hi)); return r; }
; __device__ __forceinline__ float gelu_tanh(float x) { const float u = 0.7978845608028654f * (x + 0.044715f * x * x * x); return x * fast_rcp(1.0f + fast_exp2(-2.0f * LOG2E * u)); }
; #define PG8_STAGE(bufoff, gbase, voff) do { _Pragma("unroll") for (int _i = 0; _i < 2; ++_i) \
;         __builtin_amdgcn_global_load_lds((const unsigned*)((const char*)(gbase) + (voff)[_i]), (LAS unsigned*)(lds + (bufoff) + ldsw + _i * 8192), 16, 0, 0); } while (0)
; #define PG8_LDA(dst, b, h) do { _Pragma("unroll") for (int m = 0; m < 4; ++m) _Pragma("unroll") for (int k = 0; k < 2; ++k) dst[m][k] = *(const LAS bf16x8*)(lds + PG8_SA(b, h) + aoff + m * 2048 + k * 1024); } while (0)
; #define PG8_WAIT_V(n) asm volatile("s_waitcnt vmcnt(" #n ")" ::: "memory")
;     __device__ __forceinline__ void operator()(const f32x4 (&acc)[2][2][4][2], const Unit& u, int wr, int wc, int fr, int fq) const {
;         const int row0 = u.pm * BM + wr * 64 + fr, col0 = u.pn * BM + wc * 32 + 8 * fq;
;         float rsv[2][4]; load_rstd(rsv, ssq, row0);
; #pragma unroll
;         for (int ai = 0; ai < 2; ++ai)
; #pragma unroll
;             for (int m = 0; m < 4; ++m) { const int row = row0 + ai * HALF + m * 16; bf16_t* rowp = O + (size_t)row * ldc + col0; const float rs = rsv[ai][m];
; #pragma unroll
;                 for (int bj = 0; bj < 2; ++bj) { f32x4 v0 = acc[ai][bj][m][0] * rs, v1 = acc[ai][bj][m][1] * rs;
;                     if (ACT == 1) {
; #pragma unroll
;                         for (int j = 0; j < 4; ++j) { v0[j] = gelu_tanh(v0[j]); v1[j] = gelu_tanh(v1[j]); } }
;                     u32x4 w; w.x = cvt_pk_bf16(v0[0], v0[1]); w.y = cvt_pk_bf16(v0[2], v0[3]); w.z = cvt_pk_bf16(v1[0], v1[1]); w.w = cvt_pk_bf16(v1[2], v1[3]);
;                     *(u32x4*)(rowp + bj * HALF) = w; } }
; template <class Epi, bool ALIGN_EPI>
; __device__ __forceinline__ void gemm_phase(LAS unsigned char* lds, const Gemm g, const StaticOrder& S, const Epi& E, const int tid) {
;     ...
;             PG8_LDA(At, 1, 1); PG8_STAGE(PG8_SB(1, 0), b3, voffB); PG8_STAGE(PG8_SB(1, 1), b3 + hB, voffB); PG8_STAGE(PG8_SA(1, 0), a3, voffA);
;             PG8_WAIT_V(8); PG8_WAIT_L(0); PG8_BAR; PG8_MMA(1, 0, At, B0); PG8_MMA(1, 1, At, B1); PG8_BAR; PG8_SCHED;
	s_setprio 1
	s_waitcnt lgkmcnt(0)
	v_mfma_f32_16x16x32_bf16 v[60:63], v[152:155], v[192:195], v[60:63]
	v_lshrrev_b32_e32 v171, 8, v170
	v_and_b32_e32 v234, 15, v170
	v_lshl_add_u32 v171, v171, 6, v234
	s_lshl_b32 s98, s61, 8
	v_mfma_f32_16x16x32_bf16 v[56:59], v[160:163], v[192:195], v[56:59]
	v_add_u32_e32 v171, s98, v171
	v_mul_lo_u32 v171, v171, s28
	v_bfe_u32 v234, v170, 6, 2
	v_bfe_u32 v224, v170, 4, 2
	v_mfma_f32_16x16x32_bf16 v[44:47], v[152:155], v[200:203], v[44:47]
	v_lshlrev_b32_e32 v234, 5, v234
	v_lshl_or_b32 v234, v224, 3, v234
	s_lshl_b32 s98, s60, 8
	v_add_u32_e32 v234, s98, v234
	v_mfma_f32_16x16x32_bf16 v[40:43], v[160:163], v[200:203], v[40:43]
	v_add_lshl_u32 v232, v171, v234, 1
	s_lshl_b32 s98, s28, 5
	s_mov_b32 s99, 0
	v_mul_f32_e32 v124, v172, v124
	v_mfma_f32_16x16x32_bf16 v[28:31], v[152:155], v[208:211], v[28:31]
	v_mul_f32_e32 v125, v172, v125
	v_mul_f32_e32 v126, v172, v126
	v_mul_f32_e32 v127, v172, v127
	v_mul_f32_e32 v120, v172, v120
	v_mfma_f32_16x16x32_bf16 v[24:27], v[160:163], v[208:211], v[24:27]
	v_mul_f32_e32 v121, v172, v121
	v_mul_f32_e32 v122, v172, v122
	v_mul_f32_e32 v123, v172, v123
	v_cvt_pk_bf16_f32 v124, v124, v125
	v_mfma_f32_16x16x32_bf16 v[12:15], v[152:155], v[216:219], v[12:15]
	v_cvt_pk_bf16_f32 v125, v126, v127
	v_cvt_pk_bf16_f32 v126, v120, v121
	v_cvt_pk_bf16_f32 v127, v122, v123
	global_store_dwordx4 v232, v[124:127], s[30:31]
	v_mfma_f32_16x16x32_bf16 v[8:11], v[160:163], v[216:219], v[8:11]
	v_mul_f32_e32 v116, v172, v116
	v_mul_f32_e32 v117, v172, v117
	v_mul_f32_e32 v118, v172, v118
	v_mul_f32_e32 v119, v172, v119
	v_mfma_f32_16x16x32_bf16 v[60:63], v[156:159], v[196:199], v[60:63]
	v_mul_f32_e32 v112, v172, v112
	v_mul_f32_e32 v113, v172, v113
	v_mul_f32_e32 v114, v172, v114
	v_mul_f32_e32 v115, v172, v115
	v_mfma_f32_16x16x32_bf16 v[56:59], v[164:167], v[196:199], v[56:59]
	v_cvt_pk_bf16_f32 v116, v116, v117
	v_cvt_pk_bf16_f32 v117, v118, v119
	v_cvt_pk_bf16_f32 v118, v112, v113
	v_cvt_pk_bf16_f32 v119, v114, v115
	v_mfma_f32_16x16x32_bf16 v[44:47], v[156:159], v[204:207], v[44:47]
	global_store_dwordx4 v232, v[116:119], s[30:31] offset:256
	v_add_u32_e32 v232, s98, v232
	v_mul_f32_e32 v108, v173, v108
	v_mul_f32_e32 v109, v173, v109
	v_mfma_f32_16x16x32_bf16 v[40:43], v[164:167], v[204:207], v[40:43]
	v_mul_f32_e32 v110, v173, v110
	v_mul_f32_e32 v111, v173, v111
	v_mul_f32_e32 v104, v173, v104
	v_mul_f32_e32 v105, v173, v105
	v_mfma_f32_16x16x32_bf16 v[28:31], v[156:159], v[212:215], v[28:31]
	v_mul_f32_e32 v106, v173, v106
	v_mul_f32_e32 v107, v173, v107
	v_cvt_pk_bf16_f32 v108, v108, v109
	v_cvt_pk_bf16_f32 v109, v110, v111
	v_mfma_f32_16x16x32_bf16 v[24:27], v[164:167], v[212:215], v[24:27]
	v_cvt_pk_bf16_f32 v110, v104, v105
	v_cvt_pk_bf16_f32 v111, v106, v107
	global_store_dwordx4 v232, v[108:111], s[30:31]
	v_mul_f32_e32 v100, v173, v100
	v_mfma_f32_16x16x32_bf16 v[12:15], v[156:159], v[240:243], v[12:15]
	v_mul_f32_e32 v101, v173, v101
	v_mul_f32_e32 v102, v173, v102
	v_mul_f32_e32 v103, v173, v103
	v_mul_f32_e32 v96, v173, v96
	v_mfma_f32_16x16x32_bf16 v[8:11], v[164:167], v[240:243], v[8:11]
	v_mul_f32_e32 v97, v173, v97
	v_mul_f32_e32 v98, v173, v98
	v_mul_f32_e32 v99, v173, v99
	v_cvt_pk_bf16_f32 v100, v100, v101
	s_setprio 0
	s_setprio 1
	v_mfma_f32_16x16x32_bf16 v[52:55], v[176:179], v[192:195], v[52:55]
	v_cvt_pk_bf16_f32 v101, v102, v103
	v_cvt_pk_bf16_f32 v102, v96, v97
	v_cvt_pk_bf16_f32 v103, v98, v99
	global_store_dwordx4 v232, v[100:103], s[30:31] offset:256
	v_mfma_f32_16x16x32_bf16 v[48:51], v[184:187], v[192:195], v[48:51]
	v_add_u32_e32 v232, s98, v232
	v_mul_f32_e32 v92, v236, v92
	v_mul_f32_e32 v93, v236, v93
	v_mul_f32_e32 v94, v236, v94
	v_mfma_f32_16x16x32_bf16 v[36:39], v[176:179], v[200:203], v[36:39]
	v_mul_f32_e32 v95, v236, v95
	v_mul_f32_e32 v88, v236, v88
	v_mul_f32_e32 v89, v236, v89
	v_mul_f32_e32 v90, v236, v90
	v_mfma_f32_16x16x32_bf16 v[32:35], v[184:187], v[200:203], v[32:35]
	v_mul_f32_e32 v91, v236, v91
	v_cvt_pk_bf16_f32 v92, v92, v93
	v_cvt_pk_bf16_f32 v93, v94, v95
	v_cvt_pk_bf16_f32 v94, v88, v89
	v_mfma_f32_16x16x32_bf16 v[20:23], v[176:179], v[208:211], v[20:23]
	v_cvt_pk_bf16_f32 v95, v90, v91
	global_store_dwordx4 v232, v[92:95], s[30:31]
	v_mul_f32_e32 v84, v236, v84
	v_mul_f32_e32 v85, v236, v85
	v_mfma_f32_16x16x32_bf16 v[16:19], v[184:187], v[208:211], v[16:19]
	v_mul_f32_e32 v86, v236, v86
	v_mul_f32_e32 v87, v236, v87
	v_mul_f32_e32 v80, v236, v80
	v_mul_f32_e32 v81, v236, v81
	v_mfma_f32_16x16x32_bf16 v[4:7], v[176:179], v[216:219], v[4:7]
	v_mul_f32_e32 v82, v236, v82
	v_mul_f32_e32 v83, v236, v83
	v_cvt_pk_bf16_f32 v84, v84, v85
	v_cvt_pk_bf16_f32 v85, v86, v87
	v_mfma_f32_16x16x32_bf16 v[0:3], v[184:187], v[216:219], v[0:3]
	v_cvt_pk_bf16_f32 v86, v80, v81
	v_cvt_pk_bf16_f32 v87, v82, v83
	global_store_dwordx4 v232, v[84:87], s[30:31] offset:256
	v_add_u32_e32 v232, s98, v232
	v_mfma_f32_16x16x32_bf16 v[52:55], v[180:183], v[196:199], v[52:55]
	v_mul_f32_e32 v76, v237, v76
	v_mul_f32_e32 v77, v237, v77
	v_mul_f32_e32 v78, v237, v78
	v_mul_f32_e32 v79, v237, v79
	v_mfma_f32_16x16x32_bf16 v[48:51], v[188:191], v[196:199], v[48:51]
	v_mul_f32_e32 v72, v237, v72
	v_mul_f32_e32 v73, v237, v73
	v_mul_f32_e32 v74, v237, v74
	v_mul_f32_e32 v75, v237, v75
	v_mfma_f32_16x16x32_bf16 v[36:39], v[180:183], v[204:207], v[36:39]
	v_cvt_pk_bf16_f32 v76, v76, v77
	v_cvt_pk_bf16_f32 v77, v78, v79
	v_cvt_pk_bf16_f32 v78, v72, v73
	v_cvt_pk_bf16_f32 v79, v74, v75
	v_mfma_f32_16x16x32_bf16 v[32:35], v[188:191], v[204:207], v[32:35]
	global_store_dwordx4 v232, v[76:79], s[30:31]
	v_mul_f32_e32 v68, v237, v68
	v_mul_f32_e32 v69, v237, v69
	v_mul_f32_e32 v70, v237, v70
	v_mfma_f32_16x16x32_bf16 v[20:23], v[180:183], v[212:215], v[20:23]
	v_mul_f32_e32 v71, v237, v71
	v_mul_f32_e32 v64, v237, v64
	v_mul_f32_e32 v65, v237, v65
	v_mul_f32_e32 v66, v237, v66
	v_mfma_f32_16x16x32_bf16 v[16:19], v[188:191], v[212:215], v[16:19]
	v_mul_f32_e32 v67, v237, v67
	v_cvt_pk_bf16_f32 v68, v68, v69
	v_cvt_pk_bf16_f32 v69, v70, v71
	v_cvt_pk_bf16_f32 v70, v64, v65
	v_mfma_f32_16x16x32_bf16 v[4:7], v[180:183], v[240:243], v[4:7]
	v_cvt_pk_bf16_f32 v71, v66, v67
	global_store_dwordx4 v232, v[68:71], s[30:31] offset:256
	v_add_u32_e32 v232, s98, v232
	v_add_u32_e32 v232, s98, v232
	v_mfma_f32_16x16x32_bf16 v[0:3], v[188:191], v[240:243], v[0:3]
	v_add_u32_e32 v232, s98, v232
	v_add_u32_e32 v232, s98, v232
	v_add_u32_e32 v232, s98, v232
	s_setprio 0
	s_barrier
	v_lshl_add_u64 v[142:143], v[142:143], 0, s[80:81]
	v_lshl_add_u64 v[144:145], v[144:145], 0, s[80:81]
	s_and_b64 vcc, exec, s[8:9]
	s_cbranch_vccnz .Lq5_notdefer
	s_cmp_lg_u32 s59, s61
	s_cbranch_scc1 .Lq5_notdefer
	s_mov_b32 s101, 1
	s_mov_b32 s60, s58
	s_mov_b32 s61, s59
	v_mov_b64_e32 v[144:145], v[140:141]
	v_mov_b64_e32 v[142:143], v[138:139]
	s_branch .LBB0_346

; __device__ __forceinline__ unsigned cvt_pk_bf16(float lo, float hi) { unsigned r; asm volatile("v_cvt_pk_bf16_f32 %0, %1, %2" : "=v"(r) : "v"(lo), "v"(hi)); return r; }
; __device__ __forceinline__ float gelu_tanh(float x) { const float u = 0.7978845608028654f * (x + 0.044715f * x * x * x); return x * fast_rcp(1.0f + fast_exp2(-2.0f * LOG2E * u)); }
;     __device__ __forceinline__ void operator()(const f32x4 (&acc)[2][2][4][2], const Unit& u, int wr, int wc, int fr, int fq) const {
;     ...
;             for (int m = 0; m < 4; ++m) { const int row = row0 + ai * HALF + m * 16; bf16_t* rowp = O + (size_t)row * ldc + col0; const float rs = rsv[ai][m];
; #pragma unroll
;                 for (int bj = 0; bj < 2; ++bj) { f32x4 v0 = acc[ai][bj][m][0] * rs, v1 = acc[ai][bj][m][1] * rs;
;                     if (ACT == 1) {
; #pragma unroll
;                         for (int j = 0; j < 4; ++j) { v0[j] = gelu_tanh(v0[j]); v1[j] = gelu_tanh(v1[j]); } }
;                     u32x4 w; w.x = cvt_pk_bf16(v0[0], v0[1]); w.y = cvt_pk_bf16(v0[2], v0[3]); w.z = cvt_pk_bf16(v1[0], v1[1]); w.w = cvt_pk_bf16(v1[2], v1[3]);
;                     *(u32x4*)(rowp + bj * HALF) = w; } }
.Lq5_nopf:
	s_lshl_b32 s98, s28, 5
	s_mov_b32 s99, 0
	v_pk_mul_f32 v[60:61], v[60:61], v[238:239] op_sel_hi:[1,0]
	v_pk_mul_f32 v[62:63], v[62:63], v[238:239] op_sel_hi:[1,0]
	v_pk_mul_f32 v[56:57], v[56:57], v[238:239] op_sel_hi:[1,0]
	v_pk_mul_f32 v[58:59], v[58:59], v[238:239] op_sel_hi:[1,0]
	v_cvt_pk_bf16_f32 v60, v60, v61
	v_cvt_pk_bf16_f32 v61, v62, v63
	v_cvt_pk_bf16_f32 v62, v56, v57
	v_cvt_pk_bf16_f32 v63, v58, v59
	global_store_dwordx4 v232, v[60:63], s[30:31]
	v_pk_mul_f32 v[52:53], v[52:53], v[238:239] op_sel_hi:[1,0]
	v_pk_mul_f32 v[54:55], v[54:55], v[238:239] op_sel_hi:[1,0]
	v_pk_mul_f32 v[48:49], v[48:49], v[238:239] op_sel_hi:[1,0]
	v_pk_mul_f32 v[50:51], v[50:51], v[238:239] op_sel_hi:[1,0]
	v_cvt_pk_bf16_f32 v52, v52, v53
	v_cvt_pk_bf16_f32 v53, v54, v55
	v_cvt_pk_bf16_f32 v54, v48, v49
	v_cvt_pk_bf16_f32 v55, v50, v51
	global_store_dwordx4 v232, v[52:55], s[30:31] offset:256
	v_add_u32_e32 v232, s98, v232
	v_pk_mul_f32 v[44:45], v[44:45], v[238:239] op_sel:[0,1]
	v_pk_mul_f32 v[46:47], v[46:47], v[238:239] op_sel:[0,1]
	v_pk_mul_f32 v[40:41], v[40:41], v[238:239] op_sel:[0,1]
	v_pk_mul_f32 v[42:43], v[42:43], v[238:239] op_sel:[0,1]
	v_cvt_pk_bf16_f32 v44, v44, v45
	v_cvt_pk_bf16_f32 v45, v46, v47
	v_cvt_pk_bf16_f32 v46, v40, v41
	v_cvt_pk_bf16_f32 v47, v42, v43
	global_store_dwordx4 v232, v[44:47], s[30:31]
	v_pk_mul_f32 v[36:37], v[36:37], v[238:239] op_sel:[0,1]
	v_pk_mul_f32 v[38:39], v[38:39], v[238:239] op_sel:[0,1]
	v_pk_mul_f32 v[32:33], v[32:33], v[238:239] op_sel:[0,1]
	v_pk_mul_f32 v[34:35], v[34:35], v[238:239] op_sel:[0,1]
	v_cvt_pk_bf16_f32 v36, v36, v37
	v_cvt_pk_bf16_f32 v37, v38, v39
	v_cvt_pk_bf16_f32 v38, v32, v33
	v_cvt_pk_bf16_f32 v39, v34, v35
	global_store_dwordx4 v232, v[36:39], s[30:31] offset:256
	v_add_u32_e32 v232, s98, v232
	v_pk_mul_f32 v[28:29], v[28:29], v[230:231] op_sel_hi:[1,0]
	v_pk_mul_f32 v[30:31], v[30:31], v[230:231] op_sel_hi:[1,0]
	v_pk_mul_f32 v[24:25], v[24:25], v[230:231] op_sel_hi:[1,0]
	v_pk_mul_f32 v[26:27], v[26:27], v[230:231] op_sel_hi:[1,0]
	v_cvt_pk_bf16_f32 v28, v28, v29
	v_cvt_pk_bf16_f32 v29, v30, v31
	v_cvt_pk_bf16_f32 v30, v24, v25
	v_cvt_pk_bf16_f32 v31, v26, v27
	global_store_dwordx4 v232, v[28:31], s[30:31]
	v_pk_mul_f32 v[20:21], v[20:21], v[230:231] op_sel_hi:[1,0]
	v_pk_mul_f32 v[22:23], v[22:23], v[230:231] op_sel_hi:[1,0]
	v_pk_mul_f32 v[16:17], v[16:17], v[230:231] op_sel_hi:[1,0]
	v_pk_mul_f32 v[18:19], v[18:19], v[230:231] op_sel_hi:[1,0]
	v_cvt_pk_bf16_f32 v20, v20, v21
	v_cvt_pk_bf16_f32 v21, v22, v23
	v_cvt_pk_bf16_f32 v22, v16, v17
	v_cvt_pk_bf16_f32 v23, v18, v19
	global_store_dwordx4 v232, v[20:23], s[30:31] offset:256
	v_add_u32_e32 v232, s98, v232
	v_pk_mul_f32 v[12:13], v[12:13], v[230:231] op_sel:[0,1]
	v_pk_mul_f32 v[14:15], v[14:15], v[230:231] op_sel:[0,1]
	v_pk_mul_f32 v[8:9], v[8:9], v[230:231] op_sel:[0,1]
	v_pk_mul_f32 v[10:11], v[10:11], v[230:231] op_sel:[0,1]
	v_cvt_pk_bf16_f32 v12, v12, v13
	v_cvt_pk_bf16_f32 v13, v14, v15
	v_cvt_pk_bf16_f32 v14, v8, v9
	v_cvt_pk_bf16_f32 v15, v10, v11
	global_store_dwordx4 v232, v[12:15], s[30:31]
	v_pk_mul_f32 v[4:5], v[4:5], v[230:231] op_sel:[0,1]
	v_pk_mul_f32 v[6:7], v[6:7], v[230:231] op_sel:[0,1]
	v_pk_mul_f32 v[0:1], v[0:1], v[230:231] op_sel:[0,1]
	v_pk_mul_f32 v[2:3], v[2:3], v[230:231] op_sel:[0,1]
	v_cvt_pk_bf16_f32 v4, v4, v5
	v_cvt_pk_bf16_f32 v5, v6, v7
	v_cvt_pk_bf16_f32 v6, v0, v1
	v_cvt_pk_bf16_f32 v7, v2, v3
	global_store_dwordx4 v232, v[4:7], s[30:31] offset:256
	s_mov_b32 s101, 0
	s_mov_b64 s[10:11], -1
	s_and_b64 vcc, exec, s[8:9]
	s_cbranch_vccnz .LBB0_345
	s_andn2_b64 vcc, exec, s[40:41]
	s_cbranch_vccnz .LBB0_344
	s_barrier
	s_branch .LBB0_344
